# final LayerNorm row loop prefetches the next row; residual-GEMM epilogue waits recounted so that only younger loads may stay outstanding
# speedup vs baseline: 1.0641x; 1.0027x over previous
; __device__ __forceinline__ u32x2 pk4(f32x4 v) { u32x2 r; r.x = pk2(v.x, v.y); r.y = pk2(v.z, v.w); return r; }
;     __device__ __forceinline__ void operator()(const f32x4 (&acc)[2][2][4][2], const pg8::Unit& u, int wr, int wc, int fr, int fq) const {
;     ...
;                 for (int bj = 0; bj < 2; ++bj)
; #pragma unroll
;                     for (int n = 0; n < 2; ++n) {
;                         const int col = u.pn * 256 + bj * 128 + wc * 32 + n * 16 + fq * 4;
;                         const u32x2 raw = *(const u32x2*)(src + (size_t)row * DM + col);
;                         f32x4 x = (f32x4){bflo(raw.x), bfhi(raw.x), bflo(raw.y), bfhi(raw.y)};
;                         if (ln) x = (x - mu) * rs * *(const f32x4*)(g + col) + *(const f32x4*)(b + col);
;                         const u32x2 pz = pk4(x * ALPHA + acc[ai][bj][m][n]);
;                         *(u32x2*)(dst + (size_t)row * DM + col) = pz;
;                         const float z0 = bflo(pz.x), z1 = bfhi(pz.x), z2 = bflo(pz.y), z3 = bfhi(pz.y);
;                         s1 += (z0 + z1) + (z2 + z3); s2 += (z0 * z0 + z1 * z1) + (z2 * z2 + z3 * z3);
;                     }
.LBB0_1841:
	v_readlane_b32 s70, v250, 30
	v_lshlrev_b64 v[166:167], 10, v[146:147]
	v_pk_fma_f32 v[128:129], v[156:157], s[72:73], v[128:129] op_sel_hi:[1,0,1]
	v_readlane_b32 s71, v250, 31
	v_pk_fma_f32 v[158:159], v[158:159], s[72:73], v[130:131] op_sel_hi:[1,0,1]
	v_cvt_pk_bf16_f32 v130, v128, v129
	v_lshl_add_u64 v[128:129], v[166:167], 1, s[70:71]
	v_cvt_pk_bf16_f32 v131, v158, v159
	v_lshl_add_u64 v[128:129], v[144:145], 1, v[128:129]
	global_store_dwordx2 v[128:129], v[130:131], off
	s_waitcnt vmcnt(11)
	v_mov_b64_e32 v[158:159], v[200:201]
	global_load_dwordx2 v[200:201], v243, s[46:47] offset:32
	s_and_b64 vcc, exec, s[44:45]
	s_waitcnt lgkmcnt(0)
	v_lshlrev_b32_e32 v156, 16, v158
	v_and_b32_e32 v157, 0xffff0000, v158
	v_lshlrev_b32_e32 v158, 16, v159
	v_and_b32_e32 v159, 0xffff0000, v159
	s_cbranch_vccnz .LBB0_1843
	v_sub_f32_e32 v157, v157, v151
	v_sub_f32_e32 v156, v156, v151
	v_sub_f32_e32 v159, v159, v151
	v_sub_f32_e32 v158, v158, v151
	v_pk_mul_f32 v[166:167], v[152:153], v[156:157]
	v_mov_b32_e32 v156, v152
	v_mov_b32_e32 v157, v152
	v_pk_mul_f32 v[168:169], v[156:157], v[158:159]
	ds_read_b128 v[156:159], v244 offset:64
	ds_read_b128 v[180:183], v244 offset:320
	s_waitcnt lgkmcnt(0)
	v_pk_fma_f32 v[158:159], v[168:169], v[158:159], v[182:183]
	v_pk_fma_f32 v[156:157], v[166:167], v[156:157], v[180:181]
.LBB0_1843:
	v_pk_fma_f32 v[126:127], v[158:159], s[72:73], v[126:127] op_sel_hi:[1,0,1]
	v_pk_fma_f32 v[124:125], v[156:157], s[72:73], v[124:125] op_sel_hi:[1,0,1]
	s_and_b64 vcc, exec, s[44:45]
	v_cvt_pk_bf16_f32 v124, v124, v125
	v_cvt_pk_bf16_f32 v125, v126, v127
	global_store_dwordx2 v[128:129], v[124:125], off offset:32
	s_waitcnt vmcnt(11)
	v_mov_b64_e32 v[156:157], v[202:203]
	global_load_dwordx2 v[202:203], v243, s[46:47] offset:256
	s_waitcnt lgkmcnt(0)
	v_lshlrev_b32_e32 v126, 16, v156
	v_and_b32_e32 v127, 0xffff0000, v156
	v_lshlrev_b32_e32 v156, 16, v157
	v_and_b32_e32 v157, 0xffff0000, v157
	s_cbranch_vccnz .LBB0_1845
	ds_read_b128 v[180:183], v244 offset:128
	ds_read_b128 v[184:187], v244 offset:384
	v_sub_f32_e32 v157, v157, v151
	v_sub_f32_e32 v156, v156, v151
	v_sub_f32_e32 v127, v127, v151
	v_sub_f32_e32 v126, v126, v151
	v_mov_b32_e32 v158, v152
	v_mov_b32_e32 v159, v152
	v_pk_mul_f32 v[126:127], v[152:153], v[126:127]
	v_pk_mul_f32 v[156:157], v[158:159], v[156:157]
	s_waitcnt lgkmcnt(0)
	v_pk_fma_f32 v[126:127], v[126:127], v[180:181], v[184:185]
	v_pk_fma_f32 v[156:157], v[156:157], v[182:183], v[186:187]
.LBB0_1845:
	s_nop 0
	v_pk_fma_f32 v[122:123], v[156:157], s[72:73], v[122:123] op_sel_hi:[1,0,1]
	v_pk_fma_f32 v[120:121], v[126:127], s[72:73], v[120:121] op_sel_hi:[1,0,1]
	s_and_b64 vcc, exec, s[44:45]
	v_cvt_pk_bf16_f32 v120, v120, v121
	v_cvt_pk_bf16_f32 v121, v122, v123
	global_store_dwordx2 v[128:129], v[120:121], off offset:256
	s_waitcnt vmcnt(11)
	v_mov_b64_e32 v[126:127], v[204:205]
	global_load_dwordx2 v[204:205], v243, s[46:47] offset:288
	s_waitcnt lgkmcnt(0)
	v_lshlrev_b32_e32 v122, 16, v126
	v_and_b32_e32 v123, 0xffff0000, v126
	v_lshlrev_b32_e32 v126, 16, v127
	v_and_b32_e32 v127, 0xffff0000, v127
	s_cbranch_vccnz .LBB0_1847
	v_sub_f32_e32 v123, v123, v151
	v_sub_f32_e32 v122, v122, v151
	v_sub_f32_e32 v127, v127, v151
	v_sub_f32_e32 v126, v126, v151
	v_pk_mul_f32 v[122:123], v[152:153], v[122:123]
	v_mov_b32_e32 v153, v152
	v_pk_mul_f32 v[126:127], v[152:153], v[126:127]
	ds_read_b128 v[150:153], v244 offset:192
	ds_read_b128 v[154:157], v244 offset:448
	s_waitcnt lgkmcnt(0)
	v_pk_fma_f32 v[126:127], v[126:127], v[152:153], v[156:157]
	v_pk_fma_f32 v[122:123], v[122:123], v[150:151], v[154:155]

; __device__ __forceinline__ void stats_main(const float* stm, int row, int fq, float& mu, float& rs) {
;     const f32x4* p = (const f32x4*)(stm + (size_t)row * 32 + fq * 8);
;     const f32x4 a = p[0], b = p[1];
;     float s1 = (a.x + a.z) + (b.x + b.z), s2 = (a.y + a.w) + (b.y + b.w);
;     s1 += __shfl_xor(s1, 16); s2 += __shfl_xor(s2, 16); s1 += __shfl_xor(s1, 32); s2 += __shfl_xor(s2, 32);
;     mu = s1 * (1.f / DM); rs = __builtin_amdgcn_rsqf(fmaxf(s2 * (1.f / DM) - mu * mu, 0.f) + LN_EPS);
; }
;     __device__ __forceinline__ void operator()(const f32x4 (&acc)[2][2][4][2], const pg8::Unit& u, int wr, int wc, int fr, int fq) const {
;     ...
;                 const int row = u.pm * 256 + ai * 128 + wr * 64 + m * 16 + fr;
;                 float mu = 0.f, rs = 1.f; if (ln) stats_main(stm_p, row, fq, mu, rs);
.LBB0_1849:
	s_or_b64 exec, exec, s[0:1]
	v_or_b32_e32 v124, 16, v146
	v_ashrrev_i32_e32 v125, 31, v124
	s_and_b64 vcc, exec, s[44:45]
	v_lshlrev_b64 v[116:117], 7, v[124:125]
	s_cbranch_vccnz .LBB0_1851
	v_lshl_add_u64 v[122:123], v[134:135], 0, v[116:117]
	s_waitcnt lgkmcnt(0)
	s_waitcnt vmcnt(10)
	v_mov_b64_e32 v[118:119], v[214:215]
	v_mov_b64_e32 v[120:121], v[216:217]
	s_waitcnt vmcnt(11)
	v_mov_b64_e32 v[126:127], v[206:207]
	v_mov_b64_e32 v[128:129], v[208:209]
	s_waitcnt lgkmcnt(0)
	v_mov_b32_e32 v122, v118
	s_waitcnt lgkmcnt(0)
	v_mov_b32_e32 v123, v126
	v_mov_b32_e32 v130, v120
	v_mov_b32_e32 v131, v128
	v_pk_add_f32 v[122:123], v[122:123], v[130:131]
	v_add_f32_e32 v118, v119, v121
	v_add_f32_e32 v120, v127, v129
	v_mov_b32_e32 v119, v122
	v_mov_b32_e32 v121, v123
	v_pk_add_f32 v[118:119], v[118:119], v[120:121]
	ds_bpermute_b32 v121, v165, v119
	ds_bpermute_b32 v120, v165, v118
	s_waitcnt lgkmcnt(0)
	v_pk_add_f32 v[118:119], v[118:119], v[120:121]
	ds_bpermute_b32 v121, v164, v119
	ds_bpermute_b32 v120, v164, v118
	s_waitcnt lgkmcnt(0)
	v_pk_add_f32 v[118:119], v[118:119], v[120:121]
	s_nop 0
	v_pk_mul_f32 v[118:119], v[118:119], s[82:83] op_sel_hi:[1,0]
	s_nop 0
	v_fma_f32 v3, -v119, v119, v118
	v_max_f32_e32 v3, 0, v3
	v_add_f32_e32 v3, 0x3727c5ac, v3
	v_rsq_f32_e32 v120, v3
	s_branch .LBB0_1852

; __device__ __forceinline__ u32x2 pk4(f32x4 v) { u32x2 r; r.x = pk2(v.x, v.y); r.y = pk2(v.z, v.w); return r; }
;     __device__ __forceinline__ void operator()(const f32x4 (&acc)[2][2][4][2], const pg8::Unit& u, int wr, int wc, int fr, int fq) const {
;     ...
;                 for (int bj = 0; bj < 2; ++bj)
; #pragma unroll
;                     for (int n = 0; n < 2; ++n) {
;                         const int col = u.pn * 256 + bj * 128 + wc * 32 + n * 16 + fq * 4;
;                         const u32x2 raw = *(const u32x2*)(src + (size_t)row * DM + col);
;                         f32x4 x = (f32x4){bflo(raw.x), bfhi(raw.x), bflo(raw.y), bfhi(raw.y)};
;                         if (ln) x = (x - mu) * rs * *(const f32x4*)(g + col) + *(const f32x4*)(b + col);
;                         const u32x2 pz = pk4(x * ALPHA + acc[ai][bj][m][n]);
;                         *(u32x2*)(dst + (size_t)row * DM + col) = pz;
;                         const float z0 = bflo(pz.x), z1 = bfhi(pz.x), z2 = bflo(pz.y), z3 = bfhi(pz.y);
;                         s1 += (z0 + z1) + (z2 + z3); s2 += (z0 * z0 + z1 * z1) + (z2 * z2 + z3 * z3);
;                     }
.LBB0_1852:
	v_lshlrev_b64 v[122:123], 11, v[124:125]
	v_lshl_add_u64 v[122:123], s[46:47], 0, v[122:123]
	v_lshl_add_u64 v[122:123], v[144:145], 1, v[122:123]
	v_add_u32_e32 v243, 0x18000, v242
	s_waitcnt vmcnt(9)
	v_mov_b64_e32 v[128:129], v[234:235]
	global_load_dwordx4 v[206:209], v[246:247], off offset:2064
	global_load_dwordx4 v[214:217], v[246:247], off offset:2048
	global_load_dwordx2 v[234:235], v243, s[46:47]
	v_mov_b32_e32 v121, v120
	s_and_b64 vcc, exec, s[44:45]
	s_waitcnt lgkmcnt(0)
	v_lshlrev_b32_e32 v126, 16, v128
	v_and_b32_e32 v127, 0xffff0000, v128
	v_lshlrev_b32_e32 v128, 16, v129
	v_and_b32_e32 v129, 0xffff0000, v129
	s_cbranch_vccnz .LBB0_1854
	v_sub_f32_e32 v127, v127, v119
	v_sub_f32_e32 v126, v126, v119
	v_sub_f32_e32 v129, v129, v119
	v_sub_f32_e32 v128, v128, v119
	v_pk_mul_f32 v[130:131], v[120:121], v[126:127]
	v_mov_b32_e32 v126, v120
	v_mov_b32_e32 v127, v120
	v_pk_mul_f32 v[152:153], v[126:127], v[128:129]
	ds_read_b128 v[126:129], v244
	ds_read_b128 v[148:151], v244 offset:256
	s_waitcnt lgkmcnt(0)
	v_pk_fma_f32 v[128:129], v[152:153], v[128:129], v[150:151]
	v_pk_fma_f32 v[126:127], v[130:131], v[126:127], v[148:149]
.LBB0_1854:
	v_lshlrev_b64 v[124:125], 10, v[124:125]
	v_pk_fma_f32 v[112:113], v[126:127], s[72:73], v[112:113] op_sel_hi:[1,0,1]
	v_pk_fma_f32 v[128:129], v[128:129], s[72:73], v[114:115] op_sel_hi:[1,0,1]
	v_cvt_pk_bf16_f32 v114, v112, v113
	v_lshl_add_u64 v[112:113], v[124:125], 1, s[70:71]
	v_cvt_pk_bf16_f32 v115, v128, v129
	v_lshl_add_u64 v[112:113], v[144:145], 1, v[112:113]
	global_store_dwordx2 v[112:113], v[114:115], off
	s_waitcnt vmcnt(11)
	v_mov_b64_e32 v[126:127], v[236:237]
	global_load_dwordx2 v[236:237], v243, s[46:47] offset:32
	s_and_b64 vcc, exec, s[44:45]
	s_waitcnt lgkmcnt(0)
	v_lshlrev_b32_e32 v124, 16, v126
	v_and_b32_e32 v125, 0xffff0000, v126
	v_lshlrev_b32_e32 v126, 16, v127
	v_and_b32_e32 v127, 0xffff0000, v127
	s_cbranch_vccnz .LBB0_1856
	v_sub_f32_e32 v125, v125, v119
	v_sub_f32_e32 v124, v124, v119
	v_sub_f32_e32 v127, v127, v119
	v_sub_f32_e32 v126, v126, v119
	v_pk_mul_f32 v[148:149], v[120:121], v[124:125]
	v_mov_b32_e32 v124, v120
	v_mov_b32_e32 v125, v120
	v_pk_mul_f32 v[150:151], v[124:125], v[126:127]
	ds_read_b128 v[124:127], v244 offset:64
	ds_read_b128 v[128:131], v244 offset:320
	s_waitcnt lgkmcnt(0)
	v_pk_fma_f32 v[126:127], v[150:151], v[126:127], v[130:131]
	v_pk_fma_f32 v[124:125], v[148:149], v[124:125], v[128:129]
.LBB0_1856:
	v_pk_fma_f32 v[110:111], v[126:127], s[72:73], v[110:111] op_sel_hi:[1,0,1]
	v_pk_fma_f32 v[108:109], v[124:125], s[72:73], v[108:109] op_sel_hi:[1,0,1]
	s_and_b64 vcc, exec, s[44:45]
	v_cvt_pk_bf16_f32 v108, v108, v109
	v_cvt_pk_bf16_f32 v109, v110, v111
	global_store_dwordx2 v[112:113], v[108:109], off offset:32
	s_waitcnt vmcnt(11)
	v_mov_b64_e32 v[124:125], v[238:239]
	global_load_dwordx2 v[238:239], v243, s[46:47] offset:256
	s_waitcnt lgkmcnt(0)
	v_lshlrev_b32_e32 v110, 16, v124
	v_and_b32_e32 v111, 0xffff0000, v124
	v_lshlrev_b32_e32 v124, 16, v125
	v_and_b32_e32 v125, 0xffff0000, v125
	s_cbranch_vccnz .LBB0_1858
	v_sub_f32_e32 v125, v125, v119
	v_sub_f32_e32 v124, v124, v119
	v_mov_b32_e32 v126, v120
	v_mov_b32_e32 v127, v120
	v_pk_mul_f32 v[124:125], v[126:127], v[124:125]
	ds_read_b128 v[126:129], v244 offset:128
	ds_read_b128 v[148:151], v244 offset:384
	v_sub_f32_e32 v111, v111, v119
	v_sub_f32_e32 v110, v110, v119
	v_pk_mul_f32 v[110:111], v[120:121], v[110:111]
	s_waitcnt lgkmcnt(0)
	v_pk_fma_f32 v[124:125], v[124:125], v[128:129], v[150:151]
	v_pk_fma_f32 v[110:111], v[110:111], v[126:127], v[148:149]
.LBB0_1858:
	v_pk_fma_f32 v[106:107], v[124:125], s[72:73], v[106:107] op_sel_hi:[1,0,1]
	v_pk_fma_f32 v[104:105], v[110:111], s[72:73], v[104:105] op_sel_hi:[1,0,1]
	s_and_b64 vcc, exec, s[44:45]
	v_cvt_pk_bf16_f32 v104, v104, v105
	v_cvt_pk_bf16_f32 v105, v106, v107
	global_store_dwordx2 v[112:113], v[104:105], off offset:256
	s_waitcnt vmcnt(11)
	v_mov_b64_e32 v[110:111], v[240:241]
	global_load_dwordx2 v[240:241], v243, s[46:47] offset:288
	s_waitcnt lgkmcnt(0)
	v_lshlrev_b32_e32 v106, 16, v110
	v_and_b32_e32 v107, 0xffff0000, v110
	v_lshlrev_b32_e32 v110, 16, v111
	v_and_b32_e32 v111, 0xffff0000, v111
	s_cbranch_vccnz .LBB0_1860
	v_sub_f32_e32 v107, v107, v119
	v_sub_f32_e32 v106, v106, v119
	v_sub_f32_e32 v111, v111, v119
	v_sub_f32_e32 v110, v110, v119
	v_pk_mul_f32 v[106:107], v[120:121], v[106:107]
	v_mov_b32_e32 v121, v120
	v_pk_mul_f32 v[110:111], v[120:121], v[110:111]
	ds_read_b128 v[118:121], v244 offset:192
	ds_read_b128 v[122:125], v244 offset:448
	s_waitcnt lgkmcnt(0)
	v_pk_fma_f32 v[110:111], v[110:111], v[120:121], v[124:125]
	v_pk_fma_f32 v[106:107], v[106:107], v[118:119], v[122:123]

; __device__ __forceinline__ void stats_main(const float* stm, int row, int fq, float& mu, float& rs) {
;     const f32x4* p = (const f32x4*)(stm + (size_t)row * 32 + fq * 8);
;     const f32x4 a = p[0], b = p[1];
;     float s1 = (a.x + a.z) + (b.x + b.z), s2 = (a.y + a.w) + (b.y + b.w);
;     s1 += __shfl_xor(s1, 16); s2 += __shfl_xor(s2, 16); s1 += __shfl_xor(s1, 32); s2 += __shfl_xor(s2, 32);
;     mu = s1 * (1.f / DM); rs = __builtin_amdgcn_rsqf(fmaxf(s2 * (1.f / DM) - mu * mu, 0.f) + LN_EPS);
; }
;     __device__ __forceinline__ void operator()(const f32x4 (&acc)[2][2][4][2], const pg8::Unit& u, int wr, int wc, int fr, int fq) const {
;     ...
;                 const int row = u.pm * 256 + ai * 128 + wr * 64 + m * 16 + fr;
;                 float mu = 0.f, rs = 1.f; if (ln) stats_main(stm_p, row, fq, mu, rs);
.LBB0_1862:
	s_or_b64 exec, exec, s[0:1]
	v_or_b32_e32 v108, 32, v146
	v_ashrrev_i32_e32 v109, 31, v108
	s_and_b64 vcc, exec, s[44:45]
	v_lshlrev_b64 v[100:101], 7, v[108:109]
	s_cbranch_vccnz .LBB0_1864
	v_lshl_add_u64 v[106:107], v[134:135], 0, v[100:101]
	s_waitcnt lgkmcnt(0)
	s_waitcnt vmcnt(10)
	v_mov_b64_e32 v[102:103], v[194:195]
	v_mov_b64_e32 v[104:105], v[196:197]
	s_waitcnt vmcnt(11)
	v_mov_b64_e32 v[110:111], v[190:191]
	v_mov_b64_e32 v[112:113], v[192:193]
	s_waitcnt lgkmcnt(0)
	v_mov_b32_e32 v106, v102
	s_waitcnt lgkmcnt(0)
	v_mov_b32_e32 v107, v110
	v_mov_b32_e32 v114, v104
	v_mov_b32_e32 v115, v112
	v_pk_add_f32 v[106:107], v[106:107], v[114:115]
	v_add_f32_e32 v102, v103, v105
	v_add_f32_e32 v104, v111, v113
	v_mov_b32_e32 v103, v106
	v_mov_b32_e32 v105, v107
	v_pk_add_f32 v[102:103], v[102:103], v[104:105]
	ds_bpermute_b32 v105, v165, v103
	ds_bpermute_b32 v104, v165, v102
	s_waitcnt lgkmcnt(0)
	v_pk_add_f32 v[102:103], v[102:103], v[104:105]
	ds_bpermute_b32 v105, v164, v103
	ds_bpermute_b32 v104, v164, v102
	s_waitcnt lgkmcnt(0)
	v_pk_add_f32 v[102:103], v[102:103], v[104:105]
	s_nop 0
	v_pk_mul_f32 v[102:103], v[102:103], s[82:83] op_sel_hi:[1,0]
	s_nop 0
	v_fma_f32 v3, -v103, v103, v102
	v_max_f32_e32 v3, 0, v3
	v_add_f32_e32 v3, 0x3727c5ac, v3
	v_rsq_f32_e32 v104, v3
	s_branch .LBB0_1865

; __device__ __forceinline__ u32x2 pk4(f32x4 v) { u32x2 r; r.x = pk2(v.x, v.y); r.y = pk2(v.z, v.w); return r; }
;     __device__ __forceinline__ void operator()(const f32x4 (&acc)[2][2][4][2], const pg8::Unit& u, int wr, int wc, int fr, int fq) const {
;     ...
;                 for (int bj = 0; bj < 2; ++bj)
; #pragma unroll
;                     for (int n = 0; n < 2; ++n) {
;                         const int col = u.pn * 256 + bj * 128 + wc * 32 + n * 16 + fq * 4;
;                         const u32x2 raw = *(const u32x2*)(src + (size_t)row * DM + col);
;                         f32x4 x = (f32x4){bflo(raw.x), bfhi(raw.x), bflo(raw.y), bfhi(raw.y)};
;                         if (ln) x = (x - mu) * rs * *(const f32x4*)(g + col) + *(const f32x4*)(b + col);
;                         const u32x2 pz = pk4(x * ALPHA + acc[ai][bj][m][n]);
;                         *(u32x2*)(dst + (size_t)row * DM + col) = pz;
;                         const float z0 = bflo(pz.x), z1 = bfhi(pz.x), z2 = bflo(pz.y), z3 = bfhi(pz.y);
;                         s1 += (z0 + z1) + (z2 + z3); s2 += (z0 * z0 + z1 * z1) + (z2 * z2 + z3 * z3);
;                     }
.LBB0_1865:
	v_lshlrev_b64 v[106:107], 11, v[108:109]
	v_lshl_add_u64 v[106:107], s[46:47], 0, v[106:107]
	v_lshl_add_u64 v[106:107], v[144:145], 1, v[106:107]
	v_add_u32_e32 v243, 0x40000, v242
	s_waitcnt vmcnt(9)
	v_mov_b64_e32 v[112:113], v[198:199]
	global_load_dwordx4 v[190:193], v[248:249], off offset:-4080
	global_load_dwordx4 v[194:197], v[248:249], off offset:-4096
	global_load_dwordx2 v[198:199], v243, s[46:47]
	v_mov_b32_e32 v105, v104
	s_and_b64 vcc, exec, s[44:45]
	s_waitcnt lgkmcnt(0)
	v_lshlrev_b32_e32 v110, 16, v112
	v_and_b32_e32 v111, 0xffff0000, v112
	v_lshlrev_b32_e32 v112, 16, v113
	v_and_b32_e32 v113, 0xffff0000, v113
	s_cbranch_vccnz .LBB0_1867
	v_sub_f32_e32 v111, v111, v103
	v_sub_f32_e32 v110, v110, v103
	v_sub_f32_e32 v113, v113, v103
	v_sub_f32_e32 v112, v112, v103
	v_pk_mul_f32 v[118:119], v[104:105], v[110:111]
	v_mov_b32_e32 v110, v104
	v_mov_b32_e32 v111, v104
	v_pk_mul_f32 v[120:121], v[110:111], v[112:113]
	ds_read_b128 v[110:113], v244
	ds_read_b128 v[114:117], v244 offset:256
	s_waitcnt lgkmcnt(0)
	v_pk_fma_f32 v[112:113], v[120:121], v[112:113], v[116:117]
	v_pk_fma_f32 v[110:111], v[118:119], v[110:111], v[114:115]
.LBB0_1867:
	v_lshlrev_b64 v[108:109], 10, v[108:109]
	v_pk_fma_f32 v[96:97], v[110:111], s[72:73], v[96:97] op_sel_hi:[1,0,1]
	v_pk_fma_f32 v[112:113], v[112:113], s[72:73], v[98:99] op_sel_hi:[1,0,1]
	v_cvt_pk_bf16_f32 v98, v96, v97
	v_lshl_add_u64 v[96:97], v[108:109], 1, s[70:71]
	v_cvt_pk_bf16_f32 v99, v112, v113
	v_lshl_add_u64 v[96:97], v[144:145], 1, v[96:97]
	global_store_dwordx2 v[96:97], v[98:99], off
	s_waitcnt vmcnt(11)
	v_mov_b64_e32 v[110:111], v[200:201]
	global_load_dwordx2 v[200:201], v243, s[46:47] offset:32
	s_and_b64 vcc, exec, s[44:45]
	s_waitcnt lgkmcnt(0)
	v_lshlrev_b32_e32 v108, 16, v110
	v_and_b32_e32 v109, 0xffff0000, v110
	v_lshlrev_b32_e32 v110, 16, v111
	v_and_b32_e32 v111, 0xffff0000, v111
	s_cbranch_vccnz .LBB0_1869
	v_sub_f32_e32 v109, v109, v103
	v_sub_f32_e32 v108, v108, v103
	v_sub_f32_e32 v111, v111, v103
	v_sub_f32_e32 v110, v110, v103
	v_pk_mul_f32 v[116:117], v[104:105], v[108:109]
	v_mov_b32_e32 v108, v104
	v_mov_b32_e32 v109, v104
	v_pk_mul_f32 v[118:119], v[108:109], v[110:111]
	ds_read_b128 v[108:111], v244 offset:64
	ds_read_b128 v[112:115], v244 offset:320
	s_waitcnt lgkmcnt(0)
	v_pk_fma_f32 v[110:111], v[118:119], v[110:111], v[114:115]
	v_pk_fma_f32 v[108:109], v[116:117], v[108:109], v[112:113]
.LBB0_1869:
	v_pk_fma_f32 v[94:95], v[110:111], s[72:73], v[94:95] op_sel_hi:[1,0,1]
	v_pk_fma_f32 v[92:93], v[108:109], s[72:73], v[92:93] op_sel_hi:[1,0,1]
	s_and_b64 vcc, exec, s[44:45]
	v_cvt_pk_bf16_f32 v92, v92, v93
	v_cvt_pk_bf16_f32 v93, v94, v95
	global_store_dwordx2 v[96:97], v[92:93], off offset:32
	s_waitcnt vmcnt(11)
	v_mov_b64_e32 v[108:109], v[202:203]
	global_load_dwordx2 v[202:203], v243, s[46:47] offset:256
	s_waitcnt lgkmcnt(0)
	v_lshlrev_b32_e32 v94, 16, v108
	v_and_b32_e32 v95, 0xffff0000, v108
	v_lshlrev_b32_e32 v108, 16, v109
	v_and_b32_e32 v109, 0xffff0000, v109
	s_cbranch_vccnz .LBB0_1871
	v_sub_f32_e32 v109, v109, v103
	v_sub_f32_e32 v108, v108, v103
	v_mov_b32_e32 v110, v104
	v_mov_b32_e32 v111, v104
	v_pk_mul_f32 v[108:109], v[110:111], v[108:109]
	ds_read_b128 v[110:113], v244 offset:128
	ds_read_b128 v[114:117], v244 offset:384
	v_sub_f32_e32 v95, v95, v103
	v_sub_f32_e32 v94, v94, v103
	v_pk_mul_f32 v[94:95], v[104:105], v[94:95]
	s_waitcnt lgkmcnt(0)
	v_pk_fma_f32 v[108:109], v[108:109], v[112:113], v[116:117]
	v_pk_fma_f32 v[94:95], v[94:95], v[110:111], v[114:115]
.LBB0_1871:
	v_pk_fma_f32 v[90:91], v[108:109], s[72:73], v[90:91] op_sel_hi:[1,0,1]
	v_pk_fma_f32 v[88:89], v[94:95], s[72:73], v[88:89] op_sel_hi:[1,0,1]
	s_and_b64 vcc, exec, s[44:45]
	v_cvt_pk_bf16_f32 v88, v88, v89
	v_cvt_pk_bf16_f32 v89, v90, v91
	global_store_dwordx2 v[96:97], v[88:89], off offset:256
	s_waitcnt vmcnt(11)
	v_mov_b64_e32 v[94:95], v[204:205]
	global_load_dwordx2 v[204:205], v243, s[46:47] offset:288
	s_waitcnt lgkmcnt(0)
	v_lshlrev_b32_e32 v90, 16, v94
	v_and_b32_e32 v91, 0xffff0000, v94
	v_lshlrev_b32_e32 v94, 16, v95
	v_and_b32_e32 v95, 0xffff0000, v95
	s_cbranch_vccnz .LBB0_1873
	v_sub_f32_e32 v91, v91, v103
	v_sub_f32_e32 v90, v90, v103
	v_sub_f32_e32 v95, v95, v103
	v_sub_f32_e32 v94, v94, v103
	v_pk_mul_f32 v[90:91], v[104:105], v[90:91]
	v_mov_b32_e32 v105, v104
	v_pk_mul_f32 v[94:95], v[104:105], v[94:95]
	ds_read_b128 v[102:105], v244 offset:192
	ds_read_b128 v[106:109], v244 offset:448
	s_waitcnt lgkmcnt(0)
	v_pk_fma_f32 v[94:95], v[94:95], v[104:105], v[108:109]
	v_pk_fma_f32 v[90:91], v[90:91], v[102:103], v[106:107]

; __device__ __forceinline__ void stats_main(const float* stm, int row, int fq, float& mu, float& rs) {
;     const f32x4* p = (const f32x4*)(stm + (size_t)row * 32 + fq * 8);
;     const f32x4 a = p[0], b = p[1];
;     float s1 = (a.x + a.z) + (b.x + b.z), s2 = (a.y + a.w) + (b.y + b.w);
;     s1 += __shfl_xor(s1, 16); s2 += __shfl_xor(s2, 16); s1 += __shfl_xor(s1, 32); s2 += __shfl_xor(s2, 32);
;     mu = s1 * (1.f / DM); rs = __builtin_amdgcn_rsqf(fmaxf(s2 * (1.f / DM) - mu * mu, 0.f) + LN_EPS);
; }
;     __device__ __forceinline__ void operator()(const f32x4 (&acc)[2][2][4][2], const pg8::Unit& u, int wr, int wc, int fr, int fq) const {
;     ...
;                 const int row = u.pm * 256 + ai * 128 + wr * 64 + m * 16 + fr;
;                 float mu = 0.f, rs = 1.f; if (ln) stats_main(stm_p, row, fq, mu, rs);
.LBB0_1875:
	s_or_b64 exec, exec, s[0:1]
	v_or_b32_e32 v92, 48, v146
	v_ashrrev_i32_e32 v93, 31, v92
	s_and_b64 vcc, exec, s[44:45]
	v_lshlrev_b64 v[84:85], 7, v[92:93]
	s_cbranch_vccnz .LBB0_1877
	v_lshl_add_u64 v[90:91], v[134:135], 0, v[84:85]
	s_waitcnt lgkmcnt(0)
	s_waitcnt vmcnt(10)
	v_mov_b64_e32 v[86:87], v[214:215]
	v_mov_b64_e32 v[88:89], v[216:217]
	s_waitcnt vmcnt(11)
	v_mov_b64_e32 v[94:95], v[206:207]
	v_mov_b64_e32 v[96:97], v[208:209]
	s_waitcnt lgkmcnt(0)
	v_mov_b32_e32 v90, v86
	s_waitcnt lgkmcnt(0)
	v_mov_b32_e32 v91, v94
	v_mov_b32_e32 v98, v88
	v_mov_b32_e32 v99, v96
	v_pk_add_f32 v[90:91], v[90:91], v[98:99]
	v_add_f32_e32 v86, v87, v89
	v_add_f32_e32 v88, v95, v97
	v_mov_b32_e32 v87, v90
	v_mov_b32_e32 v89, v91
	v_pk_add_f32 v[86:87], v[86:87], v[88:89]
	ds_bpermute_b32 v89, v165, v87
	ds_bpermute_b32 v88, v165, v86
	s_waitcnt lgkmcnt(0)
	v_pk_add_f32 v[86:87], v[86:87], v[88:89]
	ds_bpermute_b32 v89, v164, v87
	ds_bpermute_b32 v88, v164, v86
	s_waitcnt lgkmcnt(0)
	v_pk_add_f32 v[86:87], v[86:87], v[88:89]
	s_nop 0
	v_pk_mul_f32 v[86:87], v[86:87], s[82:83] op_sel_hi:[1,0]
	s_nop 0
	v_fma_f32 v3, -v87, v87, v86
	v_max_f32_e32 v3, 0, v3
	v_add_f32_e32 v3, 0x3727c5ac, v3
	v_rsq_f32_e32 v88, v3
	s_branch .LBB0_1878

; __device__ __forceinline__ u32x2 pk4(f32x4 v) { u32x2 r; r.x = pk2(v.x, v.y); r.y = pk2(v.z, v.w); return r; }
;     __device__ __forceinline__ void operator()(const f32x4 (&acc)[2][2][4][2], const pg8::Unit& u, int wr, int wc, int fr, int fq) const {
;     ...
;                 for (int bj = 0; bj < 2; ++bj)
; #pragma unroll
;                     for (int n = 0; n < 2; ++n) {
;                         const int col = u.pn * 256 + bj * 128 + wc * 32 + n * 16 + fq * 4;
;                         const u32x2 raw = *(const u32x2*)(src + (size_t)row * DM + col);
;                         f32x4 x = (f32x4){bflo(raw.x), bfhi(raw.x), bflo(raw.y), bfhi(raw.y)};
;                         if (ln) x = (x - mu) * rs * *(const f32x4*)(g + col) + *(const f32x4*)(b + col);
;                         const u32x2 pz = pk4(x * ALPHA + acc[ai][bj][m][n]);
;                         *(u32x2*)(dst + (size_t)row * DM + col) = pz;
;                         const float z0 = bflo(pz.x), z1 = bfhi(pz.x), z2 = bflo(pz.y), z3 = bfhi(pz.y);
;                         s1 += (z0 + z1) + (z2 + z3); s2 += (z0 * z0 + z1 * z1) + (z2 * z2 + z3 * z3);
;                     }
.LBB0_1878:
	v_lshlrev_b64 v[90:91], 11, v[92:93]
	v_lshl_add_u64 v[90:91], s[46:47], 0, v[90:91]
	v_lshl_add_u64 v[90:91], v[144:145], 1, v[90:91]
	v_add_u32_e32 v243, 0x48000, v242
	s_waitcnt vmcnt(9)
	v_mov_b64_e32 v[96:97], v[234:235]
	global_load_dwordx4 v[206:209], v[248:249], off offset:-2032
	global_load_dwordx4 v[214:217], v[248:249], off offset:-2048
	global_load_dwordx2 v[234:235], v243, s[46:47]
	v_mov_b32_e32 v89, v88
	s_and_b64 vcc, exec, s[44:45]
	s_waitcnt lgkmcnt(0)
	v_lshlrev_b32_e32 v94, 16, v96
	v_and_b32_e32 v95, 0xffff0000, v96
	v_lshlrev_b32_e32 v96, 16, v97
	v_and_b32_e32 v97, 0xffff0000, v97
	s_cbranch_vccnz .LBB0_1880
	v_sub_f32_e32 v95, v95, v87
	v_sub_f32_e32 v94, v94, v87
	v_sub_f32_e32 v97, v97, v87
	v_sub_f32_e32 v96, v96, v87
	v_pk_mul_f32 v[102:103], v[88:89], v[94:95]
	v_mov_b32_e32 v94, v88
	v_mov_b32_e32 v95, v88
	v_pk_mul_f32 v[104:105], v[94:95], v[96:97]
	ds_read_b128 v[94:97], v244
	ds_read_b128 v[98:101], v244 offset:256
	s_waitcnt lgkmcnt(0)
	v_pk_fma_f32 v[96:97], v[104:105], v[96:97], v[100:101]
	v_pk_fma_f32 v[94:95], v[102:103], v[94:95], v[98:99]
.LBB0_1880:
	v_lshlrev_b64 v[92:93], 10, v[92:93]
	v_pk_fma_f32 v[80:81], v[94:95], s[72:73], v[80:81] op_sel_hi:[1,0,1]
	v_pk_fma_f32 v[96:97], v[96:97], s[72:73], v[82:83] op_sel_hi:[1,0,1]
	v_cvt_pk_bf16_f32 v82, v80, v81
	v_lshl_add_u64 v[80:81], v[92:93], 1, s[70:71]
	v_cvt_pk_bf16_f32 v83, v96, v97
	v_lshl_add_u64 v[80:81], v[144:145], 1, v[80:81]
	global_store_dwordx2 v[80:81], v[82:83], off
	s_waitcnt vmcnt(11)
	v_mov_b64_e32 v[94:95], v[236:237]
	global_load_dwordx2 v[236:237], v243, s[46:47] offset:32
	s_and_b64 vcc, exec, s[44:45]
	s_waitcnt lgkmcnt(0)
	v_lshlrev_b32_e32 v92, 16, v94
	v_and_b32_e32 v93, 0xffff0000, v94
	v_lshlrev_b32_e32 v94, 16, v95
	v_and_b32_e32 v95, 0xffff0000, v95
	s_cbranch_vccnz .LBB0_1882
	v_sub_f32_e32 v93, v93, v87
	v_sub_f32_e32 v92, v92, v87
	v_sub_f32_e32 v95, v95, v87
	v_sub_f32_e32 v94, v94, v87
	v_pk_mul_f32 v[100:101], v[88:89], v[92:93]
	v_mov_b32_e32 v92, v88
	v_mov_b32_e32 v93, v88
	v_pk_mul_f32 v[102:103], v[92:93], v[94:95]
	ds_read_b128 v[92:95], v244 offset:64
	ds_read_b128 v[96:99], v244 offset:320
	s_waitcnt lgkmcnt(0)
	v_pk_fma_f32 v[94:95], v[102:103], v[94:95], v[98:99]
	v_pk_fma_f32 v[92:93], v[100:101], v[92:93], v[96:97]
.LBB0_1882:
	v_pk_fma_f32 v[78:79], v[94:95], s[72:73], v[78:79] op_sel_hi:[1,0,1]
	v_pk_fma_f32 v[76:77], v[92:93], s[72:73], v[76:77] op_sel_hi:[1,0,1]
	s_and_b64 vcc, exec, s[44:45]
	v_cvt_pk_bf16_f32 v76, v76, v77
	v_cvt_pk_bf16_f32 v77, v78, v79
	global_store_dwordx2 v[80:81], v[76:77], off offset:32
	s_waitcnt vmcnt(11)
	v_mov_b64_e32 v[92:93], v[238:239]
	global_load_dwordx2 v[238:239], v243, s[46:47] offset:256
	s_waitcnt lgkmcnt(0)
	v_lshlrev_b32_e32 v78, 16, v92
	v_and_b32_e32 v79, 0xffff0000, v92
	v_lshlrev_b32_e32 v92, 16, v93
	v_and_b32_e32 v93, 0xffff0000, v93
	s_cbranch_vccnz .LBB0_1884
	v_sub_f32_e32 v93, v93, v87
	v_sub_f32_e32 v92, v92, v87
	v_mov_b32_e32 v94, v88
	v_mov_b32_e32 v95, v88
	v_pk_mul_f32 v[92:93], v[94:95], v[92:93]
	ds_read_b128 v[94:97], v244 offset:128
	ds_read_b128 v[98:101], v244 offset:384
	v_sub_f32_e32 v79, v79, v87
	v_sub_f32_e32 v78, v78, v87
	v_pk_mul_f32 v[78:79], v[88:89], v[78:79]
	s_waitcnt lgkmcnt(0)
	v_pk_fma_f32 v[92:93], v[92:93], v[96:97], v[100:101]
	v_pk_fma_f32 v[78:79], v[78:79], v[94:95], v[98:99]
.LBB0_1884:
	v_pk_fma_f32 v[74:75], v[92:93], s[72:73], v[74:75] op_sel_hi:[1,0,1]
	v_pk_fma_f32 v[72:73], v[78:79], s[72:73], v[72:73] op_sel_hi:[1,0,1]
	s_and_b64 vcc, exec, s[44:45]
	v_cvt_pk_bf16_f32 v72, v72, v73
	v_cvt_pk_bf16_f32 v73, v74, v75
	global_store_dwordx2 v[80:81], v[72:73], off offset:256
	s_waitcnt vmcnt(11)
	v_mov_b64_e32 v[78:79], v[240:241]
	global_load_dwordx2 v[240:241], v243, s[46:47] offset:288
	s_waitcnt lgkmcnt(0)
	v_lshlrev_b32_e32 v74, 16, v78
	v_and_b32_e32 v75, 0xffff0000, v78
	v_lshlrev_b32_e32 v78, 16, v79
	v_and_b32_e32 v79, 0xffff0000, v79
	s_cbranch_vccnz .LBB0_1886
	v_sub_f32_e32 v75, v75, v87
	v_sub_f32_e32 v74, v74, v87
	v_sub_f32_e32 v79, v79, v87
	v_sub_f32_e32 v78, v78, v87
	v_pk_mul_f32 v[74:75], v[88:89], v[74:75]
	v_mov_b32_e32 v89, v88
	v_pk_mul_f32 v[78:79], v[88:89], v[78:79]
	ds_read_b128 v[86:89], v244 offset:192
	ds_read_b128 v[90:93], v244 offset:448
	s_waitcnt lgkmcnt(0)
	v_pk_fma_f32 v[78:79], v[78:79], v[88:89], v[92:93]
	v_pk_fma_f32 v[74:75], v[74:75], v[86:87], v[90:91]

; __device__ __forceinline__ void stats_main(const float* stm, int row, int fq, float& mu, float& rs) {
;     const f32x4* p = (const f32x4*)(stm + (size_t)row * 32 + fq * 8);
;     const f32x4 a = p[0], b = p[1];
;     float s1 = (a.x + a.z) + (b.x + b.z), s2 = (a.y + a.w) + (b.y + b.w);
;     s1 += __shfl_xor(s1, 16); s2 += __shfl_xor(s2, 16); s1 += __shfl_xor(s1, 32); s2 += __shfl_xor(s2, 32);
;     mu = s1 * (1.f / DM); rs = __builtin_amdgcn_rsqf(fmaxf(s2 * (1.f / DM) - mu * mu, 0.f) + LN_EPS);
; }
;     __device__ __forceinline__ void operator()(const f32x4 (&acc)[2][2][4][2], const pg8::Unit& u, int wr, int wc, int fr, int fq) const {
;     ...
;                 const int row = u.pm * 256 + ai * 128 + wr * 64 + m * 16 + fr;
;                 float mu = 0.f, rs = 1.f; if (ln) stats_main(stm_p, row, fq, mu, rs);
.LBB0_1888:
	s_or_b64 exec, exec, s[0:1]
	v_add_u32_e32 v76, 0x80, v146
	v_ashrrev_i32_e32 v77, 31, v76
	s_and_b64 vcc, exec, s[44:45]
	v_lshlrev_b64 v[68:69], 7, v[76:77]
	s_cbranch_vccnz .LBB0_1890
	v_lshl_add_u64 v[74:75], v[134:135], 0, v[68:69]
	s_waitcnt lgkmcnt(0)
	s_waitcnt vmcnt(10)
	v_mov_b64_e32 v[70:71], v[194:195]
	v_mov_b64_e32 v[72:73], v[196:197]
	s_waitcnt vmcnt(11)
	v_mov_b64_e32 v[78:79], v[190:191]
	v_mov_b64_e32 v[80:81], v[192:193]
	s_waitcnt lgkmcnt(0)
	v_mov_b32_e32 v74, v70
	s_waitcnt lgkmcnt(0)
	v_mov_b32_e32 v75, v78
	v_mov_b32_e32 v82, v72
	v_mov_b32_e32 v83, v80
	v_pk_add_f32 v[74:75], v[74:75], v[82:83]
	v_add_f32_e32 v70, v71, v73
	v_add_f32_e32 v72, v79, v81
	v_mov_b32_e32 v71, v74
	v_mov_b32_e32 v73, v75
	v_pk_add_f32 v[70:71], v[70:71], v[72:73]
	ds_bpermute_b32 v73, v165, v71
	ds_bpermute_b32 v72, v165, v70
	s_waitcnt lgkmcnt(0)
	v_pk_add_f32 v[70:71], v[70:71], v[72:73]
	ds_bpermute_b32 v73, v164, v71
	ds_bpermute_b32 v72, v164, v70
	s_waitcnt lgkmcnt(0)
	v_pk_add_f32 v[70:71], v[70:71], v[72:73]
	s_nop 0
	v_pk_mul_f32 v[70:71], v[70:71], s[82:83] op_sel_hi:[1,0]
	s_nop 0
	v_fma_f32 v3, -v71, v71, v70
	v_max_f32_e32 v3, 0, v3
	v_add_f32_e32 v3, 0x3727c5ac, v3
	v_rsq_f32_e32 v72, v3
	s_branch .LBB0_1891

; __device__ __forceinline__ u32x2 pk4(f32x4 v) { u32x2 r; r.x = pk2(v.x, v.y); r.y = pk2(v.z, v.w); return r; }
;     __device__ __forceinline__ void operator()(const f32x4 (&acc)[2][2][4][2], const pg8::Unit& u, int wr, int wc, int fr, int fq) const {
;     ...
;                 for (int bj = 0; bj < 2; ++bj)
; #pragma unroll
;                     for (int n = 0; n < 2; ++n) {
;                         const int col = u.pn * 256 + bj * 128 + wc * 32 + n * 16 + fq * 4;
;                         const u32x2 raw = *(const u32x2*)(src + (size_t)row * DM + col);
;                         f32x4 x = (f32x4){bflo(raw.x), bfhi(raw.x), bflo(raw.y), bfhi(raw.y)};
;                         if (ln) x = (x - mu) * rs * *(const f32x4*)(g + col) + *(const f32x4*)(b + col);
;                         const u32x2 pz = pk4(x * ALPHA + acc[ai][bj][m][n]);
;                         *(u32x2*)(dst + (size_t)row * DM + col) = pz;
;                         const float z0 = bflo(pz.x), z1 = bfhi(pz.x), z2 = bflo(pz.y), z3 = bfhi(pz.y);
;                         s1 += (z0 + z1) + (z2 + z3); s2 += (z0 * z0 + z1 * z1) + (z2 * z2 + z3 * z3);
;                     }
.LBB0_1891:
	v_lshlrev_b64 v[74:75], 11, v[76:77]
	v_lshl_add_u64 v[74:75], s[46:47], 0, v[74:75]
	v_lshl_add_u64 v[74:75], v[144:145], 1, v[74:75]
	v_add_u32_e32 v243, 0x50000, v242
	s_waitcnt vmcnt(9)
	v_mov_b64_e32 v[80:81], v[198:199]
	global_load_dwordx4 v[190:193], v[248:249], off offset:16
	global_load_dwordx4 v[194:197], v[248:249], off
	global_load_dwordx2 v[198:199], v243, s[46:47]
	v_mov_b32_e32 v73, v72
	s_and_b64 vcc, exec, s[44:45]
	s_waitcnt lgkmcnt(0)
	v_lshlrev_b32_e32 v78, 16, v80
	v_and_b32_e32 v79, 0xffff0000, v80
	v_lshlrev_b32_e32 v80, 16, v81
	v_and_b32_e32 v81, 0xffff0000, v81
	s_cbranch_vccnz .LBB0_1893
	v_sub_f32_e32 v79, v79, v71
	v_sub_f32_e32 v78, v78, v71
	v_sub_f32_e32 v81, v81, v71
	v_sub_f32_e32 v80, v80, v71
	v_pk_mul_f32 v[86:87], v[72:73], v[78:79]
	v_mov_b32_e32 v78, v72
	v_mov_b32_e32 v79, v72
	v_pk_mul_f32 v[88:89], v[78:79], v[80:81]
	ds_read_b128 v[78:81], v244
	ds_read_b128 v[82:85], v244 offset:256
	s_waitcnt lgkmcnt(0)
	v_pk_fma_f32 v[80:81], v[88:89], v[80:81], v[84:85]
	v_pk_fma_f32 v[78:79], v[86:87], v[78:79], v[82:83]
.LBB0_1893:
	v_lshlrev_b64 v[76:77], 10, v[76:77]
	v_pk_fma_f32 v[64:65], v[78:79], s[72:73], v[64:65] op_sel_hi:[1,0,1]
	v_pk_fma_f32 v[80:81], v[80:81], s[72:73], v[66:67] op_sel_hi:[1,0,1]
	v_cvt_pk_bf16_f32 v66, v64, v65
	v_lshl_add_u64 v[64:65], v[76:77], 1, s[70:71]
	v_cvt_pk_bf16_f32 v67, v80, v81
	v_lshl_add_u64 v[64:65], v[144:145], 1, v[64:65]
	global_store_dwordx2 v[64:65], v[66:67], off
	s_waitcnt vmcnt(11)
	v_mov_b64_e32 v[78:79], v[200:201]
	global_load_dwordx2 v[200:201], v243, s[46:47] offset:32
	s_and_b64 vcc, exec, s[44:45]
	s_waitcnt lgkmcnt(0)
	v_lshlrev_b32_e32 v76, 16, v78
	v_and_b32_e32 v77, 0xffff0000, v78
	v_lshlrev_b32_e32 v78, 16, v79
	v_and_b32_e32 v79, 0xffff0000, v79
	s_cbranch_vccnz .LBB0_1895
	v_sub_f32_e32 v77, v77, v71
	v_sub_f32_e32 v76, v76, v71
	v_sub_f32_e32 v79, v79, v71
	v_sub_f32_e32 v78, v78, v71
	v_pk_mul_f32 v[84:85], v[72:73], v[76:77]
	v_mov_b32_e32 v76, v72
	v_mov_b32_e32 v77, v72
	v_pk_mul_f32 v[86:87], v[76:77], v[78:79]
	ds_read_b128 v[76:79], v244 offset:64
	ds_read_b128 v[80:83], v244 offset:320
	s_waitcnt lgkmcnt(0)
	v_pk_fma_f32 v[78:79], v[86:87], v[78:79], v[82:83]
	v_pk_fma_f32 v[76:77], v[84:85], v[76:77], v[80:81]
.LBB0_1895:
	v_pk_fma_f32 v[62:63], v[78:79], s[72:73], v[62:63] op_sel_hi:[1,0,1]
	v_pk_fma_f32 v[60:61], v[76:77], s[72:73], v[60:61] op_sel_hi:[1,0,1]
	s_and_b64 vcc, exec, s[44:45]
	v_cvt_pk_bf16_f32 v60, v60, v61
	v_cvt_pk_bf16_f32 v61, v62, v63
	global_store_dwordx2 v[64:65], v[60:61], off offset:32
	s_waitcnt vmcnt(11)
	v_mov_b64_e32 v[76:77], v[202:203]
	global_load_dwordx2 v[202:203], v243, s[46:47] offset:256
	s_waitcnt lgkmcnt(0)
	v_lshlrev_b32_e32 v62, 16, v76
	v_and_b32_e32 v63, 0xffff0000, v76
	v_lshlrev_b32_e32 v76, 16, v77
	v_and_b32_e32 v77, 0xffff0000, v77
	s_cbranch_vccnz .LBB0_1897
	v_sub_f32_e32 v77, v77, v71
	v_sub_f32_e32 v76, v76, v71
	v_mov_b32_e32 v78, v72
	v_mov_b32_e32 v79, v72
	v_pk_mul_f32 v[76:77], v[78:79], v[76:77]
	ds_read_b128 v[78:81], v244 offset:128
	ds_read_b128 v[82:85], v244 offset:384
	v_sub_f32_e32 v63, v63, v71
	v_sub_f32_e32 v62, v62, v71
	v_pk_mul_f32 v[62:63], v[72:73], v[62:63]
	s_waitcnt lgkmcnt(0)
	v_pk_fma_f32 v[76:77], v[76:77], v[80:81], v[84:85]
	v_pk_fma_f32 v[62:63], v[62:63], v[78:79], v[82:83]
.LBB0_1897:
	v_pk_fma_f32 v[58:59], v[76:77], s[72:73], v[58:59] op_sel_hi:[1,0,1]
	v_pk_fma_f32 v[56:57], v[62:63], s[72:73], v[56:57] op_sel_hi:[1,0,1]
	s_and_b64 vcc, exec, s[44:45]
	v_cvt_pk_bf16_f32 v56, v56, v57
	v_cvt_pk_bf16_f32 v57, v58, v59
	global_store_dwordx2 v[64:65], v[56:57], off offset:256
	s_waitcnt vmcnt(11)
	v_mov_b64_e32 v[62:63], v[204:205]
	global_load_dwordx2 v[204:205], v243, s[46:47] offset:288
	s_waitcnt lgkmcnt(0)
	v_lshlrev_b32_e32 v58, 16, v62
	v_and_b32_e32 v59, 0xffff0000, v62
	v_lshlrev_b32_e32 v62, 16, v63
	v_and_b32_e32 v63, 0xffff0000, v63
	s_cbranch_vccnz .LBB0_1899
	v_sub_f32_e32 v59, v59, v71
	v_sub_f32_e32 v58, v58, v71
	v_sub_f32_e32 v63, v63, v71
	v_sub_f32_e32 v62, v62, v71
	v_pk_mul_f32 v[58:59], v[72:73], v[58:59]
	v_mov_b32_e32 v73, v72
	v_pk_mul_f32 v[62:63], v[72:73], v[62:63]
	ds_read_b128 v[70:73], v244 offset:192
	ds_read_b128 v[74:77], v244 offset:448
	s_waitcnt lgkmcnt(0)
	v_pk_fma_f32 v[62:63], v[62:63], v[72:73], v[76:77]
	v_pk_fma_f32 v[58:59], v[58:59], v[70:71], v[74:75]

; __device__ __forceinline__ void stats_main(const float* stm, int row, int fq, float& mu, float& rs) {
;     const f32x4* p = (const f32x4*)(stm + (size_t)row * 32 + fq * 8);
;     const f32x4 a = p[0], b = p[1];
;     float s1 = (a.x + a.z) + (b.x + b.z), s2 = (a.y + a.w) + (b.y + b.w);
;     s1 += __shfl_xor(s1, 16); s2 += __shfl_xor(s2, 16); s1 += __shfl_xor(s1, 32); s2 += __shfl_xor(s2, 32);
;     mu = s1 * (1.f / DM); rs = __builtin_amdgcn_rsqf(fmaxf(s2 * (1.f / DM) - mu * mu, 0.f) + LN_EPS);
; }
;     __device__ __forceinline__ void operator()(const f32x4 (&acc)[2][2][4][2], const pg8::Unit& u, int wr, int wc, int fr, int fq) const {
;     ...
;                 const int row = u.pm * 256 + ai * 128 + wr * 64 + m * 16 + fr;
;                 float mu = 0.f, rs = 1.f; if (ln) stats_main(stm_p, row, fq, mu, rs);
.LBB0_1901:
	s_or_b64 exec, exec, s[0:1]
	v_add_u32_e32 v60, 0x90, v146
	v_ashrrev_i32_e32 v61, 31, v60
	s_and_b64 vcc, exec, s[44:45]
	v_lshlrev_b64 v[52:53], 7, v[60:61]
	s_cbranch_vccnz .LBB0_1903
	v_lshl_add_u64 v[58:59], v[134:135], 0, v[52:53]
	s_waitcnt lgkmcnt(0)
	s_waitcnt vmcnt(10)
	v_mov_b64_e32 v[54:55], v[214:215]
	v_mov_b64_e32 v[56:57], v[216:217]
	s_waitcnt vmcnt(11)
	v_mov_b64_e32 v[62:63], v[206:207]
	v_mov_b64_e32 v[64:65], v[208:209]
	s_waitcnt lgkmcnt(0)
	v_mov_b32_e32 v58, v54
	s_waitcnt lgkmcnt(0)
	v_mov_b32_e32 v59, v62
	v_mov_b32_e32 v66, v56
	v_mov_b32_e32 v67, v64
	v_pk_add_f32 v[58:59], v[58:59], v[66:67]
	v_add_f32_e32 v54, v55, v57
	v_add_f32_e32 v56, v63, v65
	v_mov_b32_e32 v55, v58
	v_mov_b32_e32 v57, v59
	v_pk_add_f32 v[54:55], v[54:55], v[56:57]
	ds_bpermute_b32 v57, v165, v55
	ds_bpermute_b32 v56, v165, v54
	s_waitcnt lgkmcnt(0)
	v_pk_add_f32 v[54:55], v[54:55], v[56:57]
	ds_bpermute_b32 v57, v164, v55
	ds_bpermute_b32 v56, v164, v54
	s_waitcnt lgkmcnt(0)
	v_pk_add_f32 v[54:55], v[54:55], v[56:57]
	s_nop 0
	v_pk_mul_f32 v[54:55], v[54:55], s[82:83] op_sel_hi:[1,0]
	s_nop 0
	v_fma_f32 v3, -v55, v55, v54
	v_max_f32_e32 v3, 0, v3
	v_add_f32_e32 v3, 0x3727c5ac, v3
	v_rsq_f32_e32 v56, v3
	s_branch .LBB0_1904

; __device__ __forceinline__ u32x2 pk4(f32x4 v) { u32x2 r; r.x = pk2(v.x, v.y); r.y = pk2(v.z, v.w); return r; }
;     __device__ __forceinline__ void operator()(const f32x4 (&acc)[2][2][4][2], const pg8::Unit& u, int wr, int wc, int fr, int fq) const {
;     ...
;                 for (int bj = 0; bj < 2; ++bj)
; #pragma unroll
;                     for (int n = 0; n < 2; ++n) {
;                         const int col = u.pn * 256 + bj * 128 + wc * 32 + n * 16 + fq * 4;
;                         const u32x2 raw = *(const u32x2*)(src + (size_t)row * DM + col);
;                         f32x4 x = (f32x4){bflo(raw.x), bfhi(raw.x), bflo(raw.y), bfhi(raw.y)};
;                         if (ln) x = (x - mu) * rs * *(const f32x4*)(g + col) + *(const f32x4*)(b + col);
;                         const u32x2 pz = pk4(x * ALPHA + acc[ai][bj][m][n]);
;                         *(u32x2*)(dst + (size_t)row * DM + col) = pz;
;                         const float z0 = bflo(pz.x), z1 = bfhi(pz.x), z2 = bflo(pz.y), z3 = bfhi(pz.y);
;                         s1 += (z0 + z1) + (z2 + z3); s2 += (z0 * z0 + z1 * z1) + (z2 * z2 + z3 * z3);
;                     }
.LBB0_1904:
	v_lshlrev_b64 v[58:59], 11, v[60:61]
	v_lshl_add_u64 v[58:59], s[46:47], 0, v[58:59]
	v_lshl_add_u64 v[58:59], v[144:145], 1, v[58:59]
	v_add_u32_e32 v243, 0x58000, v242
	s_waitcnt vmcnt(9)
	v_mov_b64_e32 v[64:65], v[234:235]
	global_load_dwordx4 v[206:209], v[248:249], off offset:2064
	global_load_dwordx4 v[214:217], v[248:249], off offset:2048
	global_load_dwordx2 v[234:235], v243, s[46:47]
	v_mov_b32_e32 v57, v56
	s_and_b64 vcc, exec, s[44:45]
	s_waitcnt lgkmcnt(0)
	v_lshlrev_b32_e32 v62, 16, v64
	v_and_b32_e32 v63, 0xffff0000, v64
	v_lshlrev_b32_e32 v64, 16, v65
	v_and_b32_e32 v65, 0xffff0000, v65
	s_cbranch_vccnz .LBB0_1906
	v_sub_f32_e32 v63, v63, v55
	v_sub_f32_e32 v62, v62, v55
	v_sub_f32_e32 v65, v65, v55
	v_sub_f32_e32 v64, v64, v55
	v_pk_mul_f32 v[70:71], v[56:57], v[62:63]
	v_mov_b32_e32 v62, v56
	v_mov_b32_e32 v63, v56
	v_pk_mul_f32 v[72:73], v[62:63], v[64:65]
	ds_read_b128 v[62:65], v244
	ds_read_b128 v[66:69], v244 offset:256
	s_waitcnt lgkmcnt(0)
	v_pk_fma_f32 v[64:65], v[72:73], v[64:65], v[68:69]
	v_pk_fma_f32 v[62:63], v[70:71], v[62:63], v[66:67]
.LBB0_1906:
	v_lshlrev_b64 v[60:61], 10, v[60:61]
	v_pk_fma_f32 v[48:49], v[62:63], s[72:73], v[48:49] op_sel_hi:[1,0,1]
	v_pk_fma_f32 v[64:65], v[64:65], s[72:73], v[50:51] op_sel_hi:[1,0,1]
	v_cvt_pk_bf16_f32 v50, v48, v49
	v_lshl_add_u64 v[48:49], v[60:61], 1, s[70:71]
	v_cvt_pk_bf16_f32 v51, v64, v65
	v_lshl_add_u64 v[48:49], v[144:145], 1, v[48:49]
	global_store_dwordx2 v[48:49], v[50:51], off
	s_waitcnt vmcnt(11)
	v_mov_b64_e32 v[62:63], v[236:237]
	global_load_dwordx2 v[236:237], v243, s[46:47] offset:32
	s_and_b64 vcc, exec, s[44:45]
	s_waitcnt lgkmcnt(0)
	v_lshlrev_b32_e32 v60, 16, v62
	v_and_b32_e32 v61, 0xffff0000, v62
	v_lshlrev_b32_e32 v62, 16, v63
	v_and_b32_e32 v63, 0xffff0000, v63
	s_cbranch_vccnz .LBB0_1908
	v_sub_f32_e32 v61, v61, v55
	v_sub_f32_e32 v60, v60, v55
	v_sub_f32_e32 v63, v63, v55
	v_sub_f32_e32 v62, v62, v55
	v_pk_mul_f32 v[68:69], v[56:57], v[60:61]
	v_mov_b32_e32 v60, v56
	v_mov_b32_e32 v61, v56
	v_pk_mul_f32 v[70:71], v[60:61], v[62:63]
	ds_read_b128 v[60:63], v244 offset:64
	ds_read_b128 v[64:67], v244 offset:320
	s_waitcnt lgkmcnt(0)
	v_pk_fma_f32 v[62:63], v[70:71], v[62:63], v[66:67]
	v_pk_fma_f32 v[60:61], v[68:69], v[60:61], v[64:65]
.LBB0_1908:
	v_pk_fma_f32 v[46:47], v[62:63], s[72:73], v[46:47] op_sel_hi:[1,0,1]
	v_pk_fma_f32 v[44:45], v[60:61], s[72:73], v[44:45] op_sel_hi:[1,0,1]
	s_and_b64 vcc, exec, s[44:45]
	v_cvt_pk_bf16_f32 v44, v44, v45
	v_cvt_pk_bf16_f32 v45, v46, v47
	global_store_dwordx2 v[48:49], v[44:45], off offset:32
	s_waitcnt vmcnt(11)
	v_mov_b64_e32 v[60:61], v[238:239]
	global_load_dwordx2 v[238:239], v243, s[46:47] offset:256
	s_waitcnt lgkmcnt(0)
	v_lshlrev_b32_e32 v46, 16, v60
	v_and_b32_e32 v47, 0xffff0000, v60
	v_lshlrev_b32_e32 v60, 16, v61
	v_and_b32_e32 v61, 0xffff0000, v61
	s_cbranch_vccnz .LBB0_1910
	v_sub_f32_e32 v61, v61, v55
	v_sub_f32_e32 v60, v60, v55
	v_mov_b32_e32 v62, v56
	v_mov_b32_e32 v63, v56
	v_pk_mul_f32 v[60:61], v[62:63], v[60:61]
	ds_read_b128 v[62:65], v244 offset:128
	ds_read_b128 v[66:69], v244 offset:384
	v_sub_f32_e32 v47, v47, v55
	v_sub_f32_e32 v46, v46, v55
	v_pk_mul_f32 v[46:47], v[56:57], v[46:47]
	s_waitcnt lgkmcnt(0)
	v_pk_fma_f32 v[60:61], v[60:61], v[64:65], v[68:69]
	v_pk_fma_f32 v[46:47], v[46:47], v[62:63], v[66:67]
.LBB0_1910:
	v_pk_fma_f32 v[42:43], v[60:61], s[72:73], v[42:43] op_sel_hi:[1,0,1]
	v_pk_fma_f32 v[40:41], v[46:47], s[72:73], v[40:41] op_sel_hi:[1,0,1]
	s_and_b64 vcc, exec, s[44:45]
	v_cvt_pk_bf16_f32 v40, v40, v41
	v_cvt_pk_bf16_f32 v41, v42, v43
	global_store_dwordx2 v[48:49], v[40:41], off offset:256
	s_waitcnt vmcnt(11)
	v_mov_b64_e32 v[46:47], v[240:241]
	global_load_dwordx2 v[240:241], v243, s[46:47] offset:288
	s_waitcnt lgkmcnt(0)
	v_lshlrev_b32_e32 v42, 16, v46
	v_and_b32_e32 v43, 0xffff0000, v46
	v_lshlrev_b32_e32 v46, 16, v47
	v_and_b32_e32 v47, 0xffff0000, v47
	s_cbranch_vccnz .LBB0_1912
	v_sub_f32_e32 v43, v43, v55
	v_sub_f32_e32 v42, v42, v55
	v_sub_f32_e32 v47, v47, v55
	v_sub_f32_e32 v46, v46, v55
	v_pk_mul_f32 v[42:43], v[56:57], v[42:43]
	v_mov_b32_e32 v57, v56
	v_pk_mul_f32 v[46:47], v[56:57], v[46:47]
	ds_read_b128 v[54:57], v244 offset:192
	ds_read_b128 v[58:61], v244 offset:448
	s_waitcnt lgkmcnt(0)
	v_pk_fma_f32 v[46:47], v[46:47], v[56:57], v[60:61]
	v_pk_fma_f32 v[42:43], v[42:43], v[54:55], v[58:59]

; __device__ __forceinline__ void stats_main(const float* stm, int row, int fq, float& mu, float& rs) {
;     const f32x4* p = (const f32x4*)(stm + (size_t)row * 32 + fq * 8);
;     const f32x4 a = p[0], b = p[1];
;     float s1 = (a.x + a.z) + (b.x + b.z), s2 = (a.y + a.w) + (b.y + b.w);
;     s1 += __shfl_xor(s1, 16); s2 += __shfl_xor(s2, 16); s1 += __shfl_xor(s1, 32); s2 += __shfl_xor(s2, 32);
;     mu = s1 * (1.f / DM); rs = __builtin_amdgcn_rsqf(fmaxf(s2 * (1.f / DM) - mu * mu, 0.f) + LN_EPS);
; }
;     __device__ __forceinline__ void operator()(const f32x4 (&acc)[2][2][4][2], const pg8::Unit& u, int wr, int wc, int fr, int fq) const {
;     ...
;                 const int row = u.pm * 256 + ai * 128 + wr * 64 + m * 16 + fr;
;                 float mu = 0.f, rs = 1.f; if (ln) stats_main(stm_p, row, fq, mu, rs);
.LBB0_1914:
	s_or_b64 exec, exec, s[0:1]
	v_add_u32_e32 v44, 0xa0, v146
	v_ashrrev_i32_e32 v45, 31, v44
	s_and_b64 vcc, exec, s[44:45]
	v_lshlrev_b64 v[36:37], 7, v[44:45]
	s_cbranch_vccnz .LBB0_1916
	v_lshl_add_u64 v[42:43], v[134:135], 0, v[36:37]
	s_waitcnt lgkmcnt(0)
	s_waitcnt vmcnt(10)
	v_mov_b64_e32 v[38:39], v[194:195]
	v_mov_b64_e32 v[40:41], v[196:197]
	s_waitcnt vmcnt(11)
	v_mov_b64_e32 v[46:47], v[190:191]
	v_mov_b64_e32 v[48:49], v[192:193]
	s_waitcnt lgkmcnt(0)
	v_mov_b32_e32 v42, v38
	s_waitcnt lgkmcnt(0)
	v_mov_b32_e32 v43, v46
	v_mov_b32_e32 v50, v40
	v_mov_b32_e32 v51, v48
	v_pk_add_f32 v[42:43], v[42:43], v[50:51]
	v_add_f32_e32 v38, v39, v41
	v_add_f32_e32 v40, v47, v49
	v_mov_b32_e32 v39, v42
	v_mov_b32_e32 v41, v43
	v_pk_add_f32 v[38:39], v[38:39], v[40:41]
	ds_bpermute_b32 v41, v165, v39
	ds_bpermute_b32 v40, v165, v38
	s_waitcnt lgkmcnt(0)
	v_pk_add_f32 v[38:39], v[38:39], v[40:41]
	ds_bpermute_b32 v41, v164, v39
	ds_bpermute_b32 v40, v164, v38
	s_waitcnt lgkmcnt(0)
	v_pk_add_f32 v[38:39], v[38:39], v[40:41]
	s_nop 0
	v_pk_mul_f32 v[38:39], v[38:39], s[82:83] op_sel_hi:[1,0]
	s_nop 0
	v_fma_f32 v3, -v39, v39, v38
	v_max_f32_e32 v3, 0, v3
	v_add_f32_e32 v3, 0x3727c5ac, v3
	v_rsq_f32_e32 v40, v3
	s_branch .LBB0_1917

; __device__ __forceinline__ u32x2 pk4(f32x4 v) { u32x2 r; r.x = pk2(v.x, v.y); r.y = pk2(v.z, v.w); return r; }
;     __device__ __forceinline__ void operator()(const f32x4 (&acc)[2][2][4][2], const pg8::Unit& u, int wr, int wc, int fr, int fq) const {
;     ...
;                 for (int bj = 0; bj < 2; ++bj)
; #pragma unroll
;                     for (int n = 0; n < 2; ++n) {
;                         const int col = u.pn * 256 + bj * 128 + wc * 32 + n * 16 + fq * 4;
;                         const u32x2 raw = *(const u32x2*)(src + (size_t)row * DM + col);
;                         f32x4 x = (f32x4){bflo(raw.x), bfhi(raw.x), bflo(raw.y), bfhi(raw.y)};
;                         if (ln) x = (x - mu) * rs * *(const f32x4*)(g + col) + *(const f32x4*)(b + col);
;                         const u32x2 pz = pk4(x * ALPHA + acc[ai][bj][m][n]);
;                         *(u32x2*)(dst + (size_t)row * DM + col) = pz;
;                         const float z0 = bflo(pz.x), z1 = bfhi(pz.x), z2 = bflo(pz.y), z3 = bfhi(pz.y);
;                         s1 += (z0 + z1) + (z2 + z3); s2 += (z0 * z0 + z1 * z1) + (z2 * z2 + z3 * z3);
;                     }
.LBB0_1917:
	v_lshlrev_b64 v[42:43], 11, v[44:45]
	v_lshl_add_u64 v[42:43], s[46:47], 0, v[42:43]
	v_lshl_add_u64 v[42:43], v[144:145], 1, v[42:43]
	s_waitcnt vmcnt(9)
	v_mov_b64_e32 v[48:49], v[198:199]
	v_mov_b32_e32 v41, v40
	s_and_b64 vcc, exec, s[44:45]
	s_waitcnt lgkmcnt(0)
	v_lshlrev_b32_e32 v46, 16, v48
	v_and_b32_e32 v47, 0xffff0000, v48
	v_lshlrev_b32_e32 v48, 16, v49
	v_and_b32_e32 v49, 0xffff0000, v49
	s_cbranch_vccnz .LBB0_1919
	v_sub_f32_e32 v47, v47, v39
	v_sub_f32_e32 v46, v46, v39
	v_sub_f32_e32 v49, v49, v39
	v_sub_f32_e32 v48, v48, v39
	v_pk_mul_f32 v[54:55], v[40:41], v[46:47]
	v_mov_b32_e32 v46, v40
	v_mov_b32_e32 v47, v40
	v_pk_mul_f32 v[56:57], v[46:47], v[48:49]
	ds_read_b128 v[46:49], v244
	ds_read_b128 v[50:53], v244 offset:256
	s_waitcnt lgkmcnt(0)
	v_pk_fma_f32 v[48:49], v[56:57], v[48:49], v[52:53]
	v_pk_fma_f32 v[46:47], v[54:55], v[46:47], v[50:51]
.LBB0_1919:
	v_lshlrev_b64 v[44:45], 10, v[44:45]
	v_pk_fma_f32 v[32:33], v[46:47], s[72:73], v[32:33] op_sel_hi:[1,0,1]
	v_pk_fma_f32 v[48:49], v[48:49], s[72:73], v[34:35] op_sel_hi:[1,0,1]
	v_cvt_pk_bf16_f32 v34, v32, v33
	v_lshl_add_u64 v[32:33], v[44:45], 1, s[70:71]
	v_cvt_pk_bf16_f32 v35, v48, v49
	v_lshl_add_u64 v[32:33], v[144:145], 1, v[32:33]
	global_store_dwordx2 v[32:33], v[34:35], off
	s_waitcnt vmcnt(8)
	v_mov_b64_e32 v[46:47], v[200:201]
	s_and_b64 vcc, exec, s[44:45]
	s_waitcnt lgkmcnt(0)
	v_lshlrev_b32_e32 v44, 16, v46
	v_and_b32_e32 v45, 0xffff0000, v46
	v_lshlrev_b32_e32 v46, 16, v47
	v_and_b32_e32 v47, 0xffff0000, v47
	s_cbranch_vccnz .LBB0_1921
	v_sub_f32_e32 v45, v45, v39
	v_sub_f32_e32 v44, v44, v39
	v_sub_f32_e32 v47, v47, v39
	v_sub_f32_e32 v46, v46, v39
	v_pk_mul_f32 v[52:53], v[40:41], v[44:45]
	v_mov_b32_e32 v44, v40
	v_mov_b32_e32 v45, v40
	v_pk_mul_f32 v[54:55], v[44:45], v[46:47]
	ds_read_b128 v[44:47], v244 offset:64
	ds_read_b128 v[48:51], v244 offset:320
	s_waitcnt lgkmcnt(0)
	v_pk_fma_f32 v[46:47], v[54:55], v[46:47], v[50:51]
	v_pk_fma_f32 v[44:45], v[52:53], v[44:45], v[48:49]
.LBB0_1921:
	v_pk_fma_f32 v[30:31], v[46:47], s[72:73], v[30:31] op_sel_hi:[1,0,1]
	v_pk_fma_f32 v[28:29], v[44:45], s[72:73], v[28:29] op_sel_hi:[1,0,1]
	s_and_b64 vcc, exec, s[44:45]
	v_cvt_pk_bf16_f32 v28, v28, v29
	v_cvt_pk_bf16_f32 v29, v30, v31
	global_store_dwordx2 v[32:33], v[28:29], off offset:32
	s_waitcnt vmcnt(7)
	v_mov_b64_e32 v[44:45], v[202:203]
	s_waitcnt lgkmcnt(0)
	v_lshlrev_b32_e32 v30, 16, v44
	v_and_b32_e32 v31, 0xffff0000, v44
	v_lshlrev_b32_e32 v44, 16, v45
	v_and_b32_e32 v45, 0xffff0000, v45
	s_cbranch_vccnz .LBB0_1923
	v_sub_f32_e32 v45, v45, v39
	v_sub_f32_e32 v44, v44, v39
	v_mov_b32_e32 v46, v40
	v_mov_b32_e32 v47, v40
	v_pk_mul_f32 v[44:45], v[46:47], v[44:45]
	ds_read_b128 v[46:49], v244 offset:128
	ds_read_b128 v[50:53], v244 offset:384
	v_sub_f32_e32 v31, v31, v39
	v_sub_f32_e32 v30, v30, v39
	v_pk_mul_f32 v[30:31], v[40:41], v[30:31]
	s_waitcnt lgkmcnt(0)
	v_pk_fma_f32 v[44:45], v[44:45], v[48:49], v[52:53]
	v_pk_fma_f32 v[30:31], v[30:31], v[46:47], v[50:51]
.LBB0_1923:
	v_pk_fma_f32 v[26:27], v[44:45], s[72:73], v[26:27] op_sel_hi:[1,0,1]
	v_pk_fma_f32 v[24:25], v[30:31], s[72:73], v[24:25] op_sel_hi:[1,0,1]
	s_and_b64 vcc, exec, s[44:45]
	v_cvt_pk_bf16_f32 v24, v24, v25
	v_cvt_pk_bf16_f32 v25, v26, v27
	global_store_dwordx2 v[32:33], v[24:25], off offset:256
	s_waitcnt vmcnt(6)
	v_mov_b64_e32 v[30:31], v[204:205]
	s_waitcnt lgkmcnt(0)
	v_lshlrev_b32_e32 v26, 16, v30
	v_and_b32_e32 v27, 0xffff0000, v30
	v_lshlrev_b32_e32 v30, 16, v31
	v_and_b32_e32 v31, 0xffff0000, v31
	s_cbranch_vccnz .LBB0_1925
	v_sub_f32_e32 v27, v27, v39
	v_sub_f32_e32 v26, v26, v39
	v_sub_f32_e32 v31, v31, v39
	v_sub_f32_e32 v30, v30, v39
	v_pk_mul_f32 v[26:27], v[40:41], v[26:27]
	v_mov_b32_e32 v41, v40
	v_pk_mul_f32 v[30:31], v[40:41], v[30:31]
	ds_read_b128 v[38:41], v244 offset:192
	ds_read_b128 v[42:45], v244 offset:448
	s_waitcnt lgkmcnt(0)
	v_pk_fma_f32 v[30:31], v[30:31], v[40:41], v[44:45]
	v_pk_fma_f32 v[26:27], v[26:27], v[38:39], v[42:43]

; __device__ __forceinline__ void stats_main(const float* stm, int row, int fq, float& mu, float& rs) {
;     const f32x4* p = (const f32x4*)(stm + (size_t)row * 32 + fq * 8);
;     const f32x4 a = p[0], b = p[1];
;     float s1 = (a.x + a.z) + (b.x + b.z), s2 = (a.y + a.w) + (b.y + b.w);
;     s1 += __shfl_xor(s1, 16); s2 += __shfl_xor(s2, 16); s1 += __shfl_xor(s1, 32); s2 += __shfl_xor(s2, 32);
;     mu = s1 * (1.f / DM); rs = __builtin_amdgcn_rsqf(fmaxf(s2 * (1.f / DM) - mu * mu, 0.f) + LN_EPS);
; }
;     __device__ __forceinline__ void operator()(const f32x4 (&acc)[2][2][4][2], const pg8::Unit& u, int wr, int wc, int fr, int fq) const {
;     ...
;                 const int row = u.pm * 256 + ai * 128 + wr * 64 + m * 16 + fr;
;                 float mu = 0.f, rs = 1.f; if (ln) stats_main(stm_p, row, fq, mu, rs);
.LBB0_1927:
	s_or_b64 exec, exec, s[0:1]
	v_add_u32_e32 v28, 0xb0, v146
	v_ashrrev_i32_e32 v29, 31, v28
	s_and_b64 vcc, exec, s[44:45]
	v_lshlrev_b64 v[20:21], 7, v[28:29]
	s_cbranch_vccnz .LBB0_1929
	v_lshl_add_u64 v[26:27], v[134:135], 0, v[20:21]
	s_waitcnt lgkmcnt(0)
	s_waitcnt vmcnt(4)
	v_mov_b64_e32 v[22:23], v[214:215]
	v_mov_b64_e32 v[24:25], v[216:217]
	s_waitcnt vmcnt(5)
	v_mov_b64_e32 v[30:31], v[206:207]
	v_mov_b64_e32 v[32:33], v[208:209]
	s_waitcnt lgkmcnt(0)
	v_mov_b32_e32 v26, v22
	s_waitcnt lgkmcnt(0)
	v_mov_b32_e32 v27, v30
	v_mov_b32_e32 v34, v24
	v_mov_b32_e32 v35, v32
	v_pk_add_f32 v[26:27], v[26:27], v[34:35]
	v_add_f32_e32 v22, v23, v25
	v_add_f32_e32 v24, v31, v33
	v_mov_b32_e32 v23, v26
	v_mov_b32_e32 v25, v27
	v_pk_add_f32 v[22:23], v[22:23], v[24:25]
	ds_bpermute_b32 v25, v165, v23
	ds_bpermute_b32 v24, v165, v22
	s_waitcnt lgkmcnt(0)
	v_pk_add_f32 v[22:23], v[22:23], v[24:25]
	ds_bpermute_b32 v25, v164, v23
	ds_bpermute_b32 v24, v164, v22
	s_waitcnt lgkmcnt(0)
	v_pk_add_f32 v[22:23], v[22:23], v[24:25]
	s_nop 0
	v_pk_mul_f32 v[22:23], v[22:23], s[82:83] op_sel_hi:[1,0]
	s_nop 0
	v_fma_f32 v3, -v23, v23, v22
	v_max_f32_e32 v3, 0, v3
	v_add_f32_e32 v3, 0x3727c5ac, v3
	v_rsq_f32_e32 v24, v3
	s_branch .LBB0_1930

; __device__ __forceinline__ u32x2 pk4(f32x4 v) { u32x2 r; r.x = pk2(v.x, v.y); r.y = pk2(v.z, v.w); return r; }
;     __device__ __forceinline__ void operator()(const f32x4 (&acc)[2][2][4][2], const pg8::Unit& u, int wr, int wc, int fr, int fq) const {
;     ...
;                 for (int bj = 0; bj < 2; ++bj)
; #pragma unroll
;                     for (int n = 0; n < 2; ++n) {
;                         const int col = u.pn * 256 + bj * 128 + wc * 32 + n * 16 + fq * 4;
;                         const u32x2 raw = *(const u32x2*)(src + (size_t)row * DM + col);
;                         f32x4 x = (f32x4){bflo(raw.x), bfhi(raw.x), bflo(raw.y), bfhi(raw.y)};
;                         if (ln) x = (x - mu) * rs * *(const f32x4*)(g + col) + *(const f32x4*)(b + col);
;                         const u32x2 pz = pk4(x * ALPHA + acc[ai][bj][m][n]);
;                         *(u32x2*)(dst + (size_t)row * DM + col) = pz;
;                         const float z0 = bflo(pz.x), z1 = bfhi(pz.x), z2 = bflo(pz.y), z3 = bfhi(pz.y);
;                         s1 += (z0 + z1) + (z2 + z3); s2 += (z0 * z0 + z1 * z1) + (z2 * z2 + z3 * z3);
;                     }
.LBB0_1930:
	v_lshlrev_b64 v[26:27], 11, v[28:29]
	v_lshl_add_u64 v[26:27], s[46:47], 0, v[26:27]
	v_lshl_add_u64 v[26:27], v[144:145], 1, v[26:27]
	s_waitcnt vmcnt(3)
	v_mov_b64_e32 v[32:33], v[234:235]
	v_mov_b32_e32 v25, v24
	s_and_b64 vcc, exec, s[44:45]
	s_waitcnt lgkmcnt(0)
	v_lshlrev_b32_e32 v30, 16, v32
	v_and_b32_e32 v31, 0xffff0000, v32
	v_lshlrev_b32_e32 v32, 16, v33
	v_and_b32_e32 v33, 0xffff0000, v33
	s_cbranch_vccnz .LBB0_1932
	v_sub_f32_e32 v31, v31, v23
	v_sub_f32_e32 v30, v30, v23
	v_sub_f32_e32 v33, v33, v23
	v_sub_f32_e32 v32, v32, v23
	v_pk_mul_f32 v[38:39], v[24:25], v[30:31]
	v_mov_b32_e32 v30, v24
	v_mov_b32_e32 v31, v24
	v_pk_mul_f32 v[40:41], v[30:31], v[32:33]
	ds_read_b128 v[30:33], v244
	ds_read_b128 v[34:37], v244 offset:256
	s_waitcnt lgkmcnt(0)
	v_pk_fma_f32 v[32:33], v[40:41], v[32:33], v[36:37]
	v_pk_fma_f32 v[30:31], v[38:39], v[30:31], v[34:35]
.LBB0_1932:
	v_lshlrev_b64 v[28:29], 10, v[28:29]
	v_pk_fma_f32 v[16:17], v[30:31], s[72:73], v[16:17] op_sel_hi:[1,0,1]
	v_pk_fma_f32 v[32:33], v[32:33], s[72:73], v[18:19] op_sel_hi:[1,0,1]
	v_cvt_pk_bf16_f32 v18, v16, v17
	v_lshl_add_u64 v[16:17], v[28:29], 1, s[70:71]
	v_cvt_pk_bf16_f32 v19, v32, v33
	v_lshl_add_u64 v[16:17], v[144:145], 1, v[16:17]
	global_store_dwordx2 v[16:17], v[18:19], off
	s_waitcnt vmcnt(2)
	v_mov_b64_e32 v[30:31], v[236:237]
	s_and_b64 vcc, exec, s[44:45]
	s_waitcnt lgkmcnt(0)
	v_lshlrev_b32_e32 v28, 16, v30
	v_and_b32_e32 v29, 0xffff0000, v30
	v_lshlrev_b32_e32 v30, 16, v31
	v_and_b32_e32 v31, 0xffff0000, v31
	s_cbranch_vccnz .LBB0_1934
	v_sub_f32_e32 v29, v29, v23
	v_sub_f32_e32 v28, v28, v23
	v_sub_f32_e32 v31, v31, v23
	v_sub_f32_e32 v30, v30, v23
	v_pk_mul_f32 v[36:37], v[24:25], v[28:29]
	v_mov_b32_e32 v28, v24
	v_mov_b32_e32 v29, v24
	v_pk_mul_f32 v[38:39], v[28:29], v[30:31]
	ds_read_b128 v[28:31], v244 offset:64
	ds_read_b128 v[32:35], v244 offset:320
	s_waitcnt lgkmcnt(0)
	v_pk_fma_f32 v[30:31], v[38:39], v[30:31], v[34:35]
	v_pk_fma_f32 v[28:29], v[36:37], v[28:29], v[32:33]
.LBB0_1934:
	v_pk_fma_f32 v[14:15], v[30:31], s[72:73], v[14:15] op_sel_hi:[1,0,1]
	v_pk_fma_f32 v[12:13], v[28:29], s[72:73], v[12:13] op_sel_hi:[1,0,1]
	s_and_b64 vcc, exec, s[44:45]
	v_cvt_pk_bf16_f32 v12, v12, v13
	v_cvt_pk_bf16_f32 v13, v14, v15
	global_store_dwordx2 v[16:17], v[12:13], off offset:32
	s_waitcnt vmcnt(1)
	v_mov_b64_e32 v[28:29], v[238:239]
	s_waitcnt lgkmcnt(0)
	v_lshlrev_b32_e32 v14, 16, v28
	v_and_b32_e32 v15, 0xffff0000, v28
	v_lshlrev_b32_e32 v28, 16, v29
	v_and_b32_e32 v29, 0xffff0000, v29
	s_cbranch_vccnz .LBB0_1936
	v_sub_f32_e32 v29, v29, v23
	v_sub_f32_e32 v28, v28, v23
	v_mov_b32_e32 v30, v24
	v_mov_b32_e32 v31, v24
	v_pk_mul_f32 v[28:29], v[30:31], v[28:29]
	ds_read_b128 v[30:33], v244 offset:128
	ds_read_b128 v[34:37], v244 offset:384
	v_sub_f32_e32 v15, v15, v23
	v_sub_f32_e32 v14, v14, v23
	v_pk_mul_f32 v[14:15], v[24:25], v[14:15]
	s_waitcnt lgkmcnt(0)
	v_pk_fma_f32 v[28:29], v[28:29], v[32:33], v[36:37]
	v_pk_fma_f32 v[14:15], v[14:15], v[30:31], v[34:35]
.LBB0_1936:
	v_pk_fma_f32 v[10:11], v[28:29], s[72:73], v[10:11] op_sel_hi:[1,0,1]
	v_pk_fma_f32 v[8:9], v[14:15], s[72:73], v[8:9] op_sel_hi:[1,0,1]
	s_and_b64 vcc, exec, s[44:45]
	v_cvt_pk_bf16_f32 v8, v8, v9
	v_cvt_pk_bf16_f32 v9, v10, v11
	global_store_dwordx2 v[16:17], v[8:9], off offset:256
	s_waitcnt vmcnt(0)
	v_mov_b64_e32 v[14:15], v[240:241]
	s_waitcnt lgkmcnt(0)
	v_lshlrev_b32_e32 v10, 16, v14
	v_and_b32_e32 v11, 0xffff0000, v14
	v_lshlrev_b32_e32 v14, 16, v15
	v_and_b32_e32 v15, 0xffff0000, v15
	s_cbranch_vccnz .LBB0_1938
	v_sub_f32_e32 v11, v11, v23
	v_sub_f32_e32 v10, v10, v23
	v_sub_f32_e32 v15, v15, v23
	v_sub_f32_e32 v14, v14, v23
	v_pk_mul_f32 v[10:11], v[24:25], v[10:11]
	v_mov_b32_e32 v25, v24
	v_pk_mul_f32 v[14:15], v[24:25], v[14:15]
	ds_read_b128 v[22:25], v244 offset:192
	ds_read_b128 v[26:29], v244 offset:448
	s_waitcnt lgkmcnt(0)
	v_pk_fma_f32 v[14:15], v[14:15], v[24:25], v[28:29]
	v_pk_fma_f32 v[10:11], v[10:11], v[22:23], v[26:27]

; __device__ __forceinline__ u32x2 pk4(f32x4 v) { u32x2 r; r.x = pk2(v.x, v.y); r.y = pk2(v.z, v.w); return r; }
;     __device__ __forceinline__ void operator()(int row, int col, f32x4 v, int, float&, float&) const { *(u32x2*)(O + (size_t)row * ldc + col) = pk4(v * s); }
;     __device__ __forceinline__ void operator()(const f32x4 (&acc)[2][2][4][2], const pg8::Unit& u, int wr, int wc, int fr, int fq) const {
; #pragma unroll
;         for (int ai = 0; ai < 2; ++ai)
; #pragma unroll
;             for (int m = 0; m < 4; ++m) {
;                 const int row = u.pm * 256 + ai * 128 + wr * 64 + m * 16 + fr;
;                 float mu = 0.f, rs = 1.f; if (ln) stats_main(stm_p, row, fq, mu, rs);
;                 float s1 = 0.f, s2 = 0.f;
; #pragma unroll
;                 for (int bj = 0; bj < 2; ++bj)
; #pragma unroll
;                     for (int n = 0; n < 2; ++n) {
;                         const int col = u.pn * 256 + bj * 128 + wc * 32 + n * 16 + fq * 4;
;                         const u32x2 raw = *(const u32x2*)(src + (size_t)row * DM + col);
;                         f32x4 x = (f32x4){bflo(raw.x), bfhi(raw.x), bflo(raw.y), bfhi(raw.y)};
;                         if (ln) x = (x - mu) * rs * *(const f32x4*)(g + col) + *(const f32x4*)(b + col);
;                         const u32x2 pz = pk4(x * ALPHA + acc[ai][bj][m][n]);
;                         *(u32x2*)(dst + (size_t)row * DM + col) = pz;
.LBB0_2203:
	v_readlane_b32 s70, v250, 30
	v_readlane_b32 s71, v250, 31
	v_and_b32_e32 v244, 0xfffffff0, v166
	v_lshl_add_u32 v244, s22, 8, v244
	v_and_b32_e32 v245, 31, v219
	v_add_u32_e32 v244, v244, v245
	v_lshrrev_b32_e32 v245, 5, v219
	v_lshl_add_u32 v244, v245, 7, v244
	v_lshlrev_b32_e32 v244, 2, v244
	global_load_dword v214, v244, s[46:47]
	global_load_dword v215, v244, s[48:49]
	v_lshl_add_u32 v245, s23, 8, v164
	v_lshl_add_u32 v244, s22, 8, v166
	v_lshlrev_b32_e32 v242, 11, v245
	v_lshl_add_u32 v242, v244, 1, v242
	v_lshlrev_b32_e32 v246, 7, v245
	v_mov_b32_e32 v247, 0
	v_lshlrev_b32_e32 v248, 7, v245
	v_mov_b32_e32 v249, 0
	v_add_u32_e32 v246, 0x1000, v246
	v_add_u32_e32 v248, 0x5000, v248
	v_lshl_add_u64 v[246:247], v[246:247], 0, v[134:135]
	v_lshl_add_u64 v[248:249], v[248:249], 0, v[134:135]
	global_load_dwordx4 v[190:193], v[246:247], off offset:-4080
	global_load_dwordx4 v[194:197], v[246:247], off offset:-4096
	global_load_dwordx2 v[198:199], v242, s[70:71]
	global_load_dwordx2 v[200:201], v242, s[70:71] offset:32
	global_load_dwordx2 v[202:203], v242, s[70:71] offset:256
	global_load_dwordx2 v[204:205], v242, s[70:71] offset:288
	v_lshrrev_b32_e32 v245, 6, v164
	v_lshrrev_b32_e32 v244, 5, v166
	v_lshl_add_u32 v245, v245, 2, v244
	v_lshlrev_b32_e32 v245, 9, v245
	v_and_b32_e32 v244, 12, v166
	v_lshl_add_u32 v244, v244, 2, v245
	v_add_u32_e32 v244, 0x20000, v244
	v_lshl_add_u32 v245, v219, 2, v245
	v_add_u32_e32 v245, 0x20000, v245
	s_waitcnt vmcnt(7)
	ds_write_b32 v245, v214
	s_waitcnt vmcnt(6)
	ds_write_b32 v245, v215 offset:256
	v_add_u32_e32 v243, 0x8000, v242
	global_load_dwordx4 v[206:209], v[246:247], off offset:-2032
	global_load_dwordx4 v[214:217], v[246:247], off offset:-2048
	global_load_dwordx2 v[234:235], v243, s[70:71]
	global_load_dwordx2 v[236:237], v243, s[70:71] offset:32
	global_load_dwordx2 v[238:239], v243, s[70:71] offset:256
	global_load_dwordx2 v[240:241], v243, s[70:71] offset:288
	s_waitcnt lgkmcnt(0)
	v_and_b32_e32 v140, 64, v219
	v_lshl_add_u32 v146, s23, 8, v164
	v_xor_b32_e32 v3, 16, v219
	v_add_u32_e32 v140, 64, v140
	v_cmp_lt_i32_e32 vcc, v3, v140
	v_ashrrev_i32_e32 v147, 31, v146
	v_lshlrev_b64 v[148:149], 7, v[146:147]
	v_cndmask_b32_e32 v3, v219, v3, vcc
	v_lshlrev_b32_e32 v181, 2, v3
	v_xor_b32_e32 v3, 32, v219
	v_lshl_add_u64 v[150:151], v[134:135], 0, v[148:149]
	v_cmp_lt_i32_e32 vcc, v3, v140
	s_waitcnt vmcnt(11)
	v_mov_b64_e32 v[140:141], v[190:191]
	v_mov_b64_e32 v[142:143], v[192:193]
	global_load_dwordx4 v[190:193], v[246:247], off offset:16
	s_nop 0
	s_waitcnt vmcnt(11)
	v_mov_b64_e32 v[150:151], v[194:195]
	v_mov_b64_e32 v[152:153], v[196:197]
	global_load_dwordx4 v[194:197], v[246:247], off
	v_cndmask_b32_e32 v3, v219, v3, vcc
	v_lshlrev_b32_e32 v180, 2, v3
	v_readlane_b32 s70, v250, 30
	v_lshl_add_u32 v144, s22, 8, v166
	v_readlane_b32 s71, v250, 31
	v_ashrrev_i32_e32 v145, 31, v144
	s_lshl_b32 s0, s22, 3
	v_readlane_b32 s1, v252, 30
	s_or_b32 s60, s0, s1
	s_ashr_i32 s61, s60, 31
	s_waitcnt lgkmcnt(0)
	v_pk_add_f32 v[140:141], v[140:141], v[142:143]
	v_pk_add_f32 v[150:151], v[150:151], v[152:153]
	s_nop 0
	v_pk_add_f32 v[140:141], v[150:151], v[140:141]
	ds_bpermute_b32 v142, v181, v140
	ds_bpermute_b32 v143, v181, v141
	s_waitcnt lgkmcnt(0)
	v_pk_add_f32 v[140:141], v[140:141], v[142:143]
	ds_bpermute_b32 v142, v180, v140
	ds_bpermute_b32 v143, v180, v141
	s_waitcnt lgkmcnt(0)
	v_pk_add_f32 v[140:141], v[140:141], v[142:143]
	s_nop 0
	v_pk_mul_f32 v[160:161], v[140:141], s[82:83] op_sel_hi:[1,0]
	v_lshlrev_b64 v[140:141], 11, v[146:147]
	v_lshl_add_u64 v[140:141], s[70:71], 0, v[140:141]
	v_lshl_add_u64 v[152:153], v[144:145], 1, v[140:141]
	v_add_u32_e32 v243, 0x10000, v242
	s_waitcnt vmcnt(11)
	v_mov_b64_e32 v[140:141], v[198:199]
	global_load_dwordx2 v[198:199], v243, s[70:71]
	v_fma_f32 v3, -v160, v160, v161
	v_max_f32_e32 v3, 0, v3
	v_add_f32_e32 v3, 0x3727c5ac, v3
	v_rsq_f32_e32 v162, v3
	s_waitcnt lgkmcnt(0)
	v_lshlrev_b32_e32 v142, 16, v141
	v_and_b32_e32 v143, 0xffff0000, v141
	v_lshlrev_b32_e32 v3, 16, v140
	v_and_b32_e32 v140, 0xffff0000, v140
	v_sub_f32_e32 v143, v143, v160
	v_sub_f32_e32 v142, v142, v160
	v_sub_f32_e32 v141, v140, v160
	v_sub_f32_e32 v140, v3, v160
	v_pk_mul_f32 v[150:151], v[142:143], v[162:163] op_sel_hi:[1,0]
	v_lshlrev_b64 v[142:143], 2, v[144:145]
	v_pk_mul_f32 v[158:159], v[140:141], v[162:163] op_sel_hi:[1,0]
	v_lshl_add_u64 v[140:141], s[46:47], 0, v[142:143]
	v_lshl_add_u64 v[142:143], s[48:49], 0, v[142:143]
	ds_read_b128 v[154:157], v244
	ds_read_b128 v[182:185], v244 offset:256
	s_waitcnt lgkmcnt(0)
	v_pk_fma_f32 v[154:155], v[154:155], v[158:159], v[182:183]
	s_nop 0
	v_pk_fma_f32 v[128:129], v[154:155], s[72:73], v[128:129] op_sel_hi:[1,0,1]
	s_waitcnt vmcnt(11)
	v_mov_b64_e32 v[154:155], v[200:201]
	global_load_dwordx2 v[200:201], v243, s[70:71] offset:32
	v_pk_fma_f32 v[150:151], v[156:157], v[150:151], v[184:185]
	s_waitcnt lgkmcnt(0)
	v_lshlrev_b32_e32 v3, 16, v154
	v_pk_fma_f32 v[130:131], v[150:151], s[72:73], v[130:131] op_sel_hi:[1,0,1]
	v_cvt_pk_bf16_f32 v150, v128, v129
	v_cvt_pk_bf16_f32 v151, v130, v131
	v_and_b32_e32 v129, 0xffff0000, v154
	v_lshlrev_b32_e32 v131, 16, v155
	v_and_b32_e32 v147, 0xffff0000, v155
	global_store_dwordx2 v[152:153], v[150:151], off
	v_sub_f32_e32 v155, v129, v160
	v_sub_f32_e32 v154, v3, v160
	v_sub_f32_e32 v157, v147, v160
	v_sub_f32_e32 v156, v131, v160
	v_pk_mul_f32 v[158:159], v[162:163], v[156:157] op_sel_hi:[0,1]
	v_pk_mul_f32 v[168:169], v[162:163], v[154:155] op_sel_hi:[0,1]
	ds_read_b128 v[154:157], v244 offset:64
	ds_read_b128 v[182:185], v244 offset:320
	v_and_b32_e32 v130, 0xffff0000, v150
	v_lshlrev_b32_e32 v128, 16, v151
	s_waitcnt lgkmcnt(0)
; __device__ __forceinline__ u32x2 pk4(f32x4 v) { u32x2 r; r.x = pk2(v.x, v.y); r.y = pk2(v.z, v.w); return r; }
;     __device__ __forceinline__ void operator()(const f32x4 (&acc)[2][2][4][2], const pg8::Unit& u, int wr, int wc, int fr, int fq) const {
;     ...
;                         const u32x2 raw = *(const u32x2*)(src + (size_t)row * DM + col);
;                         f32x4 x = (f32x4){bflo(raw.x), bfhi(raw.x), bflo(raw.y), bfhi(raw.y)};
;                         if (ln) x = (x - mu) * rs * *(const f32x4*)(g + col) + *(const f32x4*)(b + col);
;                         const u32x2 pz = pk4(x * ALPHA + acc[ai][bj][m][n]);
;                         *(u32x2*)(dst + (size_t)row * DM + col) = pz;
;                         const float z0 = bflo(pz.x), z1 = bfhi(pz.x), z2 = bflo(pz.y), z3 = bfhi(pz.y);
;                         s1 += (z0 + z1) + (z2 + z3); s2 += (z0 * z0 + z1 * z1) + (z2 * z2 + z3 * z3);
;                     }
;                 s1 += __shfl_xor(s1, 16); s2 += __shfl_xor(s2, 16); s1 += __shfl_xor(s1, 32); s2 += __shfl_xor(s2, 32);
;                 if (fq == 0) { float* p = stm_n + (size_t)row * 32 + (u.pn * 4 + wc) * 2; p[0] = s1; p[1] = s2; }
	v_pk_fma_f32 v[154:155], v[154:155], v[168:169], v[182:183]
	s_nop 0
	v_pk_fma_f32 v[124:125], v[154:155], s[72:73], v[124:125] op_sel_hi:[1,0,1]
	s_waitcnt vmcnt(11)
	v_mov_b64_e32 v[154:155], v[202:203]
	global_load_dwordx2 v[202:203], v243, s[70:71] offset:256
	v_pk_fma_f32 v[156:157], v[156:157], v[158:159], v[184:185]
	v_cvt_pk_bf16_f32 v158, v124, v125
	v_pk_fma_f32 v[126:127], v[156:157], s[72:73], v[126:127] op_sel_hi:[1,0,1]
	s_waitcnt lgkmcnt(0)
	v_lshlrev_b32_e32 v3, 16, v154
	v_cvt_pk_bf16_f32 v159, v126, v127
	v_lshlrev_b32_e32 v126, 16, v159
	v_and_b32_e32 v127, 0xffff0000, v159
	v_mul_f32_e32 v124, v126, v126
	v_pk_fma_f32 v[124:125], v[126:127], v[126:127], v[124:125] op_sel_hi:[1,1,0]
	v_lshlrev_b32_e32 v129, 16, v155
	v_and_b32_e32 v124, 0xffff0000, v154
	v_and_b32_e32 v131, 0xffff0000, v155
	global_store_dwordx2 v[152:153], v[158:159], off offset:32
	v_sub_f32_e32 v155, v124, v160
	v_sub_f32_e32 v154, v3, v160
	v_sub_f32_e32 v157, v131, v160
	v_sub_f32_e32 v156, v129, v160
	v_pk_mul_f32 v[168:169], v[162:163], v[156:157] op_sel_hi:[0,1]
	v_pk_mul_f32 v[186:187], v[162:163], v[154:155] op_sel_hi:[0,1]
	ds_read_b128 v[154:157], v244 offset:128
	ds_read_b128 v[182:185], v244 offset:384
	v_and_b32_e32 v159, 0xffff0000, v158
	s_waitcnt lgkmcnt(0)
	v_pk_fma_f32 v[154:155], v[154:155], v[186:187], v[182:183]
	v_pk_fma_f32 v[156:157], v[156:157], v[168:169], v[184:185]
	v_pk_fma_f32 v[120:121], v[154:155], s[72:73], v[120:121] op_sel_hi:[1,0,1]
	v_pk_fma_f32 v[122:123], v[156:157], s[72:73], v[122:123] op_sel_hi:[1,0,1]
	s_waitcnt vmcnt(11)
	v_mov_b64_e32 v[168:169], v[204:205]
	global_load_dwordx2 v[204:205], v243, s[70:71] offset:288
	v_cvt_pk_bf16_f32 v120, v120, v121
	v_cvt_pk_bf16_f32 v121, v122, v123
	global_store_dwordx2 v[152:153], v[120:121], off offset:256
	ds_read_b128 v[182:185], v244 offset:192
	ds_read_b128 v[186:189], v244 offset:448
	v_lshlrev_b32_e32 v154, 16, v120
	v_and_b32_e32 v156, 0xffff0000, v120
	v_lshlrev_b32_e32 v120, 16, v121
	v_and_b32_e32 v122, 0xffff0000, v121
	v_mul_f32_e32 v155, v154, v154
	v_mul_f32_e32 v157, v156, v156
	v_mul_f32_e32 v121, v120, v120
	v_mul_f32_e32 v123, v122, v122
	v_pk_add_f32 v[120:121], v[120:121], v[122:123]
	s_waitcnt lgkmcnt(0)
	v_lshlrev_b32_e32 v3, 16, v168
	v_and_b32_e32 v124, 0xffff0000, v168
	v_lshlrev_b32_e32 v129, 16, v169
	v_and_b32_e32 v131, 0xffff0000, v169
	v_sub_f32_e32 v169, v124, v160
	v_sub_f32_e32 v168, v3, v160
	v_sub_f32_e32 v161, v131, v160
	v_sub_f32_e32 v160, v129, v160
	v_pk_mul_f32 v[160:161], v[162:163], v[160:161] op_sel_hi:[0,1]
	v_pk_mul_f32 v[162:163], v[162:163], v[168:169] op_sel_hi:[0,1]
	s_waitcnt lgkmcnt(0)
	v_pk_fma_f32 v[162:163], v[182:183], v[162:163], v[186:187]
	v_mov_b32_e32 v129, v159
	v_pk_fma_f32 v[116:117], v[162:163], s[72:73], v[116:117] op_sel_hi:[1,0,1]
	v_lshlrev_b32_e32 v163, 16, v158
	v_lshlrev_b32_e32 v162, 16, v150
	v_mov_b32_e32 v131, v163
	v_pk_mul_f32 v[168:169], v[162:163], v[162:163]
	v_pk_mul_f32 v[182:183], v[130:131], v[130:131]
	v_and_b32_e32 v158, 0xffff0000, v151
	v_pk_fma_f32 v[160:161], v[184:185], v[160:161], v[188:189]
	v_pk_mul_f32 v[150:151], v[128:129], v[128:129]
	v_pk_mul_f32 v[184:185], v[158:159], v[158:159]
	v_pk_mov_b32 v[186:187], v[162:163], v[168:169] op_sel:[1,0]
	v_pk_mov_b32 v[182:183], v[158:159], v[182:183] op_sel:[1,0]
	v_pk_add_f32 v[130:131], v[162:163], v[130:131]
	v_pk_add_f32 v[128:129], v[158:159], v[128:129]
	v_pk_fma_f32 v[118:119], v[160:161], s[72:73], v[118:119] op_sel_hi:[1,0,1]
	v_pk_add_f32 v[182:183], v[186:187], v[182:183]
	v_mov_b32_e32 v186, v126
	v_mov_b32_e32 v187, v150
	v_pk_mov_b32 v[126:127], v[126:127], v[184:185] op_sel:[1,0]
	v_mov_b32_e32 v131, v169
	v_mov_b32_e32 v129, v185
	v_cvt_pk_bf16_f32 v116, v116, v117
	v_cvt_pk_bf16_f32 v117, v118, v119
	v_pk_add_f32 v[126:127], v[186:187], v[126:127]
	v_pk_add_f32 v[128:129], v[130:131], v[128:129]
	v_mov_b32_e32 v3, v125
	global_store_dwordx2 v[152:153], v[116:117], off offset:288
	v_lshlrev_b32_e32 v152, 16, v116
	v_and_b32_e32 v160, 0xffff0000, v116
	v_lshlrev_b32_e32 v116, 16, v117
	v_and_b32_e32 v118, 0xffff0000, v117
	v_pk_add_f32 v[126:127], v[182:183], v[126:127]
	v_pk_add_f32 v[124:125], v[128:129], v[2:3]
	v_mul_f32_e32 v153, v152, v152
	v_mul_f32_e32 v161, v160, v160
	v_mul_f32_e32 v117, v116, v116
	v_mul_f32_e32 v119, v118, v118
	v_pk_add_f32 v[124:125], v[126:127], v[124:125]
	v_pk_add_f32 v[126:127], v[154:155], v[156:157]
	v_pk_add_f32 v[122:123], v[152:153], v[160:161]
	v_pk_add_f32 v[120:121], v[126:127], v[120:121]
	v_pk_add_f32 v[116:117], v[116:117], v[118:119]
	v_pk_add_f32 v[120:121], v[124:125], v[120:121]
	v_pk_add_f32 v[116:117], v[122:123], v[116:117]
	s_nop 0
	v_pk_add_f32 v[116:117], v[120:121], v[116:117]
	ds_bpermute_b32 v118, v181, v116
	ds_bpermute_b32 v119, v181, v117
	s_waitcnt lgkmcnt(0)
	v_pk_add_f32 v[116:117], v[116:117], v[118:119]
	ds_bpermute_b32 v118, v180, v116
	ds_bpermute_b32 v119, v180, v117
	s_and_saveexec_b64 s[0:1], s[40:41]
	s_cbranch_execz .LBB0_2205
	v_lshl_add_u64 v[120:121], s[50:51], 0, v[148:149]
	v_lshl_add_u64 v[120:121], s[60:61], 2, v[120:121]
	s_waitcnt lgkmcnt(0)
	v_pk_add_f32 v[116:117], v[116:117], v[118:119]
	global_store_dwordx2 v[120:121], v[116:117], off
; __device__ __forceinline__ u32x2 pk4(f32x4 v) { u32x2 r; r.x = pk2(v.x, v.y); r.y = pk2(v.z, v.w); return r; }
;     __device__ __forceinline__ void operator()(const f32x4 (&acc)[2][2][4][2], const pg8::Unit& u, int wr, int wc, int fr, int fq) const {
;     ...
;                 const int row = u.pm * 256 + ai * 128 + wr * 64 + m * 16 + fr;
;                 float mu = 0.f, rs = 1.f; if (ln) stats_main(stm_p, row, fq, mu, rs);
;                 float s1 = 0.f, s2 = 0.f;
; #pragma unroll
;                 for (int bj = 0; bj < 2; ++bj)
; #pragma unroll
;                     for (int n = 0; n < 2; ++n) {
;                         const int col = u.pn * 256 + bj * 128 + wc * 32 + n * 16 + fq * 4;
;                         const u32x2 raw = *(const u32x2*)(src + (size_t)row * DM + col);
;                         f32x4 x = (f32x4){bflo(raw.x), bfhi(raw.x), bflo(raw.y), bfhi(raw.y)};
;                         if (ln) x = (x - mu) * rs * *(const f32x4*)(g + col) + *(const f32x4*)(b + col);
;                         const u32x2 pz = pk4(x * ALPHA + acc[ai][bj][m][n]);
;                         *(u32x2*)(dst + (size_t)row * DM + col) = pz;
;                         const float z0 = bflo(pz.x), z1 = bfhi(pz.x), z2 = bflo(pz.y), z3 = bfhi(pz.y);
;                         s1 += (z0 + z1) + (z2 + z3); s2 += (z0 * z0 + z1 * z1) + (z2 * z2 + z3 * z3);
;                     }
.LBB0_2205:
	s_or_b64 exec, exec, s[0:1]
	v_or_b32_e32 v126, 16, v146
	v_ashrrev_i32_e32 v127, 31, v126
	v_lshlrev_b64 v[116:117], 7, v[126:127]
	v_lshl_add_u64 v[122:123], v[134:135], 0, v[116:117]
	s_waitcnt lgkmcnt(0)
	s_waitcnt vmcnt(11)
	v_mov_b64_e32 v[118:119], v[206:207]
	v_mov_b64_e32 v[120:121], v[208:209]
	global_load_dwordx4 v[206:209], v[246:247], off offset:2064
	s_nop 0
	s_waitcnt vmcnt(11)
	v_mov_b64_e32 v[122:123], v[214:215]
	v_mov_b64_e32 v[124:125], v[216:217]
	global_load_dwordx4 v[214:217], v[246:247], off offset:2048
	s_waitcnt lgkmcnt(0)
	v_pk_add_f32 v[118:119], v[118:119], v[120:121]
	s_waitcnt lgkmcnt(0)
	v_pk_add_f32 v[122:123], v[122:123], v[124:125]
	s_nop 0
	v_pk_add_f32 v[118:119], v[122:123], v[118:119]
	ds_bpermute_b32 v120, v181, v118
	ds_bpermute_b32 v121, v181, v119
	s_waitcnt lgkmcnt(0)
	v_pk_add_f32 v[118:119], v[118:119], v[120:121]
	ds_bpermute_b32 v120, v180, v118
	ds_bpermute_b32 v121, v180, v119
	s_waitcnt lgkmcnt(0)
	v_pk_add_f32 v[118:119], v[118:119], v[120:121]
	s_nop 0
	v_pk_mul_f32 v[128:129], v[118:119], s[82:83] op_sel_hi:[1,0]
	v_lshlrev_b64 v[118:119], 11, v[126:127]
	v_lshl_add_u64 v[118:119], s[70:71], 0, v[118:119]
	v_lshl_add_u64 v[124:125], v[144:145], 1, v[118:119]
	v_add_u32_e32 v243, 0x18000, v242
	s_waitcnt vmcnt(11)
	v_mov_b64_e32 v[118:119], v[234:235]
	global_load_dwordx2 v[234:235], v243, s[70:71]
	v_fma_f32 v3, -v128, v128, v129
	v_max_f32_e32 v3, 0, v3
	v_add_f32_e32 v3, 0x3727c5ac, v3
	v_rsq_f32_e32 v130, v3
	s_waitcnt lgkmcnt(0)
	v_lshlrev_b32_e32 v3, 16, v118
	v_and_b32_e32 v118, 0xffff0000, v118
	v_lshlrev_b32_e32 v120, 16, v119
	v_and_b32_e32 v121, 0xffff0000, v119
	v_sub_f32_e32 v119, v118, v128
	v_sub_f32_e32 v118, v3, v128
	v_sub_f32_e32 v121, v121, v128
	v_sub_f32_e32 v120, v120, v128
	v_pk_mul_f32 v[122:123], v[120:121], v[130:131] op_sel_hi:[1,0]
	v_pk_mul_f32 v[126:127], v[118:119], v[130:131] op_sel_hi:[1,0]
	ds_read_b128 v[118:121], v244
	ds_read_b128 v[148:151], v244 offset:256
	s_waitcnt lgkmcnt(0)
	v_pk_fma_f32 v[120:121], v[120:121], v[122:123], v[150:151]
	s_nop 0
	v_pk_fma_f32 v[114:115], v[120:121], s[72:73], v[114:115] op_sel_hi:[1,0,1]
	s_waitcnt vmcnt(11)
	v_mov_b64_e32 v[120:121], v[236:237]
	global_load_dwordx2 v[236:237], v243, s[70:71] offset:32
	v_pk_fma_f32 v[118:119], v[118:119], v[126:127], v[148:149]
	s_waitcnt lgkmcnt(0)
	v_lshlrev_b32_e32 v3, 16, v120
	v_pk_fma_f32 v[112:113], v[118:119], s[72:73], v[112:113] op_sel_hi:[1,0,1]
	v_cvt_pk_bf16_f32 v119, v114, v115
	v_cvt_pk_bf16_f32 v118, v112, v113
	v_and_b32_e32 v113, 0xffff0000, v120
	v_lshlrev_b32_e32 v115, 16, v121
	v_and_b32_e32 v122, 0xffff0000, v121
	global_store_dwordx2 v[124:125], v[118:119], off
	v_sub_f32_e32 v121, v113, v128
	v_sub_f32_e32 v120, v3, v128
	v_sub_f32_e32 v123, v122, v128
	v_sub_f32_e32 v122, v115, v128
	v_pk_mul_f32 v[126:127], v[130:131], v[122:123] op_sel_hi:[0,1]
	v_pk_mul_f32 v[152:153], v[130:131], v[120:121] op_sel_hi:[0,1]
	ds_read_b128 v[120:123], v244 offset:64
	ds_read_b128 v[148:151], v244 offset:320
	v_and_b32_e32 v114, 0xffff0000, v118
	v_lshlrev_b32_e32 v112, 16, v119
	s_waitcnt lgkmcnt(0)
	v_pk_fma_f32 v[120:121], v[120:121], v[152:153], v[148:149]
	s_nop 0
	v_pk_fma_f32 v[108:109], v[120:121], s[72:73], v[108:109] op_sel_hi:[1,0,1]
	s_waitcnt vmcnt(11)
	v_mov_b64_e32 v[120:121], v[238:239]
	global_load_dwordx2 v[238:239], v243, s[70:71] offset:256
	v_pk_fma_f32 v[122:123], v[122:123], v[126:127], v[150:151]
	v_cvt_pk_bf16_f32 v126, v108, v109
	v_pk_fma_f32 v[110:111], v[122:123], s[72:73], v[110:111] op_sel_hi:[1,0,1]
	s_waitcnt lgkmcnt(0)
	v_lshlrev_b32_e32 v3, 16, v120
	v_cvt_pk_bf16_f32 v127, v110, v111
	v_lshlrev_b32_e32 v110, 16, v127
	v_and_b32_e32 v111, 0xffff0000, v127
	v_mul_f32_e32 v108, v110, v110
	v_pk_fma_f32 v[108:109], v[110:111], v[110:111], v[108:109] op_sel_hi:[1,1,0]
	v_lshlrev_b32_e32 v113, 16, v121
	v_and_b32_e32 v108, 0xffff0000, v120
	v_and_b32_e32 v115, 0xffff0000, v121
	global_store_dwordx2 v[124:125], v[126:127], off offset:32
	v_sub_f32_e32 v121, v108, v128
	v_sub_f32_e32 v120, v3, v128
	v_sub_f32_e32 v123, v115, v128
	v_sub_f32_e32 v122, v113, v128
	v_pk_mul_f32 v[152:153], v[130:131], v[122:123] op_sel_hi:[0,1]
	v_pk_mul_f32 v[154:155], v[130:131], v[120:121] op_sel_hi:[0,1]
	ds_read_b128 v[120:123], v244 offset:128
	ds_read_b128 v[148:151], v244 offset:384
	v_and_b32_e32 v127, 0xffff0000, v126
	s_waitcnt lgkmcnt(0)
	v_pk_fma_f32 v[120:121], v[120:121], v[154:155], v[148:149]
	s_waitcnt vmcnt(11)
	v_mov_b64_e32 v[148:149], v[240:241]
	global_load_dwordx2 v[240:241], v243, s[70:71] offset:288
	v_pk_fma_f32 v[122:123], v[122:123], v[152:153], v[150:151]
	v_pk_fma_f32 v[104:105], v[120:121], s[72:73], v[104:105] op_sel_hi:[1,0,1]
	v_pk_fma_f32 v[106:107], v[122:123], s[72:73], v[106:107] op_sel_hi:[1,0,1]
	v_cvt_pk_bf16_f32 v104, v104, v105
	v_cvt_pk_bf16_f32 v105, v106, v107
	global_store_dwordx2 v[124:125], v[104:105], off offset:256
	v_lshlrev_b32_e32 v120, 16, v104
	v_and_b32_e32 v122, 0xffff0000, v104
	v_lshlrev_b32_e32 v104, 16, v105
	v_and_b32_e32 v106, 0xffff0000, v105
	v_mul_f32_e32 v121, v120, v120
	v_mul_f32_e32 v123, v122, v122
	v_mul_f32_e32 v105, v104, v104
	v_mul_f32_e32 v107, v106, v106
	v_pk_add_f32 v[104:105], v[104:105], v[106:107]
	s_waitcnt lgkmcnt(0)
	v_lshlrev_b32_e32 v3, 16, v148
	v_and_b32_e32 v108, 0xffff0000, v148
	v_lshlrev_b32_e32 v113, 16, v149
	v_and_b32_e32 v115, 0xffff0000, v149
	v_sub_f32_e32 v149, v108, v128
	v_sub_f32_e32 v148, v3, v128
	v_sub_f32_e32 v129, v115, v128
	v_sub_f32_e32 v128, v113, v128
	v_pk_mul_f32 v[128:129], v[130:131], v[128:129] op_sel_hi:[0,1]
	v_pk_mul_f32 v[130:131], v[130:131], v[148:149] op_sel_hi:[0,1]
	ds_read_b128 v[148:151], v244 offset:192
	ds_read_b128 v[152:155], v244 offset:448
	v_mov_b32_e32 v113, v127
	v_mov_b32_e32 v3, v109
	s_waitcnt lgkmcnt(0)
; __device__ __forceinline__ u32x2 pk4(f32x4 v) { u32x2 r; r.x = pk2(v.x, v.y); r.y = pk2(v.z, v.w); return r; }
;     __device__ __forceinline__ void operator()(const f32x4 (&acc)[2][2][4][2], const pg8::Unit& u, int wr, int wc, int fr, int fq) const {
;     ...
;                 const int row = u.pm * 256 + ai * 128 + wr * 64 + m * 16 + fr;
;                 float mu = 0.f, rs = 1.f; if (ln) stats_main(stm_p, row, fq, mu, rs);
;                 float s1 = 0.f, s2 = 0.f;
; #pragma unroll
;                 for (int bj = 0; bj < 2; ++bj)
; #pragma unroll
;                     for (int n = 0; n < 2; ++n) {
;                         const int col = u.pn * 256 + bj * 128 + wc * 32 + n * 16 + fq * 4;
;                         const u32x2 raw = *(const u32x2*)(src + (size_t)row * DM + col);
;                         f32x4 x = (f32x4){bflo(raw.x), bfhi(raw.x), bflo(raw.y), bfhi(raw.y)};
;                         if (ln) x = (x - mu) * rs * *(const f32x4*)(g + col) + *(const f32x4*)(b + col);
;                         const u32x2 pz = pk4(x * ALPHA + acc[ai][bj][m][n]);
;                         *(u32x2*)(dst + (size_t)row * DM + col) = pz;
;                         const float z0 = bflo(pz.x), z1 = bfhi(pz.x), z2 = bflo(pz.y), z3 = bfhi(pz.y);
;                         s1 += (z0 + z1) + (z2 + z3); s2 += (z0 * z0 + z1 * z1) + (z2 * z2 + z3 * z3);
;                     }
;                 s1 += __shfl_xor(s1, 16); s2 += __shfl_xor(s2, 16); s1 += __shfl_xor(s1, 32); s2 += __shfl_xor(s2, 32);
;                 if (fq == 0) { float* p = stm_n + (size_t)row * 32 + (u.pn * 4 + wc) * 2; p[0] = s1; p[1] = s2; }
	v_pk_fma_f32 v[130:131], v[148:149], v[130:131], v[152:153]
	s_nop 0
	v_pk_fma_f32 v[100:101], v[130:131], s[72:73], v[100:101] op_sel_hi:[1,0,1]
	v_lshlrev_b32_e32 v131, 16, v126
	v_lshlrev_b32_e32 v130, 16, v118
	v_mov_b32_e32 v115, v131
	v_pk_fma_f32 v[128:129], v[150:151], v[128:129], v[154:155]
	v_pk_mul_f32 v[148:149], v[130:131], v[130:131]
	v_pk_mul_f32 v[150:151], v[114:115], v[114:115]
	v_and_b32_e32 v126, 0xffff0000, v119
	v_pk_mul_f32 v[118:119], v[112:113], v[112:113]
	v_pk_mul_f32 v[152:153], v[126:127], v[126:127]
	v_pk_mov_b32 v[154:155], v[130:131], v[148:149] op_sel:[1,0]
	v_pk_mov_b32 v[150:151], v[126:127], v[150:151] op_sel:[1,0]
	v_pk_add_f32 v[114:115], v[130:131], v[114:115]
	v_pk_add_f32 v[112:113], v[126:127], v[112:113]
	v_pk_fma_f32 v[102:103], v[128:129], s[72:73], v[102:103] op_sel_hi:[1,0,1]
	v_pk_add_f32 v[150:151], v[154:155], v[150:151]
	v_mov_b32_e32 v154, v110
	v_mov_b32_e32 v155, v118
	v_pk_mov_b32 v[110:111], v[110:111], v[152:153] op_sel:[1,0]
	v_mov_b32_e32 v115, v149
	v_mov_b32_e32 v113, v153
	v_cvt_pk_bf16_f32 v100, v100, v101
	v_cvt_pk_bf16_f32 v101, v102, v103
	v_pk_add_f32 v[110:111], v[154:155], v[110:111]
	v_pk_add_f32 v[112:113], v[114:115], v[112:113]
	global_store_dwordx2 v[124:125], v[100:101], off offset:288
	v_lshlrev_b32_e32 v124, 16, v100
	v_and_b32_e32 v128, 0xffff0000, v100
	v_lshlrev_b32_e32 v100, 16, v101
	v_and_b32_e32 v102, 0xffff0000, v101
	v_pk_add_f32 v[110:111], v[150:151], v[110:111]
	v_pk_add_f32 v[108:109], v[112:113], v[2:3]
	v_mul_f32_e32 v125, v124, v124
	v_mul_f32_e32 v129, v128, v128
	v_mul_f32_e32 v101, v100, v100
	v_mul_f32_e32 v103, v102, v102
	v_pk_add_f32 v[108:109], v[110:111], v[108:109]
	v_pk_add_f32 v[110:111], v[120:121], v[122:123]
	v_pk_add_f32 v[106:107], v[124:125], v[128:129]
	v_pk_add_f32 v[104:105], v[110:111], v[104:105]
	v_pk_add_f32 v[100:101], v[100:101], v[102:103]
	v_pk_add_f32 v[104:105], v[108:109], v[104:105]
	v_pk_add_f32 v[100:101], v[106:107], v[100:101]
	s_nop 0
	v_pk_add_f32 v[100:101], v[104:105], v[100:101]
	ds_bpermute_b32 v102, v181, v100
	ds_bpermute_b32 v103, v181, v101
	s_waitcnt lgkmcnt(0)
	v_pk_add_f32 v[100:101], v[100:101], v[102:103]
	ds_bpermute_b32 v102, v180, v100
	ds_bpermute_b32 v103, v180, v101
	s_and_saveexec_b64 s[0:1], s[40:41]
	s_cbranch_execz .LBB0_2207
	v_lshl_add_u64 v[104:105], s[50:51], 0, v[116:117]
	v_lshl_add_u64 v[104:105], s[60:61], 2, v[104:105]
	s_waitcnt lgkmcnt(0)
	v_pk_add_f32 v[100:101], v[100:101], v[102:103]
	global_store_dwordx2 v[104:105], v[100:101], off
.LBB0_2207:
	s_or_b64 exec, exec, s[0:1]
	v_or_b32_e32 v110, 32, v146
	v_ashrrev_i32_e32 v111, 31, v110
	v_lshlrev_b64 v[100:101], 7, v[110:111]
	v_lshl_add_u64 v[106:107], v[134:135], 0, v[100:101]
	s_waitcnt lgkmcnt(0)
	s_waitcnt vmcnt(11)
	v_mov_b64_e32 v[102:103], v[190:191]
	v_mov_b64_e32 v[104:105], v[192:193]
	global_load_dwordx4 v[190:193], v[248:249], off offset:-4080
	s_nop 0
	s_waitcnt vmcnt(11)
	v_mov_b64_e32 v[106:107], v[194:195]
	v_mov_b64_e32 v[108:109], v[196:197]
	global_load_dwordx4 v[194:197], v[248:249], off offset:-4096
	s_waitcnt lgkmcnt(0)
	v_pk_add_f32 v[102:103], v[102:103], v[104:105]
	s_waitcnt lgkmcnt(0)
	v_pk_add_f32 v[106:107], v[106:107], v[108:109]
	s_nop 0
	v_pk_add_f32 v[102:103], v[106:107], v[102:103]
	ds_bpermute_b32 v104, v181, v102
	ds_bpermute_b32 v105, v181, v103
	s_waitcnt lgkmcnt(0)
	v_pk_add_f32 v[102:103], v[102:103], v[104:105]
	ds_bpermute_b32 v104, v180, v102
	ds_bpermute_b32 v105, v180, v103
	s_waitcnt lgkmcnt(0)
	v_pk_add_f32 v[102:103], v[102:103], v[104:105]
	s_nop 0
	v_pk_mul_f32 v[112:113], v[102:103], s[82:83] op_sel_hi:[1,0]
	v_lshlrev_b64 v[102:103], 11, v[110:111]
	v_lshl_add_u64 v[102:103], s[70:71], 0, v[102:103]
	v_lshl_add_u64 v[108:109], v[144:145], 1, v[102:103]
	v_add_u32_e32 v243, 0x40000, v242
	s_waitcnt vmcnt(11)
	v_mov_b64_e32 v[102:103], v[198:199]
	global_load_dwordx2 v[198:199], v243, s[70:71]
	v_fma_f32 v3, -v112, v112, v113
	v_max_f32_e32 v3, 0, v3
	v_add_f32_e32 v3, 0x3727c5ac, v3
	v_rsq_f32_e32 v114, v3
	s_waitcnt lgkmcnt(0)
	v_lshlrev_b32_e32 v3, 16, v102
	v_and_b32_e32 v102, 0xffff0000, v102
	v_lshlrev_b32_e32 v104, 16, v103
	v_and_b32_e32 v105, 0xffff0000, v103
	v_sub_f32_e32 v103, v102, v112
	v_sub_f32_e32 v102, v3, v112
	v_sub_f32_e32 v105, v105, v112
	v_sub_f32_e32 v104, v104, v112
	v_pk_mul_f32 v[106:107], v[104:105], v[114:115] op_sel_hi:[1,0]
	v_pk_mul_f32 v[110:111], v[102:103], v[114:115] op_sel_hi:[1,0]
	ds_read_b128 v[102:105], v244
	ds_read_b128 v[116:119], v244 offset:256
	s_waitcnt lgkmcnt(0)
	v_pk_fma_f32 v[104:105], v[104:105], v[106:107], v[118:119]
	s_nop 0
	v_pk_fma_f32 v[98:99], v[104:105], s[72:73], v[98:99] op_sel_hi:[1,0,1]
	s_waitcnt vmcnt(11)
	v_mov_b64_e32 v[104:105], v[200:201]
	global_load_dwordx2 v[200:201], v243, s[70:71] offset:32
	v_pk_fma_f32 v[102:103], v[102:103], v[110:111], v[116:117]
	s_waitcnt lgkmcnt(0)
	v_lshlrev_b32_e32 v3, 16, v104
	v_pk_fma_f32 v[96:97], v[102:103], s[72:73], v[96:97] op_sel_hi:[1,0,1]
	v_cvt_pk_bf16_f32 v103, v98, v99
	v_cvt_pk_bf16_f32 v102, v96, v97
	v_and_b32_e32 v97, 0xffff0000, v104
	v_lshlrev_b32_e32 v99, 16, v105
	v_and_b32_e32 v106, 0xffff0000, v105
	global_store_dwordx2 v[108:109], v[102:103], off
	v_sub_f32_e32 v105, v97, v112
	v_sub_f32_e32 v104, v3, v112
	v_sub_f32_e32 v107, v106, v112
	v_sub_f32_e32 v106, v99, v112
	v_pk_mul_f32 v[110:111], v[114:115], v[106:107] op_sel_hi:[0,1]
	v_pk_mul_f32 v[120:121], v[114:115], v[104:105] op_sel_hi:[0,1]
	ds_read_b128 v[104:107], v244 offset:64
	ds_read_b128 v[116:119], v244 offset:320
	v_and_b32_e32 v98, 0xffff0000, v102
	v_lshlrev_b32_e32 v96, 16, v103
	s_waitcnt lgkmcnt(0)
; __device__ __forceinline__ u32x2 pk4(f32x4 v) { u32x2 r; r.x = pk2(v.x, v.y); r.y = pk2(v.z, v.w); return r; }
;     __device__ __forceinline__ void operator()(const f32x4 (&acc)[2][2][4][2], const pg8::Unit& u, int wr, int wc, int fr, int fq) const {
;     ...
;                 for (int bj = 0; bj < 2; ++bj)
; #pragma unroll
;                     for (int n = 0; n < 2; ++n) {
;                         const int col = u.pn * 256 + bj * 128 + wc * 32 + n * 16 + fq * 4;
;                         const u32x2 raw = *(const u32x2*)(src + (size_t)row * DM + col);
;                         f32x4 x = (f32x4){bflo(raw.x), bfhi(raw.x), bflo(raw.y), bfhi(raw.y)};
;                         if (ln) x = (x - mu) * rs * *(const f32x4*)(g + col) + *(const f32x4*)(b + col);
;                         const u32x2 pz = pk4(x * ALPHA + acc[ai][bj][m][n]);
;                         *(u32x2*)(dst + (size_t)row * DM + col) = pz;
;                         const float z0 = bflo(pz.x), z1 = bfhi(pz.x), z2 = bflo(pz.y), z3 = bfhi(pz.y);
;                         s1 += (z0 + z1) + (z2 + z3); s2 += (z0 * z0 + z1 * z1) + (z2 * z2 + z3 * z3);
;                     }
;                 s1 += __shfl_xor(s1, 16); s2 += __shfl_xor(s2, 16); s1 += __shfl_xor(s1, 32); s2 += __shfl_xor(s2, 32);
;                 if (fq == 0) { float* p = stm_n + (size_t)row * 32 + (u.pn * 4 + wc) * 2; p[0] = s1; p[1] = s2; }
	v_pk_fma_f32 v[104:105], v[104:105], v[120:121], v[116:117]
	s_nop 0
	v_pk_fma_f32 v[92:93], v[104:105], s[72:73], v[92:93] op_sel_hi:[1,0,1]
	s_waitcnt vmcnt(11)
	v_mov_b64_e32 v[104:105], v[202:203]
	global_load_dwordx2 v[202:203], v243, s[70:71] offset:256
	v_pk_fma_f32 v[106:107], v[106:107], v[110:111], v[118:119]
	v_cvt_pk_bf16_f32 v110, v92, v93
	v_pk_fma_f32 v[94:95], v[106:107], s[72:73], v[94:95] op_sel_hi:[1,0,1]
	s_waitcnt lgkmcnt(0)
	v_lshlrev_b32_e32 v3, 16, v104
	v_cvt_pk_bf16_f32 v111, v94, v95
	v_lshlrev_b32_e32 v94, 16, v111
	v_and_b32_e32 v95, 0xffff0000, v111
	v_mul_f32_e32 v92, v94, v94
	v_pk_fma_f32 v[92:93], v[94:95], v[94:95], v[92:93] op_sel_hi:[1,1,0]
	v_lshlrev_b32_e32 v97, 16, v105
	v_and_b32_e32 v92, 0xffff0000, v104
	v_and_b32_e32 v99, 0xffff0000, v105
	global_store_dwordx2 v[108:109], v[110:111], off offset:32
	v_sub_f32_e32 v105, v92, v112
	v_sub_f32_e32 v104, v3, v112
	v_sub_f32_e32 v107, v99, v112
	v_sub_f32_e32 v106, v97, v112
	v_pk_mul_f32 v[120:121], v[114:115], v[106:107] op_sel_hi:[0,1]
	v_pk_mul_f32 v[122:123], v[114:115], v[104:105] op_sel_hi:[0,1]
	ds_read_b128 v[104:107], v244 offset:128
	ds_read_b128 v[116:119], v244 offset:384
	v_and_b32_e32 v111, 0xffff0000, v110
	s_waitcnt lgkmcnt(0)
	v_pk_fma_f32 v[104:105], v[104:105], v[122:123], v[116:117]
	s_waitcnt vmcnt(11)
	v_mov_b64_e32 v[116:117], v[204:205]
	global_load_dwordx2 v[204:205], v243, s[70:71] offset:288
	v_pk_fma_f32 v[106:107], v[106:107], v[120:121], v[118:119]
	v_pk_fma_f32 v[88:89], v[104:105], s[72:73], v[88:89] op_sel_hi:[1,0,1]
	v_pk_fma_f32 v[90:91], v[106:107], s[72:73], v[90:91] op_sel_hi:[1,0,1]
	v_cvt_pk_bf16_f32 v88, v88, v89
	v_cvt_pk_bf16_f32 v89, v90, v91
	global_store_dwordx2 v[108:109], v[88:89], off offset:256
	v_lshlrev_b32_e32 v104, 16, v88
	v_and_b32_e32 v106, 0xffff0000, v88
	v_lshlrev_b32_e32 v88, 16, v89
	v_and_b32_e32 v90, 0xffff0000, v89
	v_mul_f32_e32 v105, v104, v104
	v_mul_f32_e32 v107, v106, v106
	v_mul_f32_e32 v89, v88, v88
	v_mul_f32_e32 v91, v90, v90
	v_pk_add_f32 v[88:89], v[88:89], v[90:91]
	s_waitcnt lgkmcnt(0)
	v_lshlrev_b32_e32 v3, 16, v116
	v_and_b32_e32 v92, 0xffff0000, v116
	v_lshlrev_b32_e32 v97, 16, v117
	v_and_b32_e32 v99, 0xffff0000, v117
	v_sub_f32_e32 v117, v92, v112
	v_sub_f32_e32 v116, v3, v112
	v_sub_f32_e32 v113, v99, v112
	v_sub_f32_e32 v112, v97, v112
	v_pk_mul_f32 v[112:113], v[114:115], v[112:113] op_sel_hi:[0,1]
	v_pk_mul_f32 v[114:115], v[114:115], v[116:117] op_sel_hi:[0,1]
	ds_read_b128 v[116:119], v244 offset:192
	ds_read_b128 v[120:123], v244 offset:448
	v_mov_b32_e32 v97, v111
	v_mov_b32_e32 v3, v93
	s_waitcnt lgkmcnt(0)
	v_pk_fma_f32 v[114:115], v[116:117], v[114:115], v[120:121]
	s_nop 0
	v_pk_fma_f32 v[84:85], v[114:115], s[72:73], v[84:85] op_sel_hi:[1,0,1]
	v_lshlrev_b32_e32 v115, 16, v110
	v_lshlrev_b32_e32 v114, 16, v102
	v_mov_b32_e32 v99, v115
	v_pk_fma_f32 v[112:113], v[118:119], v[112:113], v[122:123]
	v_pk_mul_f32 v[116:117], v[114:115], v[114:115]
	v_pk_mul_f32 v[118:119], v[98:99], v[98:99]
	v_and_b32_e32 v110, 0xffff0000, v103
	v_pk_mul_f32 v[102:103], v[96:97], v[96:97]
	v_pk_mul_f32 v[120:121], v[110:111], v[110:111]
	v_pk_mov_b32 v[122:123], v[114:115], v[116:117] op_sel:[1,0]
	v_pk_mov_b32 v[118:119], v[110:111], v[118:119] op_sel:[1,0]
	v_pk_add_f32 v[98:99], v[114:115], v[98:99]
	v_pk_add_f32 v[96:97], v[110:111], v[96:97]
	v_pk_fma_f32 v[86:87], v[112:113], s[72:73], v[86:87] op_sel_hi:[1,0,1]
	v_pk_add_f32 v[118:119], v[122:123], v[118:119]
	v_mov_b32_e32 v122, v94
	v_mov_b32_e32 v123, v102
	v_pk_mov_b32 v[94:95], v[94:95], v[120:121] op_sel:[1,0]
	v_mov_b32_e32 v99, v117
	v_mov_b32_e32 v97, v121
	v_cvt_pk_bf16_f32 v84, v84, v85
	v_cvt_pk_bf16_f32 v85, v86, v87
	v_pk_add_f32 v[94:95], v[122:123], v[94:95]
	v_pk_add_f32 v[96:97], v[98:99], v[96:97]
	global_store_dwordx2 v[108:109], v[84:85], off offset:288
	v_lshlrev_b32_e32 v108, 16, v84
	v_and_b32_e32 v112, 0xffff0000, v84
	v_lshlrev_b32_e32 v84, 16, v85
	v_and_b32_e32 v86, 0xffff0000, v85
	v_pk_add_f32 v[94:95], v[118:119], v[94:95]
	v_pk_add_f32 v[92:93], v[96:97], v[2:3]
	v_mul_f32_e32 v109, v108, v108
	v_mul_f32_e32 v113, v112, v112
	v_mul_f32_e32 v85, v84, v84
	v_mul_f32_e32 v87, v86, v86
	v_pk_add_f32 v[92:93], v[94:95], v[92:93]
	v_pk_add_f32 v[94:95], v[104:105], v[106:107]
	v_pk_add_f32 v[90:91], v[108:109], v[112:113]
	v_pk_add_f32 v[88:89], v[94:95], v[88:89]
	v_pk_add_f32 v[84:85], v[84:85], v[86:87]
	v_pk_add_f32 v[88:89], v[92:93], v[88:89]
	v_pk_add_f32 v[84:85], v[90:91], v[84:85]
	s_nop 0
	v_pk_add_f32 v[84:85], v[88:89], v[84:85]
	ds_bpermute_b32 v86, v181, v84
	ds_bpermute_b32 v87, v181, v85
	s_waitcnt lgkmcnt(0)
	v_pk_add_f32 v[84:85], v[84:85], v[86:87]
	ds_bpermute_b32 v86, v180, v84
	ds_bpermute_b32 v87, v180, v85
	s_and_saveexec_b64 s[0:1], s[40:41]
	v_readlane_b32 s24, v251, 0
	v_readlane_b32 s25, v251, 1
	v_readlane_b32 s26, v251, 2
	v_readlane_b32 s27, v251, 3
	s_mov_b32 s76, 0x30000
	s_cbranch_execz .LBB0_2209
	v_lshl_add_u64 v[88:89], s[50:51], 0, v[100:101]
	v_lshl_add_u64 v[88:89], s[60:61], 2, v[88:89]
	s_waitcnt lgkmcnt(0)
	v_pk_add_f32 v[84:85], v[84:85], v[86:87]
	global_store_dwordx2 v[88:89], v[84:85], off
; __device__ __forceinline__ u32x2 pk4(f32x4 v) { u32x2 r; r.x = pk2(v.x, v.y); r.y = pk2(v.z, v.w); return r; }
;     __device__ __forceinline__ void operator()(const f32x4 (&acc)[2][2][4][2], const pg8::Unit& u, int wr, int wc, int fr, int fq) const {
;     ...
;                 const int row = u.pm * 256 + ai * 128 + wr * 64 + m * 16 + fr;
;                 float mu = 0.f, rs = 1.f; if (ln) stats_main(stm_p, row, fq, mu, rs);
;                 float s1 = 0.f, s2 = 0.f;
; #pragma unroll
;                 for (int bj = 0; bj < 2; ++bj)
; #pragma unroll
;                     for (int n = 0; n < 2; ++n) {
;                         const int col = u.pn * 256 + bj * 128 + wc * 32 + n * 16 + fq * 4;
;                         const u32x2 raw = *(const u32x2*)(src + (size_t)row * DM + col);
;                         f32x4 x = (f32x4){bflo(raw.x), bfhi(raw.x), bflo(raw.y), bfhi(raw.y)};
;                         if (ln) x = (x - mu) * rs * *(const f32x4*)(g + col) + *(const f32x4*)(b + col);
;                         const u32x2 pz = pk4(x * ALPHA + acc[ai][bj][m][n]);
;                         *(u32x2*)(dst + (size_t)row * DM + col) = pz;
;                         const float z0 = bflo(pz.x), z1 = bfhi(pz.x), z2 = bflo(pz.y), z3 = bfhi(pz.y);
;                         s1 += (z0 + z1) + (z2 + z3); s2 += (z0 * z0 + z1 * z1) + (z2 * z2 + z3 * z3);
;                     }
.LBB0_2209:
	s_or_b64 exec, exec, s[0:1]
	v_or_b32_e32 v94, 48, v146
	v_ashrrev_i32_e32 v95, 31, v94
	v_lshlrev_b64 v[84:85], 7, v[94:95]
	v_lshl_add_u64 v[90:91], v[134:135], 0, v[84:85]
	s_waitcnt lgkmcnt(0)
	s_waitcnt vmcnt(11)
	v_mov_b64_e32 v[86:87], v[206:207]
	v_mov_b64_e32 v[88:89], v[208:209]
	global_load_dwordx4 v[206:209], v[248:249], off offset:-2032
	s_nop 0
	s_waitcnt vmcnt(11)
	v_mov_b64_e32 v[90:91], v[214:215]
	v_mov_b64_e32 v[92:93], v[216:217]
	global_load_dwordx4 v[214:217], v[248:249], off offset:-2048
	s_waitcnt lgkmcnt(0)
	v_pk_add_f32 v[86:87], v[86:87], v[88:89]
	s_waitcnt lgkmcnt(0)
	v_pk_add_f32 v[90:91], v[90:91], v[92:93]
	s_nop 0
	v_pk_add_f32 v[86:87], v[90:91], v[86:87]
	ds_bpermute_b32 v88, v181, v86
	ds_bpermute_b32 v89, v181, v87
	s_waitcnt lgkmcnt(0)
	v_pk_add_f32 v[86:87], v[86:87], v[88:89]
	ds_bpermute_b32 v88, v180, v86
	ds_bpermute_b32 v89, v180, v87
	s_waitcnt lgkmcnt(0)
	v_pk_add_f32 v[86:87], v[86:87], v[88:89]
	s_nop 0
	v_pk_mul_f32 v[96:97], v[86:87], s[82:83] op_sel_hi:[1,0]
	v_lshlrev_b64 v[86:87], 11, v[94:95]
	v_lshl_add_u64 v[86:87], s[70:71], 0, v[86:87]
	v_lshl_add_u64 v[92:93], v[144:145], 1, v[86:87]
	v_add_u32_e32 v243, 0x48000, v242
	s_waitcnt vmcnt(11)
	v_mov_b64_e32 v[86:87], v[234:235]
	global_load_dwordx2 v[234:235], v243, s[70:71]
	v_fma_f32 v3, -v96, v96, v97
	v_max_f32_e32 v3, 0, v3
	v_add_f32_e32 v3, 0x3727c5ac, v3
	v_rsq_f32_e32 v98, v3
	s_waitcnt lgkmcnt(0)
	v_lshlrev_b32_e32 v3, 16, v86
	v_and_b32_e32 v86, 0xffff0000, v86
	v_lshlrev_b32_e32 v88, 16, v87
	v_and_b32_e32 v89, 0xffff0000, v87
	v_sub_f32_e32 v87, v86, v96
	v_sub_f32_e32 v86, v3, v96
	v_sub_f32_e32 v89, v89, v96
	v_sub_f32_e32 v88, v88, v96
	v_pk_mul_f32 v[90:91], v[88:89], v[98:99] op_sel_hi:[1,0]
	v_pk_mul_f32 v[94:95], v[86:87], v[98:99] op_sel_hi:[1,0]
	ds_read_b128 v[86:89], v244
	ds_read_b128 v[100:103], v244 offset:256
	s_waitcnt lgkmcnt(0)
	v_pk_fma_f32 v[88:89], v[88:89], v[90:91], v[102:103]
	s_nop 0
	v_pk_fma_f32 v[82:83], v[88:89], s[72:73], v[82:83] op_sel_hi:[1,0,1]
	s_waitcnt vmcnt(11)
	v_mov_b64_e32 v[88:89], v[236:237]
	global_load_dwordx2 v[236:237], v243, s[70:71] offset:32
	v_pk_fma_f32 v[86:87], v[86:87], v[94:95], v[100:101]
	s_waitcnt lgkmcnt(0)
	v_lshlrev_b32_e32 v3, 16, v88
	v_pk_fma_f32 v[80:81], v[86:87], s[72:73], v[80:81] op_sel_hi:[1,0,1]
	v_cvt_pk_bf16_f32 v87, v82, v83
	v_cvt_pk_bf16_f32 v86, v80, v81
	v_and_b32_e32 v81, 0xffff0000, v88
	v_lshlrev_b32_e32 v83, 16, v89
	v_and_b32_e32 v90, 0xffff0000, v89
	global_store_dwordx2 v[92:93], v[86:87], off
	v_sub_f32_e32 v89, v81, v96
	v_sub_f32_e32 v88, v3, v96
	v_sub_f32_e32 v91, v90, v96
	v_sub_f32_e32 v90, v83, v96
	v_pk_mul_f32 v[94:95], v[98:99], v[90:91] op_sel_hi:[0,1]
	v_pk_mul_f32 v[104:105], v[98:99], v[88:89] op_sel_hi:[0,1]
	ds_read_b128 v[88:91], v244 offset:64
	ds_read_b128 v[100:103], v244 offset:320
	v_and_b32_e32 v82, 0xffff0000, v86
	v_lshlrev_b32_e32 v80, 16, v87
	s_waitcnt lgkmcnt(0)
	v_pk_fma_f32 v[88:89], v[88:89], v[104:105], v[100:101]
	s_nop 0
	v_pk_fma_f32 v[76:77], v[88:89], s[72:73], v[76:77] op_sel_hi:[1,0,1]
	s_waitcnt vmcnt(11)
	v_mov_b64_e32 v[88:89], v[238:239]
	global_load_dwordx2 v[238:239], v243, s[70:71] offset:256
	v_pk_fma_f32 v[90:91], v[90:91], v[94:95], v[102:103]
	v_cvt_pk_bf16_f32 v94, v76, v77
	v_pk_fma_f32 v[78:79], v[90:91], s[72:73], v[78:79] op_sel_hi:[1,0,1]
	s_waitcnt lgkmcnt(0)
	v_lshlrev_b32_e32 v3, 16, v88
	v_cvt_pk_bf16_f32 v95, v78, v79
	v_lshlrev_b32_e32 v78, 16, v95
	v_and_b32_e32 v79, 0xffff0000, v95
	v_mul_f32_e32 v76, v78, v78
	v_pk_fma_f32 v[76:77], v[78:79], v[78:79], v[76:77] op_sel_hi:[1,1,0]
	v_lshlrev_b32_e32 v81, 16, v89
	v_and_b32_e32 v76, 0xffff0000, v88
	v_and_b32_e32 v83, 0xffff0000, v89
	global_store_dwordx2 v[92:93], v[94:95], off offset:32
	v_sub_f32_e32 v89, v76, v96
	v_sub_f32_e32 v88, v3, v96
	v_sub_f32_e32 v91, v83, v96
	v_sub_f32_e32 v90, v81, v96
	v_pk_mul_f32 v[104:105], v[98:99], v[90:91] op_sel_hi:[0,1]
	v_pk_mul_f32 v[106:107], v[98:99], v[88:89] op_sel_hi:[0,1]
	ds_read_b128 v[88:91], v244 offset:128
	ds_read_b128 v[100:103], v244 offset:384
	v_and_b32_e32 v95, 0xffff0000, v94
	s_waitcnt lgkmcnt(0)
	v_pk_fma_f32 v[88:89], v[88:89], v[106:107], v[100:101]
	s_waitcnt vmcnt(11)
	v_mov_b64_e32 v[100:101], v[240:241]
	global_load_dwordx2 v[240:241], v243, s[70:71] offset:288
	v_pk_fma_f32 v[90:91], v[90:91], v[104:105], v[102:103]
	v_pk_fma_f32 v[72:73], v[88:89], s[72:73], v[72:73] op_sel_hi:[1,0,1]
	v_pk_fma_f32 v[74:75], v[90:91], s[72:73], v[74:75] op_sel_hi:[1,0,1]
	v_cvt_pk_bf16_f32 v72, v72, v73
	v_cvt_pk_bf16_f32 v73, v74, v75
	global_store_dwordx2 v[92:93], v[72:73], off offset:256
	v_lshlrev_b32_e32 v88, 16, v72
	v_and_b32_e32 v90, 0xffff0000, v72
	v_lshlrev_b32_e32 v72, 16, v73
	v_and_b32_e32 v74, 0xffff0000, v73
	v_mul_f32_e32 v89, v88, v88
	v_mul_f32_e32 v91, v90, v90
	v_mul_f32_e32 v73, v72, v72
	v_mul_f32_e32 v75, v74, v74
	v_pk_add_f32 v[72:73], v[72:73], v[74:75]
	s_waitcnt lgkmcnt(0)
	v_lshlrev_b32_e32 v3, 16, v100
	v_and_b32_e32 v76, 0xffff0000, v100
	v_lshlrev_b32_e32 v81, 16, v101
	v_and_b32_e32 v83, 0xffff0000, v101
	v_sub_f32_e32 v101, v76, v96
	v_sub_f32_e32 v100, v3, v96
	v_sub_f32_e32 v97, v83, v96
	v_sub_f32_e32 v96, v81, v96
	v_pk_mul_f32 v[96:97], v[98:99], v[96:97] op_sel_hi:[0,1]
	v_pk_mul_f32 v[98:99], v[98:99], v[100:101] op_sel_hi:[0,1]
	ds_read_b128 v[100:103], v244 offset:192
	ds_read_b128 v[104:107], v244 offset:448
	v_mov_b32_e32 v81, v95
	v_mov_b32_e32 v3, v77
	s_waitcnt lgkmcnt(0)
; __device__ __forceinline__ u32x2 pk4(f32x4 v) { u32x2 r; r.x = pk2(v.x, v.y); r.y = pk2(v.z, v.w); return r; }
;     __device__ __forceinline__ void operator()(const f32x4 (&acc)[2][2][4][2], const pg8::Unit& u, int wr, int wc, int fr, int fq) const {
;     ...
;                 const int row = u.pm * 256 + ai * 128 + wr * 64 + m * 16 + fr;
;                 float mu = 0.f, rs = 1.f; if (ln) stats_main(stm_p, row, fq, mu, rs);
;                 float s1 = 0.f, s2 = 0.f;
; #pragma unroll
;                 for (int bj = 0; bj < 2; ++bj)
; #pragma unroll
;                     for (int n = 0; n < 2; ++n) {
;                         const int col = u.pn * 256 + bj * 128 + wc * 32 + n * 16 + fq * 4;
;                         const u32x2 raw = *(const u32x2*)(src + (size_t)row * DM + col);
;                         f32x4 x = (f32x4){bflo(raw.x), bfhi(raw.x), bflo(raw.y), bfhi(raw.y)};
;                         if (ln) x = (x - mu) * rs * *(const f32x4*)(g + col) + *(const f32x4*)(b + col);
;                         const u32x2 pz = pk4(x * ALPHA + acc[ai][bj][m][n]);
;                         *(u32x2*)(dst + (size_t)row * DM + col) = pz;
;                         const float z0 = bflo(pz.x), z1 = bfhi(pz.x), z2 = bflo(pz.y), z3 = bfhi(pz.y);
;                         s1 += (z0 + z1) + (z2 + z3); s2 += (z0 * z0 + z1 * z1) + (z2 * z2 + z3 * z3);
;                     }
;                 s1 += __shfl_xor(s1, 16); s2 += __shfl_xor(s2, 16); s1 += __shfl_xor(s1, 32); s2 += __shfl_xor(s2, 32);
;                 if (fq == 0) { float* p = stm_n + (size_t)row * 32 + (u.pn * 4 + wc) * 2; p[0] = s1; p[1] = s2; }
	v_pk_fma_f32 v[98:99], v[100:101], v[98:99], v[104:105]
	s_nop 0
	v_pk_fma_f32 v[68:69], v[98:99], s[72:73], v[68:69] op_sel_hi:[1,0,1]
	v_lshlrev_b32_e32 v99, 16, v94
	v_lshlrev_b32_e32 v98, 16, v86
	v_mov_b32_e32 v83, v99
	v_pk_fma_f32 v[96:97], v[102:103], v[96:97], v[106:107]
	v_pk_mul_f32 v[100:101], v[98:99], v[98:99]
	v_pk_mul_f32 v[102:103], v[82:83], v[82:83]
	v_and_b32_e32 v94, 0xffff0000, v87
	v_pk_mul_f32 v[86:87], v[80:81], v[80:81]
	v_pk_mul_f32 v[104:105], v[94:95], v[94:95]
	v_pk_mov_b32 v[106:107], v[98:99], v[100:101] op_sel:[1,0]
	v_pk_mov_b32 v[102:103], v[94:95], v[102:103] op_sel:[1,0]
	v_pk_add_f32 v[82:83], v[98:99], v[82:83]
	v_pk_add_f32 v[80:81], v[94:95], v[80:81]
	v_pk_fma_f32 v[70:71], v[96:97], s[72:73], v[70:71] op_sel_hi:[1,0,1]
	v_pk_add_f32 v[102:103], v[106:107], v[102:103]
	v_mov_b32_e32 v106, v78
	v_mov_b32_e32 v107, v86
	v_pk_mov_b32 v[78:79], v[78:79], v[104:105] op_sel:[1,0]
	v_mov_b32_e32 v83, v101
	v_mov_b32_e32 v81, v105
	v_cvt_pk_bf16_f32 v68, v68, v69
	v_cvt_pk_bf16_f32 v69, v70, v71
	v_pk_add_f32 v[78:79], v[106:107], v[78:79]
	v_pk_add_f32 v[80:81], v[82:83], v[80:81]
	global_store_dwordx2 v[92:93], v[68:69], off offset:288
	v_lshlrev_b32_e32 v92, 16, v68
	v_and_b32_e32 v96, 0xffff0000, v68
	v_lshlrev_b32_e32 v68, 16, v69
	v_and_b32_e32 v70, 0xffff0000, v69
	v_pk_add_f32 v[78:79], v[102:103], v[78:79]
	v_pk_add_f32 v[76:77], v[80:81], v[2:3]
	v_mul_f32_e32 v93, v92, v92
	v_mul_f32_e32 v97, v96, v96
	v_mul_f32_e32 v69, v68, v68
	v_mul_f32_e32 v71, v70, v70
	v_pk_add_f32 v[76:77], v[78:79], v[76:77]
	v_pk_add_f32 v[78:79], v[88:89], v[90:91]
	v_pk_add_f32 v[74:75], v[92:93], v[96:97]
	v_pk_add_f32 v[72:73], v[78:79], v[72:73]
	v_pk_add_f32 v[68:69], v[68:69], v[70:71]
	v_pk_add_f32 v[72:73], v[76:77], v[72:73]
	v_pk_add_f32 v[68:69], v[74:75], v[68:69]
	s_nop 0
	v_pk_add_f32 v[68:69], v[72:73], v[68:69]
	ds_bpermute_b32 v70, v181, v68
	ds_bpermute_b32 v71, v181, v69
	s_waitcnt lgkmcnt(0)
	v_pk_add_f32 v[68:69], v[68:69], v[70:71]
	ds_bpermute_b32 v70, v180, v68
	ds_bpermute_b32 v71, v180, v69
	s_and_saveexec_b64 s[0:1], s[40:41]
	s_cbranch_execz .LBB0_2211
	v_lshl_add_u64 v[72:73], s[50:51], 0, v[84:85]
	v_lshl_add_u64 v[72:73], s[60:61], 2, v[72:73]
	s_waitcnt lgkmcnt(0)
	v_pk_add_f32 v[68:69], v[68:69], v[70:71]
	global_store_dwordx2 v[72:73], v[68:69], off
.LBB0_2211:
	s_or_b64 exec, exec, s[0:1]
	v_add_u32_e32 v78, 0x80, v146
	v_ashrrev_i32_e32 v79, 31, v78
	v_lshlrev_b64 v[68:69], 7, v[78:79]
	v_lshl_add_u64 v[74:75], v[134:135], 0, v[68:69]
	s_waitcnt lgkmcnt(0)
	s_waitcnt vmcnt(11)
	v_mov_b64_e32 v[70:71], v[190:191]
	v_mov_b64_e32 v[72:73], v[192:193]
	global_load_dwordx4 v[190:193], v[248:249], off offset:16
	s_nop 0
	s_waitcnt vmcnt(11)
	v_mov_b64_e32 v[74:75], v[194:195]
	v_mov_b64_e32 v[76:77], v[196:197]
	global_load_dwordx4 v[194:197], v[248:249], off
	s_waitcnt lgkmcnt(0)
	v_pk_add_f32 v[70:71], v[70:71], v[72:73]
	s_waitcnt lgkmcnt(0)
	v_pk_add_f32 v[74:75], v[74:75], v[76:77]
	s_nop 0
	v_pk_add_f32 v[70:71], v[74:75], v[70:71]
	ds_bpermute_b32 v72, v181, v70
	ds_bpermute_b32 v73, v181, v71
	s_waitcnt lgkmcnt(0)
	v_pk_add_f32 v[70:71], v[70:71], v[72:73]
	ds_bpermute_b32 v72, v180, v70
	ds_bpermute_b32 v73, v180, v71
	s_waitcnt lgkmcnt(0)
	v_pk_add_f32 v[70:71], v[70:71], v[72:73]
	s_nop 0
	v_pk_mul_f32 v[80:81], v[70:71], s[82:83] op_sel_hi:[1,0]
	v_lshlrev_b64 v[70:71], 11, v[78:79]
	v_lshl_add_u64 v[70:71], s[70:71], 0, v[70:71]
	v_lshl_add_u64 v[76:77], v[144:145], 1, v[70:71]
	v_add_u32_e32 v243, 0x50000, v242
	s_waitcnt vmcnt(11)
	v_mov_b64_e32 v[70:71], v[198:199]
	global_load_dwordx2 v[198:199], v243, s[70:71]
	v_fma_f32 v3, -v80, v80, v81
	v_max_f32_e32 v3, 0, v3
	v_add_f32_e32 v3, 0x3727c5ac, v3
	v_rsq_f32_e32 v82, v3
	s_waitcnt lgkmcnt(0)
	v_lshlrev_b32_e32 v3, 16, v70
	v_and_b32_e32 v70, 0xffff0000, v70
	v_lshlrev_b32_e32 v72, 16, v71
	v_and_b32_e32 v73, 0xffff0000, v71
	v_sub_f32_e32 v71, v70, v80
	v_sub_f32_e32 v70, v3, v80
	v_sub_f32_e32 v73, v73, v80
	v_sub_f32_e32 v72, v72, v80
	v_pk_mul_f32 v[74:75], v[72:73], v[82:83] op_sel_hi:[1,0]
	v_pk_mul_f32 v[78:79], v[70:71], v[82:83] op_sel_hi:[1,0]
	ds_read_b128 v[70:73], v244
	ds_read_b128 v[84:87], v244 offset:256
	s_waitcnt lgkmcnt(0)
	v_pk_fma_f32 v[72:73], v[72:73], v[74:75], v[86:87]
	s_nop 0
	v_pk_fma_f32 v[66:67], v[72:73], s[72:73], v[66:67] op_sel_hi:[1,0,1]
	s_waitcnt vmcnt(11)
	v_mov_b64_e32 v[72:73], v[200:201]
	global_load_dwordx2 v[200:201], v243, s[70:71] offset:32
	v_pk_fma_f32 v[70:71], v[70:71], v[78:79], v[84:85]
	s_waitcnt lgkmcnt(0)
	v_lshlrev_b32_e32 v3, 16, v72
	v_pk_fma_f32 v[64:65], v[70:71], s[72:73], v[64:65] op_sel_hi:[1,0,1]
	v_cvt_pk_bf16_f32 v71, v66, v67
	v_cvt_pk_bf16_f32 v70, v64, v65
	v_and_b32_e32 v65, 0xffff0000, v72
	v_lshlrev_b32_e32 v67, 16, v73
	v_and_b32_e32 v74, 0xffff0000, v73
	global_store_dwordx2 v[76:77], v[70:71], off
	v_sub_f32_e32 v73, v65, v80
	v_sub_f32_e32 v72, v3, v80
	v_sub_f32_e32 v75, v74, v80
	v_sub_f32_e32 v74, v67, v80
	v_pk_mul_f32 v[78:79], v[82:83], v[74:75] op_sel_hi:[0,1]
	v_pk_mul_f32 v[88:89], v[82:83], v[72:73] op_sel_hi:[0,1]
	ds_read_b128 v[72:75], v244 offset:64
	ds_read_b128 v[84:87], v244 offset:320
	v_and_b32_e32 v66, 0xffff0000, v70
	v_lshlrev_b32_e32 v64, 16, v71
	s_waitcnt lgkmcnt(0)
	v_pk_fma_f32 v[72:73], v[72:73], v[88:89], v[84:85]
	s_nop 0
	v_pk_fma_f32 v[60:61], v[72:73], s[72:73], v[60:61] op_sel_hi:[1,0,1]
	s_waitcnt vmcnt(11)
	v_mov_b64_e32 v[72:73], v[202:203]
	global_load_dwordx2 v[202:203], v243, s[70:71] offset:256
	v_pk_fma_f32 v[74:75], v[74:75], v[78:79], v[86:87]
	v_cvt_pk_bf16_f32 v78, v60, v61
	v_pk_fma_f32 v[62:63], v[74:75], s[72:73], v[62:63] op_sel_hi:[1,0,1]
	s_waitcnt lgkmcnt(0)
; __device__ __forceinline__ u32x2 pk4(f32x4 v) { u32x2 r; r.x = pk2(v.x, v.y); r.y = pk2(v.z, v.w); return r; }
;     __device__ __forceinline__ void operator()(const f32x4 (&acc)[2][2][4][2], const pg8::Unit& u, int wr, int wc, int fr, int fq) const {
;     ...
;                         const int col = u.pn * 256 + bj * 128 + wc * 32 + n * 16 + fq * 4;
;                         const u32x2 raw = *(const u32x2*)(src + (size_t)row * DM + col);
;                         f32x4 x = (f32x4){bflo(raw.x), bfhi(raw.x), bflo(raw.y), bfhi(raw.y)};
;                         if (ln) x = (x - mu) * rs * *(const f32x4*)(g + col) + *(const f32x4*)(b + col);
;                         const u32x2 pz = pk4(x * ALPHA + acc[ai][bj][m][n]);
;                         *(u32x2*)(dst + (size_t)row * DM + col) = pz;
;                         const float z0 = bflo(pz.x), z1 = bfhi(pz.x), z2 = bflo(pz.y), z3 = bfhi(pz.y);
;                         s1 += (z0 + z1) + (z2 + z3); s2 += (z0 * z0 + z1 * z1) + (z2 * z2 + z3 * z3);
;                     }
;                 s1 += __shfl_xor(s1, 16); s2 += __shfl_xor(s2, 16); s1 += __shfl_xor(s1, 32); s2 += __shfl_xor(s2, 32);
;                 if (fq == 0) { float* p = stm_n + (size_t)row * 32 + (u.pn * 4 + wc) * 2; p[0] = s1; p[1] = s2; }
	v_lshlrev_b32_e32 v3, 16, v72
	v_cvt_pk_bf16_f32 v79, v62, v63
	v_lshlrev_b32_e32 v62, 16, v79
	v_and_b32_e32 v63, 0xffff0000, v79
	v_mul_f32_e32 v60, v62, v62
	v_pk_fma_f32 v[60:61], v[62:63], v[62:63], v[60:61] op_sel_hi:[1,1,0]
	v_lshlrev_b32_e32 v65, 16, v73
	v_and_b32_e32 v60, 0xffff0000, v72
	v_and_b32_e32 v67, 0xffff0000, v73
	global_store_dwordx2 v[76:77], v[78:79], off offset:32
	v_sub_f32_e32 v73, v60, v80
	v_sub_f32_e32 v72, v3, v80
	v_sub_f32_e32 v75, v67, v80
	v_sub_f32_e32 v74, v65, v80
	v_pk_mul_f32 v[88:89], v[82:83], v[74:75] op_sel_hi:[0,1]
	v_pk_mul_f32 v[90:91], v[82:83], v[72:73] op_sel_hi:[0,1]
	ds_read_b128 v[72:75], v244 offset:128
	ds_read_b128 v[84:87], v244 offset:384
	v_and_b32_e32 v79, 0xffff0000, v78
	s_waitcnt lgkmcnt(0)
	v_pk_fma_f32 v[72:73], v[72:73], v[90:91], v[84:85]
	s_waitcnt vmcnt(11)
	v_mov_b64_e32 v[84:85], v[204:205]
	global_load_dwordx2 v[204:205], v243, s[70:71] offset:288
	v_pk_fma_f32 v[74:75], v[74:75], v[88:89], v[86:87]
	v_pk_fma_f32 v[56:57], v[72:73], s[72:73], v[56:57] op_sel_hi:[1,0,1]
	v_pk_fma_f32 v[58:59], v[74:75], s[72:73], v[58:59] op_sel_hi:[1,0,1]
	v_cvt_pk_bf16_f32 v56, v56, v57
	v_cvt_pk_bf16_f32 v57, v58, v59
	global_store_dwordx2 v[76:77], v[56:57], off offset:256
	v_lshlrev_b32_e32 v72, 16, v56
	v_and_b32_e32 v74, 0xffff0000, v56
	v_lshlrev_b32_e32 v56, 16, v57
	v_and_b32_e32 v58, 0xffff0000, v57
	v_mul_f32_e32 v73, v72, v72
	v_mul_f32_e32 v75, v74, v74
	v_mul_f32_e32 v57, v56, v56
	v_mul_f32_e32 v59, v58, v58
	v_pk_add_f32 v[56:57], v[56:57], v[58:59]
	s_waitcnt lgkmcnt(0)
	v_lshlrev_b32_e32 v3, 16, v84
	v_and_b32_e32 v60, 0xffff0000, v84
	v_lshlrev_b32_e32 v65, 16, v85
	v_and_b32_e32 v67, 0xffff0000, v85
	v_sub_f32_e32 v85, v60, v80
	v_sub_f32_e32 v84, v3, v80
	v_sub_f32_e32 v81, v67, v80
	v_sub_f32_e32 v80, v65, v80
	v_pk_mul_f32 v[80:81], v[82:83], v[80:81] op_sel_hi:[0,1]
	v_pk_mul_f32 v[82:83], v[82:83], v[84:85] op_sel_hi:[0,1]
	ds_read_b128 v[84:87], v244 offset:192
	ds_read_b128 v[88:91], v244 offset:448
	v_mov_b32_e32 v65, v79
	v_mov_b32_e32 v3, v61
	s_waitcnt lgkmcnt(0)
	v_pk_fma_f32 v[82:83], v[84:85], v[82:83], v[88:89]
	s_nop 0
	v_pk_fma_f32 v[52:53], v[82:83], s[72:73], v[52:53] op_sel_hi:[1,0,1]
	v_lshlrev_b32_e32 v83, 16, v78
	v_lshlrev_b32_e32 v82, 16, v70
	v_mov_b32_e32 v67, v83
	v_pk_fma_f32 v[80:81], v[86:87], v[80:81], v[90:91]
	v_pk_mul_f32 v[84:85], v[82:83], v[82:83]
	v_pk_mul_f32 v[86:87], v[66:67], v[66:67]
	v_and_b32_e32 v78, 0xffff0000, v71
	v_pk_mul_f32 v[70:71], v[64:65], v[64:65]
	v_pk_mul_f32 v[88:89], v[78:79], v[78:79]
	v_pk_mov_b32 v[90:91], v[82:83], v[84:85] op_sel:[1,0]
	v_pk_mov_b32 v[86:87], v[78:79], v[86:87] op_sel:[1,0]
	v_pk_add_f32 v[66:67], v[82:83], v[66:67]
	v_pk_add_f32 v[64:65], v[78:79], v[64:65]
	v_pk_fma_f32 v[54:55], v[80:81], s[72:73], v[54:55] op_sel_hi:[1,0,1]
	v_pk_add_f32 v[86:87], v[90:91], v[86:87]
	v_mov_b32_e32 v90, v62
	v_mov_b32_e32 v91, v70
	v_pk_mov_b32 v[62:63], v[62:63], v[88:89] op_sel:[1,0]
	v_mov_b32_e32 v67, v85
	v_mov_b32_e32 v65, v89
	v_cvt_pk_bf16_f32 v52, v52, v53
	v_cvt_pk_bf16_f32 v53, v54, v55
	v_pk_add_f32 v[62:63], v[90:91], v[62:63]
	v_pk_add_f32 v[64:65], v[66:67], v[64:65]
	global_store_dwordx2 v[76:77], v[52:53], off offset:288
	v_lshlrev_b32_e32 v76, 16, v52
	v_and_b32_e32 v80, 0xffff0000, v52
	v_lshlrev_b32_e32 v52, 16, v53
	v_and_b32_e32 v54, 0xffff0000, v53
	v_pk_add_f32 v[62:63], v[86:87], v[62:63]
	v_pk_add_f32 v[60:61], v[64:65], v[2:3]
	v_mul_f32_e32 v77, v76, v76
	v_mul_f32_e32 v81, v80, v80
	v_mul_f32_e32 v53, v52, v52
	v_mul_f32_e32 v55, v54, v54
	v_pk_add_f32 v[60:61], v[62:63], v[60:61]
	v_pk_add_f32 v[62:63], v[72:73], v[74:75]
	v_pk_add_f32 v[58:59], v[76:77], v[80:81]
	v_pk_add_f32 v[56:57], v[62:63], v[56:57]
	v_pk_add_f32 v[52:53], v[52:53], v[54:55]
	v_pk_add_f32 v[56:57], v[60:61], v[56:57]
	v_pk_add_f32 v[52:53], v[58:59], v[52:53]
	s_nop 0
	v_pk_add_f32 v[52:53], v[56:57], v[52:53]
	ds_bpermute_b32 v54, v181, v52
	ds_bpermute_b32 v55, v181, v53
	s_waitcnt lgkmcnt(0)
	v_pk_add_f32 v[52:53], v[52:53], v[54:55]
	ds_bpermute_b32 v54, v180, v52
	ds_bpermute_b32 v55, v180, v53
	s_and_saveexec_b64 s[0:1], s[40:41]
	s_cbranch_execz .LBB0_2213
	v_lshl_add_u64 v[56:57], s[50:51], 0, v[68:69]
	v_lshl_add_u64 v[56:57], s[60:61], 2, v[56:57]
	s_waitcnt lgkmcnt(0)
	v_pk_add_f32 v[52:53], v[52:53], v[54:55]
	global_store_dwordx2 v[56:57], v[52:53], off
; __device__ __forceinline__ u32x2 pk4(f32x4 v) { u32x2 r; r.x = pk2(v.x, v.y); r.y = pk2(v.z, v.w); return r; }
; __device__ __forceinline__ void stats_main(const float* stm, int row, int fq, float& mu, float& rs) {
;     const f32x4* p = (const f32x4*)(stm + (size_t)row * 32 + fq * 8);
;     const f32x4 a = p[0], b = p[1];
;     float s1 = (a.x + a.z) + (b.x + b.z), s2 = (a.y + a.w) + (b.y + b.w);
;     s1 += __shfl_xor(s1, 16); s2 += __shfl_xor(s2, 16); s1 += __shfl_xor(s1, 32); s2 += __shfl_xor(s2, 32);
;     mu = s1 * (1.f / DM); rs = __builtin_amdgcn_rsqf(fmaxf(s2 * (1.f / DM) - mu * mu, 0.f) + LN_EPS);
; }
;     __device__ __forceinline__ void operator()(const f32x4 (&acc)[2][2][4][2], const pg8::Unit& u, int wr, int wc, int fr, int fq) const {
;     ...
;                 const int row = u.pm * 256 + ai * 128 + wr * 64 + m * 16 + fr;
;                 float mu = 0.f, rs = 1.f; if (ln) stats_main(stm_p, row, fq, mu, rs);
;                 float s1 = 0.f, s2 = 0.f;
; #pragma unroll
;                 for (int bj = 0; bj < 2; ++bj)
; #pragma unroll
;                     for (int n = 0; n < 2; ++n) {
;                         const int col = u.pn * 256 + bj * 128 + wc * 32 + n * 16 + fq * 4;
;                         const u32x2 raw = *(const u32x2*)(src + (size_t)row * DM + col);
;                         f32x4 x = (f32x4){bflo(raw.x), bfhi(raw.x), bflo(raw.y), bfhi(raw.y)};
;                         if (ln) x = (x - mu) * rs * *(const f32x4*)(g + col) + *(const f32x4*)(b + col);
;                         const u32x2 pz = pk4(x * ALPHA + acc[ai][bj][m][n]);
;                         *(u32x2*)(dst + (size_t)row * DM + col) = pz;
;                         const float z0 = bflo(pz.x), z1 = bfhi(pz.x), z2 = bflo(pz.y), z3 = bfhi(pz.y);
;                         s1 += (z0 + z1) + (z2 + z3); s2 += (z0 * z0 + z1 * z1) + (z2 * z2 + z3 * z3);
;                     }
;                 s1 += __shfl_xor(s1, 16); s2 += __shfl_xor(s2, 16); s1 += __shfl_xor(s1, 32); s2 += __shfl_xor(s2, 32);
;                 if (fq == 0) { float* p = stm_n + (size_t)row * 32 + (u.pn * 4 + wc) * 2; p[0] = s1; p[1] = s2; }
.LBB0_2213:
	s_or_b64 exec, exec, s[0:1]
	v_add_u32_e32 v62, 0x90, v146
	v_ashrrev_i32_e32 v63, 31, v62
	v_lshlrev_b64 v[52:53], 7, v[62:63]
	v_lshl_add_u64 v[58:59], v[134:135], 0, v[52:53]
	s_waitcnt lgkmcnt(0)
	s_waitcnt vmcnt(11)
	v_mov_b64_e32 v[54:55], v[206:207]
	v_mov_b64_e32 v[56:57], v[208:209]
	global_load_dwordx4 v[206:209], v[248:249], off offset:2064
	s_nop 0
	s_waitcnt vmcnt(11)
	v_mov_b64_e32 v[58:59], v[214:215]
	v_mov_b64_e32 v[60:61], v[216:217]
	global_load_dwordx4 v[214:217], v[248:249], off offset:2048
	s_waitcnt lgkmcnt(0)
	v_pk_add_f32 v[54:55], v[54:55], v[56:57]
	s_waitcnt lgkmcnt(0)
	v_pk_add_f32 v[58:59], v[58:59], v[60:61]
	s_nop 0
	v_pk_add_f32 v[54:55], v[58:59], v[54:55]
	ds_bpermute_b32 v56, v181, v54
	ds_bpermute_b32 v57, v181, v55
	s_waitcnt lgkmcnt(0)
	v_pk_add_f32 v[54:55], v[54:55], v[56:57]
	ds_bpermute_b32 v56, v180, v54
	ds_bpermute_b32 v57, v180, v55
	s_waitcnt lgkmcnt(0)
	v_pk_add_f32 v[54:55], v[54:55], v[56:57]
	s_nop 0
	v_pk_mul_f32 v[64:65], v[54:55], s[82:83] op_sel_hi:[1,0]
	v_lshlrev_b64 v[54:55], 11, v[62:63]
	v_lshl_add_u64 v[54:55], s[70:71], 0, v[54:55]
	v_lshl_add_u64 v[60:61], v[144:145], 1, v[54:55]
	v_add_u32_e32 v243, 0x58000, v242
	s_waitcnt vmcnt(11)
	v_mov_b64_e32 v[54:55], v[234:235]
	global_load_dwordx2 v[234:235], v243, s[70:71]
	v_fma_f32 v3, -v64, v64, v65
	v_max_f32_e32 v3, 0, v3
	v_add_f32_e32 v3, 0x3727c5ac, v3
	v_rsq_f32_e32 v66, v3
	s_waitcnt lgkmcnt(0)
	v_lshlrev_b32_e32 v3, 16, v54
	v_and_b32_e32 v54, 0xffff0000, v54
	v_lshlrev_b32_e32 v56, 16, v55
	v_and_b32_e32 v57, 0xffff0000, v55
	v_sub_f32_e32 v55, v54, v64
	v_sub_f32_e32 v54, v3, v64
	v_sub_f32_e32 v57, v57, v64
	v_sub_f32_e32 v56, v56, v64
	v_pk_mul_f32 v[58:59], v[56:57], v[66:67] op_sel_hi:[1,0]
	v_pk_mul_f32 v[62:63], v[54:55], v[66:67] op_sel_hi:[1,0]
	ds_read_b128 v[54:57], v244
	ds_read_b128 v[68:71], v244 offset:256
	s_waitcnt lgkmcnt(0)
	v_pk_fma_f32 v[56:57], v[56:57], v[58:59], v[70:71]
	s_nop 0
	v_pk_fma_f32 v[50:51], v[56:57], s[72:73], v[50:51] op_sel_hi:[1,0,1]
	s_waitcnt vmcnt(11)
	v_mov_b64_e32 v[56:57], v[236:237]
	global_load_dwordx2 v[236:237], v243, s[70:71] offset:32
	v_pk_fma_f32 v[54:55], v[54:55], v[62:63], v[68:69]
	s_waitcnt lgkmcnt(0)
	v_lshlrev_b32_e32 v3, 16, v56
	v_pk_fma_f32 v[48:49], v[54:55], s[72:73], v[48:49] op_sel_hi:[1,0,1]
	v_cvt_pk_bf16_f32 v55, v50, v51
	v_cvt_pk_bf16_f32 v54, v48, v49
	v_and_b32_e32 v49, 0xffff0000, v56
	v_lshlrev_b32_e32 v51, 16, v57
	v_and_b32_e32 v58, 0xffff0000, v57
	global_store_dwordx2 v[60:61], v[54:55], off
	v_sub_f32_e32 v57, v49, v64
	v_sub_f32_e32 v56, v3, v64
	v_sub_f32_e32 v59, v58, v64
	v_sub_f32_e32 v58, v51, v64
	v_pk_mul_f32 v[62:63], v[66:67], v[58:59] op_sel_hi:[0,1]
	v_pk_mul_f32 v[72:73], v[66:67], v[56:57] op_sel_hi:[0,1]
	ds_read_b128 v[56:59], v244 offset:64
	ds_read_b128 v[68:71], v244 offset:320
	v_and_b32_e32 v50, 0xffff0000, v54
	v_lshlrev_b32_e32 v48, 16, v55
	s_waitcnt lgkmcnt(0)
	v_pk_fma_f32 v[56:57], v[56:57], v[72:73], v[68:69]
	s_nop 0
	v_pk_fma_f32 v[44:45], v[56:57], s[72:73], v[44:45] op_sel_hi:[1,0,1]
	s_waitcnt vmcnt(11)
	v_mov_b64_e32 v[56:57], v[238:239]
	global_load_dwordx2 v[238:239], v243, s[70:71] offset:256
	v_pk_fma_f32 v[58:59], v[58:59], v[62:63], v[70:71]
	v_cvt_pk_bf16_f32 v62, v44, v45
	v_pk_fma_f32 v[46:47], v[58:59], s[72:73], v[46:47] op_sel_hi:[1,0,1]
	s_waitcnt lgkmcnt(0)
	v_lshlrev_b32_e32 v3, 16, v56
	v_cvt_pk_bf16_f32 v63, v46, v47
	v_lshlrev_b32_e32 v46, 16, v63
	v_and_b32_e32 v47, 0xffff0000, v63
	v_mul_f32_e32 v44, v46, v46
	v_pk_fma_f32 v[44:45], v[46:47], v[46:47], v[44:45] op_sel_hi:[1,1,0]
	v_lshlrev_b32_e32 v49, 16, v57
	v_and_b32_e32 v44, 0xffff0000, v56
	v_and_b32_e32 v51, 0xffff0000, v57
	global_store_dwordx2 v[60:61], v[62:63], off offset:32
	v_sub_f32_e32 v57, v44, v64
	v_sub_f32_e32 v56, v3, v64
	v_sub_f32_e32 v59, v51, v64
	v_sub_f32_e32 v58, v49, v64
	v_pk_mul_f32 v[72:73], v[66:67], v[58:59] op_sel_hi:[0,1]
	v_pk_mul_f32 v[74:75], v[66:67], v[56:57] op_sel_hi:[0,1]
	ds_read_b128 v[56:59], v244 offset:128
	ds_read_b128 v[68:71], v244 offset:384
	v_and_b32_e32 v63, 0xffff0000, v62
	s_waitcnt lgkmcnt(0)
	v_pk_fma_f32 v[56:57], v[56:57], v[74:75], v[68:69]
	s_waitcnt vmcnt(11)
	v_mov_b64_e32 v[68:69], v[240:241]
	global_load_dwordx2 v[240:241], v243, s[70:71] offset:288
	v_pk_fma_f32 v[58:59], v[58:59], v[72:73], v[70:71]
	v_pk_fma_f32 v[40:41], v[56:57], s[72:73], v[40:41] op_sel_hi:[1,0,1]
	v_pk_fma_f32 v[42:43], v[58:59], s[72:73], v[42:43] op_sel_hi:[1,0,1]
	v_cvt_pk_bf16_f32 v40, v40, v41
	v_cvt_pk_bf16_f32 v41, v42, v43
	global_store_dwordx2 v[60:61], v[40:41], off offset:256
	v_lshlrev_b32_e32 v56, 16, v40
	v_and_b32_e32 v58, 0xffff0000, v40
	v_lshlrev_b32_e32 v40, 16, v41
	v_and_b32_e32 v42, 0xffff0000, v41
	v_mul_f32_e32 v57, v56, v56
	v_mul_f32_e32 v59, v58, v58
	v_mul_f32_e32 v41, v40, v40
	v_mul_f32_e32 v43, v42, v42
	v_pk_add_f32 v[40:41], v[40:41], v[42:43]
	s_waitcnt lgkmcnt(0)
	v_lshlrev_b32_e32 v3, 16, v68
	v_and_b32_e32 v44, 0xffff0000, v68
	v_lshlrev_b32_e32 v49, 16, v69
	v_and_b32_e32 v51, 0xffff0000, v69
	v_sub_f32_e32 v69, v44, v64
	v_sub_f32_e32 v68, v3, v64
	v_sub_f32_e32 v65, v51, v64
	v_sub_f32_e32 v64, v49, v64
	v_pk_mul_f32 v[64:65], v[66:67], v[64:65] op_sel_hi:[0,1]
	v_pk_mul_f32 v[66:67], v[66:67], v[68:69] op_sel_hi:[0,1]
	ds_read_b128 v[68:71], v244 offset:192
	ds_read_b128 v[72:75], v244 offset:448
	v_mov_b32_e32 v49, v63
	v_mov_b32_e32 v3, v45
	s_waitcnt lgkmcnt(0)
; __device__ __forceinline__ u32x2 pk4(f32x4 v) { u32x2 r; r.x = pk2(v.x, v.y); r.y = pk2(v.z, v.w); return r; }
; __device__ __forceinline__ void stats_main(const float* stm, int row, int fq, float& mu, float& rs) {
;     const f32x4* p = (const f32x4*)(stm + (size_t)row * 32 + fq * 8);
;     const f32x4 a = p[0], b = p[1];
;     float s1 = (a.x + a.z) + (b.x + b.z), s2 = (a.y + a.w) + (b.y + b.w);
;     s1 += __shfl_xor(s1, 16); s2 += __shfl_xor(s2, 16); s1 += __shfl_xor(s1, 32); s2 += __shfl_xor(s2, 32);
;     mu = s1 * (1.f / DM); rs = __builtin_amdgcn_rsqf(fmaxf(s2 * (1.f / DM) - mu * mu, 0.f) + LN_EPS);
; }
;     __device__ __forceinline__ void operator()(const f32x4 (&acc)[2][2][4][2], const pg8::Unit& u, int wr, int wc, int fr, int fq) const {
;     ...
;                 for (int bj = 0; bj < 2; ++bj)
; #pragma unroll
;                     for (int n = 0; n < 2; ++n) {
;                         const int col = u.pn * 256 + bj * 128 + wc * 32 + n * 16 + fq * 4;
;                         const u32x2 raw = *(const u32x2*)(src + (size_t)row * DM + col);
;                         f32x4 x = (f32x4){bflo(raw.x), bfhi(raw.x), bflo(raw.y), bfhi(raw.y)};
;                         if (ln) x = (x - mu) * rs * *(const f32x4*)(g + col) + *(const f32x4*)(b + col);
;                         const u32x2 pz = pk4(x * ALPHA + acc[ai][bj][m][n]);
;                         *(u32x2*)(dst + (size_t)row * DM + col) = pz;
;                         const float z0 = bflo(pz.x), z1 = bfhi(pz.x), z2 = bflo(pz.y), z3 = bfhi(pz.y);
;                         s1 += (z0 + z1) + (z2 + z3); s2 += (z0 * z0 + z1 * z1) + (z2 * z2 + z3 * z3);
;                     }
;                 s1 += __shfl_xor(s1, 16); s2 += __shfl_xor(s2, 16); s1 += __shfl_xor(s1, 32); s2 += __shfl_xor(s2, 32);
;                 if (fq == 0) { float* p = stm_n + (size_t)row * 32 + (u.pn * 4 + wc) * 2; p[0] = s1; p[1] = s2; }
	v_pk_fma_f32 v[66:67], v[68:69], v[66:67], v[72:73]
	s_nop 0
	v_pk_fma_f32 v[36:37], v[66:67], s[72:73], v[36:37] op_sel_hi:[1,0,1]
	v_lshlrev_b32_e32 v67, 16, v62
	v_lshlrev_b32_e32 v66, 16, v54
	v_mov_b32_e32 v51, v67
	v_pk_fma_f32 v[64:65], v[70:71], v[64:65], v[74:75]
	v_pk_mul_f32 v[68:69], v[66:67], v[66:67]
	v_pk_mul_f32 v[70:71], v[50:51], v[50:51]
	v_and_b32_e32 v62, 0xffff0000, v55
	v_pk_mul_f32 v[54:55], v[48:49], v[48:49]
	v_pk_mul_f32 v[72:73], v[62:63], v[62:63]
	v_pk_mov_b32 v[74:75], v[66:67], v[68:69] op_sel:[1,0]
	v_pk_mov_b32 v[70:71], v[62:63], v[70:71] op_sel:[1,0]
	v_pk_add_f32 v[50:51], v[66:67], v[50:51]
	v_pk_add_f32 v[48:49], v[62:63], v[48:49]
	v_pk_fma_f32 v[38:39], v[64:65], s[72:73], v[38:39] op_sel_hi:[1,0,1]
	v_pk_add_f32 v[70:71], v[74:75], v[70:71]
	v_mov_b32_e32 v74, v46
	v_mov_b32_e32 v75, v54
	v_pk_mov_b32 v[46:47], v[46:47], v[72:73] op_sel:[1,0]
	v_mov_b32_e32 v51, v69
	v_mov_b32_e32 v49, v73
	v_cvt_pk_bf16_f32 v36, v36, v37
	v_cvt_pk_bf16_f32 v37, v38, v39
	v_pk_add_f32 v[46:47], v[74:75], v[46:47]
	v_pk_add_f32 v[48:49], v[50:51], v[48:49]
	global_store_dwordx2 v[60:61], v[36:37], off offset:288
	v_lshlrev_b32_e32 v60, 16, v36
	v_and_b32_e32 v64, 0xffff0000, v36
	v_lshlrev_b32_e32 v36, 16, v37
	v_and_b32_e32 v38, 0xffff0000, v37
	v_pk_add_f32 v[46:47], v[70:71], v[46:47]
	v_pk_add_f32 v[44:45], v[48:49], v[2:3]
	v_mul_f32_e32 v61, v60, v60
	v_mul_f32_e32 v65, v64, v64
	v_mul_f32_e32 v37, v36, v36
	v_mul_f32_e32 v39, v38, v38
	v_pk_add_f32 v[44:45], v[46:47], v[44:45]
	v_pk_add_f32 v[46:47], v[56:57], v[58:59]
	v_pk_add_f32 v[42:43], v[60:61], v[64:65]
	v_pk_add_f32 v[40:41], v[46:47], v[40:41]
	v_pk_add_f32 v[36:37], v[36:37], v[38:39]
	v_pk_add_f32 v[40:41], v[44:45], v[40:41]
	v_pk_add_f32 v[36:37], v[42:43], v[36:37]
	s_nop 0
	v_pk_add_f32 v[36:37], v[40:41], v[36:37]
	ds_bpermute_b32 v38, v181, v36
	ds_bpermute_b32 v39, v181, v37
	s_waitcnt lgkmcnt(0)
	v_pk_add_f32 v[36:37], v[36:37], v[38:39]
	ds_bpermute_b32 v38, v180, v36
	ds_bpermute_b32 v39, v180, v37
	s_and_saveexec_b64 s[0:1], s[40:41]
	s_cbranch_execz .LBB0_2215
	v_lshl_add_u64 v[40:41], s[50:51], 0, v[52:53]
	v_lshl_add_u64 v[40:41], s[60:61], 2, v[40:41]
	s_waitcnt lgkmcnt(0)
	v_pk_add_f32 v[36:37], v[36:37], v[38:39]
	global_store_dwordx2 v[40:41], v[36:37], off
.LBB0_2215:
	s_or_b64 exec, exec, s[0:1]
	v_add_u32_e32 v46, 0xa0, v146
	v_ashrrev_i32_e32 v47, 31, v46
	v_lshlrev_b64 v[36:37], 7, v[46:47]
	v_lshl_add_u64 v[42:43], v[134:135], 0, v[36:37]
	s_waitcnt lgkmcnt(0)
	s_waitcnt vmcnt(11)
	v_mov_b64_e32 v[38:39], v[190:191]
	v_mov_b64_e32 v[40:41], v[192:193]
	s_nop 0
	s_waitcnt vmcnt(10)
	v_mov_b64_e32 v[42:43], v[194:195]
	v_mov_b64_e32 v[44:45], v[196:197]
	s_waitcnt lgkmcnt(0)
	v_pk_add_f32 v[38:39], v[38:39], v[40:41]
	s_waitcnt lgkmcnt(0)
	v_pk_add_f32 v[42:43], v[42:43], v[44:45]
	s_nop 0
	v_pk_add_f32 v[38:39], v[42:43], v[38:39]
	ds_bpermute_b32 v40, v181, v38
	ds_bpermute_b32 v41, v181, v39
	s_waitcnt lgkmcnt(0)
	v_pk_add_f32 v[38:39], v[38:39], v[40:41]
	ds_bpermute_b32 v40, v180, v38
	ds_bpermute_b32 v41, v180, v39
	s_waitcnt lgkmcnt(0)
	v_pk_add_f32 v[38:39], v[38:39], v[40:41]
	s_nop 0
	v_pk_mul_f32 v[48:49], v[38:39], s[82:83] op_sel_hi:[1,0]
	v_lshlrev_b64 v[38:39], 11, v[46:47]
	v_lshl_add_u64 v[38:39], s[70:71], 0, v[38:39]
	v_lshl_add_u64 v[44:45], v[144:145], 1, v[38:39]
	s_waitcnt vmcnt(9)
	v_mov_b64_e32 v[38:39], v[198:199]
	v_fma_f32 v3, -v48, v48, v49
	v_max_f32_e32 v3, 0, v3
	v_add_f32_e32 v3, 0x3727c5ac, v3
	v_rsq_f32_e32 v50, v3
	s_waitcnt lgkmcnt(0)
	v_lshlrev_b32_e32 v3, 16, v38
	v_and_b32_e32 v38, 0xffff0000, v38
	v_lshlrev_b32_e32 v40, 16, v39
	v_and_b32_e32 v41, 0xffff0000, v39
	v_sub_f32_e32 v39, v38, v48
	v_sub_f32_e32 v38, v3, v48
	v_sub_f32_e32 v41, v41, v48
	v_sub_f32_e32 v40, v40, v48
	v_pk_mul_f32 v[42:43], v[40:41], v[50:51] op_sel_hi:[1,0]
	v_pk_mul_f32 v[46:47], v[38:39], v[50:51] op_sel_hi:[1,0]
	ds_read_b128 v[38:41], v244
	ds_read_b128 v[52:55], v244 offset:256
	s_waitcnt lgkmcnt(0)
	v_pk_fma_f32 v[40:41], v[40:41], v[42:43], v[54:55]
	s_nop 0
	v_pk_fma_f32 v[34:35], v[40:41], s[72:73], v[34:35] op_sel_hi:[1,0,1]
	s_waitcnt vmcnt(8)
	v_mov_b64_e32 v[40:41], v[200:201]
	v_pk_fma_f32 v[38:39], v[38:39], v[46:47], v[52:53]
	s_waitcnt lgkmcnt(0)
	v_lshlrev_b32_e32 v3, 16, v40
	v_pk_fma_f32 v[32:33], v[38:39], s[72:73], v[32:33] op_sel_hi:[1,0,1]
	v_cvt_pk_bf16_f32 v39, v34, v35
	v_cvt_pk_bf16_f32 v38, v32, v33
	v_and_b32_e32 v33, 0xffff0000, v40
	v_lshlrev_b32_e32 v35, 16, v41
	v_and_b32_e32 v42, 0xffff0000, v41
	global_store_dwordx2 v[44:45], v[38:39], off
	v_sub_f32_e32 v41, v33, v48
	v_sub_f32_e32 v40, v3, v48
	v_sub_f32_e32 v43, v42, v48
	v_sub_f32_e32 v42, v35, v48
	v_pk_mul_f32 v[46:47], v[50:51], v[42:43] op_sel_hi:[0,1]
	v_pk_mul_f32 v[56:57], v[50:51], v[40:41] op_sel_hi:[0,1]
	ds_read_b128 v[40:43], v244 offset:64
	ds_read_b128 v[52:55], v244 offset:320
	v_and_b32_e32 v34, 0xffff0000, v38
	v_lshlrev_b32_e32 v32, 16, v39
	s_waitcnt lgkmcnt(0)
	v_pk_fma_f32 v[40:41], v[40:41], v[56:57], v[52:53]
	s_nop 0
	v_pk_fma_f32 v[28:29], v[40:41], s[72:73], v[28:29] op_sel_hi:[1,0,1]
	s_waitcnt vmcnt(7)
	v_mov_b64_e32 v[40:41], v[202:203]
	v_pk_fma_f32 v[42:43], v[42:43], v[46:47], v[54:55]
	v_cvt_pk_bf16_f32 v46, v28, v29
	v_pk_fma_f32 v[30:31], v[42:43], s[72:73], v[30:31] op_sel_hi:[1,0,1]
	s_waitcnt lgkmcnt(0)
; __device__ __forceinline__ u32x2 pk4(f32x4 v) { u32x2 r; r.x = pk2(v.x, v.y); r.y = pk2(v.z, v.w); return r; }
;     __device__ __forceinline__ void operator()(const f32x4 (&acc)[2][2][4][2], const pg8::Unit& u, int wr, int wc, int fr, int fq) const {
;     ...
;                 for (int bj = 0; bj < 2; ++bj)
; #pragma unroll
;                     for (int n = 0; n < 2; ++n) {
;                         const int col = u.pn * 256 + bj * 128 + wc * 32 + n * 16 + fq * 4;
;                         const u32x2 raw = *(const u32x2*)(src + (size_t)row * DM + col);
;                         f32x4 x = (f32x4){bflo(raw.x), bfhi(raw.x), bflo(raw.y), bfhi(raw.y)};
;                         if (ln) x = (x - mu) * rs * *(const f32x4*)(g + col) + *(const f32x4*)(b + col);
;                         const u32x2 pz = pk4(x * ALPHA + acc[ai][bj][m][n]);
;                         *(u32x2*)(dst + (size_t)row * DM + col) = pz;
;                         const float z0 = bflo(pz.x), z1 = bfhi(pz.x), z2 = bflo(pz.y), z3 = bfhi(pz.y);
;                         s1 += (z0 + z1) + (z2 + z3); s2 += (z0 * z0 + z1 * z1) + (z2 * z2 + z3 * z3);
;                     }
;                 s1 += __shfl_xor(s1, 16); s2 += __shfl_xor(s2, 16); s1 += __shfl_xor(s1, 32); s2 += __shfl_xor(s2, 32);
;                 if (fq == 0) { float* p = stm_n + (size_t)row * 32 + (u.pn * 4 + wc) * 2; p[0] = s1; p[1] = s2; }
	v_lshlrev_b32_e32 v3, 16, v40
	v_cvt_pk_bf16_f32 v47, v30, v31
	v_lshlrev_b32_e32 v30, 16, v47
	v_and_b32_e32 v31, 0xffff0000, v47
	v_mul_f32_e32 v28, v30, v30
	v_pk_fma_f32 v[28:29], v[30:31], v[30:31], v[28:29] op_sel_hi:[1,1,0]
	v_lshlrev_b32_e32 v33, 16, v41
	v_and_b32_e32 v28, 0xffff0000, v40
	v_and_b32_e32 v35, 0xffff0000, v41
	global_store_dwordx2 v[44:45], v[46:47], off offset:32
	v_sub_f32_e32 v41, v28, v48
	v_sub_f32_e32 v40, v3, v48
	v_sub_f32_e32 v43, v35, v48
	v_sub_f32_e32 v42, v33, v48
	v_pk_mul_f32 v[56:57], v[50:51], v[42:43] op_sel_hi:[0,1]
	v_pk_mul_f32 v[58:59], v[50:51], v[40:41] op_sel_hi:[0,1]
	ds_read_b128 v[40:43], v244 offset:128
	ds_read_b128 v[52:55], v244 offset:384
	v_and_b32_e32 v47, 0xffff0000, v46
	s_waitcnt lgkmcnt(0)
	v_pk_fma_f32 v[40:41], v[40:41], v[58:59], v[52:53]
	s_waitcnt vmcnt(6)
	v_mov_b64_e32 v[52:53], v[204:205]
	v_pk_fma_f32 v[42:43], v[42:43], v[56:57], v[54:55]
	v_pk_fma_f32 v[24:25], v[40:41], s[72:73], v[24:25] op_sel_hi:[1,0,1]
	v_pk_fma_f32 v[26:27], v[42:43], s[72:73], v[26:27] op_sel_hi:[1,0,1]
	v_cvt_pk_bf16_f32 v24, v24, v25
	v_cvt_pk_bf16_f32 v25, v26, v27
	global_store_dwordx2 v[44:45], v[24:25], off offset:256
	v_lshlrev_b32_e32 v40, 16, v24
	v_and_b32_e32 v42, 0xffff0000, v24
	v_lshlrev_b32_e32 v24, 16, v25
	v_and_b32_e32 v26, 0xffff0000, v25
	v_mul_f32_e32 v41, v40, v40
	v_mul_f32_e32 v43, v42, v42
	v_mul_f32_e32 v25, v24, v24
	v_mul_f32_e32 v27, v26, v26
	v_pk_add_f32 v[24:25], v[24:25], v[26:27]
	s_waitcnt lgkmcnt(0)
	v_lshlrev_b32_e32 v3, 16, v52
	v_and_b32_e32 v28, 0xffff0000, v52
	v_lshlrev_b32_e32 v33, 16, v53
	v_and_b32_e32 v35, 0xffff0000, v53
	v_sub_f32_e32 v53, v28, v48
	v_sub_f32_e32 v52, v3, v48
	v_sub_f32_e32 v49, v35, v48
	v_sub_f32_e32 v48, v33, v48
	v_pk_mul_f32 v[48:49], v[50:51], v[48:49] op_sel_hi:[0,1]
	v_pk_mul_f32 v[50:51], v[50:51], v[52:53] op_sel_hi:[0,1]
	ds_read_b128 v[52:55], v244 offset:192
	ds_read_b128 v[56:59], v244 offset:448
	v_mov_b32_e32 v33, v47
	v_mov_b32_e32 v3, v29
	s_waitcnt lgkmcnt(0)
	v_pk_fma_f32 v[50:51], v[52:53], v[50:51], v[56:57]
	s_nop 0
	v_pk_fma_f32 v[20:21], v[50:51], s[72:73], v[20:21] op_sel_hi:[1,0,1]
	v_lshlrev_b32_e32 v51, 16, v46
	v_lshlrev_b32_e32 v50, 16, v38
	v_mov_b32_e32 v35, v51
	v_pk_fma_f32 v[48:49], v[54:55], v[48:49], v[58:59]
	v_pk_mul_f32 v[52:53], v[50:51], v[50:51]
	v_pk_mul_f32 v[54:55], v[34:35], v[34:35]
	v_and_b32_e32 v46, 0xffff0000, v39
	v_pk_mul_f32 v[38:39], v[32:33], v[32:33]
	v_pk_mul_f32 v[56:57], v[46:47], v[46:47]
	v_pk_mov_b32 v[58:59], v[50:51], v[52:53] op_sel:[1,0]
	v_pk_mov_b32 v[54:55], v[46:47], v[54:55] op_sel:[1,0]
	v_pk_add_f32 v[34:35], v[50:51], v[34:35]
	v_pk_add_f32 v[32:33], v[46:47], v[32:33]
	v_pk_fma_f32 v[22:23], v[48:49], s[72:73], v[22:23] op_sel_hi:[1,0,1]
	v_pk_add_f32 v[54:55], v[58:59], v[54:55]
	v_mov_b32_e32 v58, v30
	v_mov_b32_e32 v59, v38
	v_pk_mov_b32 v[30:31], v[30:31], v[56:57] op_sel:[1,0]
	v_mov_b32_e32 v35, v53
	v_mov_b32_e32 v33, v57
	v_cvt_pk_bf16_f32 v20, v20, v21
	v_cvt_pk_bf16_f32 v21, v22, v23
	v_pk_add_f32 v[30:31], v[58:59], v[30:31]
	v_pk_add_f32 v[32:33], v[34:35], v[32:33]
	global_store_dwordx2 v[44:45], v[20:21], off offset:288
	v_lshlrev_b32_e32 v44, 16, v20
	v_and_b32_e32 v48, 0xffff0000, v20
	v_lshlrev_b32_e32 v20, 16, v21
	v_and_b32_e32 v22, 0xffff0000, v21
	v_pk_add_f32 v[30:31], v[54:55], v[30:31]
	v_pk_add_f32 v[28:29], v[32:33], v[2:3]
	v_mul_f32_e32 v45, v44, v44
	v_mul_f32_e32 v49, v48, v48
	v_mul_f32_e32 v21, v20, v20
	v_mul_f32_e32 v23, v22, v22
	v_pk_add_f32 v[28:29], v[30:31], v[28:29]
	v_pk_add_f32 v[30:31], v[40:41], v[42:43]
	v_pk_add_f32 v[26:27], v[44:45], v[48:49]
	v_pk_add_f32 v[24:25], v[30:31], v[24:25]
	v_pk_add_f32 v[20:21], v[20:21], v[22:23]
	v_pk_add_f32 v[24:25], v[28:29], v[24:25]
	v_pk_add_f32 v[20:21], v[26:27], v[20:21]
	s_nop 0
	v_pk_add_f32 v[20:21], v[24:25], v[20:21]
	ds_bpermute_b32 v22, v181, v20
	ds_bpermute_b32 v23, v181, v21
	s_waitcnt lgkmcnt(0)
	v_pk_add_f32 v[20:21], v[20:21], v[22:23]
	ds_bpermute_b32 v22, v180, v20
	ds_bpermute_b32 v23, v180, v21
	s_and_saveexec_b64 s[0:1], s[40:41]
	s_cbranch_execz .LBB0_2217
	v_lshl_add_u64 v[24:25], s[50:51], 0, v[36:37]
	v_lshl_add_u64 v[24:25], s[60:61], 2, v[24:25]
	s_waitcnt lgkmcnt(0)
	v_pk_add_f32 v[20:21], v[20:21], v[22:23]
	global_store_dwordx2 v[24:25], v[20:21], off
; __device__ __forceinline__ u32x2 pk4(f32x4 v) { u32x2 r; r.x = pk2(v.x, v.y); r.y = pk2(v.z, v.w); return r; }
; __device__ __forceinline__ void stats_main(const float* stm, int row, int fq, float& mu, float& rs) {
;     const f32x4* p = (const f32x4*)(stm + (size_t)row * 32 + fq * 8);
;     const f32x4 a = p[0], b = p[1];
;     float s1 = (a.x + a.z) + (b.x + b.z), s2 = (a.y + a.w) + (b.y + b.w);
;     s1 += __shfl_xor(s1, 16); s2 += __shfl_xor(s2, 16); s1 += __shfl_xor(s1, 32); s2 += __shfl_xor(s2, 32);
;     mu = s1 * (1.f / DM); rs = __builtin_amdgcn_rsqf(fmaxf(s2 * (1.f / DM) - mu * mu, 0.f) + LN_EPS);
; }
;     __device__ __forceinline__ void operator()(const f32x4 (&acc)[2][2][4][2], const pg8::Unit& u, int wr, int wc, int fr, int fq) const {
;     ...
;                 const int row = u.pm * 256 + ai * 128 + wr * 64 + m * 16 + fr;
;                 float mu = 0.f, rs = 1.f; if (ln) stats_main(stm_p, row, fq, mu, rs);
;                 float s1 = 0.f, s2 = 0.f;
; #pragma unroll
;                 for (int bj = 0; bj < 2; ++bj)
; #pragma unroll
;                     for (int n = 0; n < 2; ++n) {
;                         const int col = u.pn * 256 + bj * 128 + wc * 32 + n * 16 + fq * 4;
;                         const u32x2 raw = *(const u32x2*)(src + (size_t)row * DM + col);
;                         f32x4 x = (f32x4){bflo(raw.x), bfhi(raw.x), bflo(raw.y), bfhi(raw.y)};
;                         if (ln) x = (x - mu) * rs * *(const f32x4*)(g + col) + *(const f32x4*)(b + col);
;                         const u32x2 pz = pk4(x * ALPHA + acc[ai][bj][m][n]);
;                         *(u32x2*)(dst + (size_t)row * DM + col) = pz;
.LBB0_2217:
	s_or_b64 exec, exec, s[0:1]
	v_add_u32_e32 v30, 0xb0, v146
	v_ashrrev_i32_e32 v31, 31, v30
	v_lshlrev_b64 v[20:21], 7, v[30:31]
	v_lshl_add_u64 v[26:27], v[134:135], 0, v[20:21]
	s_waitcnt lgkmcnt(0)
	s_waitcnt vmcnt(5)
	v_mov_b64_e32 v[22:23], v[206:207]
	v_mov_b64_e32 v[24:25], v[208:209]
	s_nop 0
	s_waitcnt vmcnt(4)
	v_mov_b64_e32 v[26:27], v[214:215]
	v_mov_b64_e32 v[28:29], v[216:217]
	s_waitcnt lgkmcnt(0)
	v_pk_add_f32 v[22:23], v[22:23], v[24:25]
	s_waitcnt lgkmcnt(0)
	v_pk_add_f32 v[26:27], v[26:27], v[28:29]
	s_nop 0
	v_pk_add_f32 v[22:23], v[26:27], v[22:23]
	ds_bpermute_b32 v24, v181, v22
	ds_bpermute_b32 v25, v181, v23
	s_waitcnt lgkmcnt(0)
	v_pk_add_f32 v[22:23], v[22:23], v[24:25]
	ds_bpermute_b32 v24, v180, v22
	ds_bpermute_b32 v25, v180, v23
	s_waitcnt lgkmcnt(0)
	v_pk_add_f32 v[22:23], v[22:23], v[24:25]
	s_nop 0
	v_pk_mul_f32 v[32:33], v[22:23], s[82:83] op_sel_hi:[1,0]
	v_lshlrev_b64 v[22:23], 11, v[30:31]
	v_lshl_add_u64 v[22:23], s[70:71], 0, v[22:23]
	v_lshl_add_u64 v[28:29], v[144:145], 1, v[22:23]
	s_waitcnt vmcnt(3)
	v_mov_b64_e32 v[22:23], v[234:235]
	v_fma_f32 v3, -v32, v32, v33
	v_max_f32_e32 v3, 0, v3
	v_add_f32_e32 v3, 0x3727c5ac, v3
	v_rsq_f32_e32 v34, v3
	s_waitcnt lgkmcnt(0)
	v_lshlrev_b32_e32 v3, 16, v22
	v_and_b32_e32 v22, 0xffff0000, v22
	v_lshlrev_b32_e32 v24, 16, v23
	v_and_b32_e32 v25, 0xffff0000, v23
	v_sub_f32_e32 v23, v22, v32
	v_sub_f32_e32 v22, v3, v32
	v_sub_f32_e32 v25, v25, v32
	v_sub_f32_e32 v24, v24, v32
	v_pk_mul_f32 v[26:27], v[24:25], v[34:35] op_sel_hi:[1,0]
	v_pk_mul_f32 v[30:31], v[22:23], v[34:35] op_sel_hi:[1,0]
	ds_read_b128 v[22:25], v244
	ds_read_b128 v[36:39], v244 offset:256
	s_waitcnt lgkmcnt(0)
	v_pk_fma_f32 v[24:25], v[24:25], v[26:27], v[38:39]
	s_nop 0
	v_pk_fma_f32 v[18:19], v[24:25], s[72:73], v[18:19] op_sel_hi:[1,0,1]
	s_waitcnt vmcnt(2)
	v_mov_b64_e32 v[24:25], v[236:237]
	v_pk_fma_f32 v[22:23], v[22:23], v[30:31], v[36:37]
	s_waitcnt lgkmcnt(0)
	v_lshlrev_b32_e32 v3, 16, v24
	v_pk_fma_f32 v[16:17], v[22:23], s[72:73], v[16:17] op_sel_hi:[1,0,1]
	v_cvt_pk_bf16_f32 v23, v18, v19
	v_cvt_pk_bf16_f32 v22, v16, v17
	v_and_b32_e32 v17, 0xffff0000, v24
	v_lshlrev_b32_e32 v19, 16, v25
	v_and_b32_e32 v26, 0xffff0000, v25
	global_store_dwordx2 v[28:29], v[22:23], off
	v_sub_f32_e32 v25, v17, v32
	v_sub_f32_e32 v24, v3, v32
	v_sub_f32_e32 v27, v26, v32
	v_sub_f32_e32 v26, v19, v32
	v_pk_mul_f32 v[30:31], v[34:35], v[26:27] op_sel_hi:[0,1]
	v_pk_mul_f32 v[40:41], v[34:35], v[24:25] op_sel_hi:[0,1]
	ds_read_b128 v[24:27], v244 offset:64
	ds_read_b128 v[36:39], v244 offset:320
	v_and_b32_e32 v18, 0xffff0000, v22
	v_lshlrev_b32_e32 v16, 16, v23
	s_waitcnt lgkmcnt(0)
	v_pk_fma_f32 v[24:25], v[24:25], v[40:41], v[36:37]
	s_nop 0
	v_pk_fma_f32 v[12:13], v[24:25], s[72:73], v[12:13] op_sel_hi:[1,0,1]
	s_waitcnt vmcnt(1)
	v_mov_b64_e32 v[24:25], v[238:239]
	v_pk_fma_f32 v[26:27], v[26:27], v[30:31], v[38:39]
	v_cvt_pk_bf16_f32 v30, v12, v13
	v_pk_fma_f32 v[14:15], v[26:27], s[72:73], v[14:15] op_sel_hi:[1,0,1]
	s_waitcnt lgkmcnt(0)
	v_lshlrev_b32_e32 v3, 16, v24
	v_cvt_pk_bf16_f32 v31, v14, v15
	v_lshlrev_b32_e32 v14, 16, v31
	v_and_b32_e32 v15, 0xffff0000, v31
	v_mul_f32_e32 v12, v14, v14
	v_pk_fma_f32 v[12:13], v[14:15], v[14:15], v[12:13] op_sel_hi:[1,1,0]
	v_lshlrev_b32_e32 v17, 16, v25
	v_and_b32_e32 v12, 0xffff0000, v24
	v_and_b32_e32 v19, 0xffff0000, v25
	global_store_dwordx2 v[28:29], v[30:31], off offset:32
	v_sub_f32_e32 v25, v12, v32
	v_sub_f32_e32 v24, v3, v32
	v_sub_f32_e32 v27, v19, v32
	v_sub_f32_e32 v26, v17, v32
	v_pk_mul_f32 v[40:41], v[34:35], v[26:27] op_sel_hi:[0,1]
	v_pk_mul_f32 v[42:43], v[34:35], v[24:25] op_sel_hi:[0,1]
	ds_read_b128 v[24:27], v244 offset:128
	ds_read_b128 v[36:39], v244 offset:384
	v_and_b32_e32 v31, 0xffff0000, v30
	s_waitcnt lgkmcnt(0)
; __device__ __forceinline__ u32x2 pk4(f32x4 v) { u32x2 r; r.x = pk2(v.x, v.y); r.y = pk2(v.z, v.w); return r; }
;     __device__ __forceinline__ void operator()(const f32x4 (&acc)[2][2][4][2], const pg8::Unit& u, int wr, int wc, int fr, int fq) const {
;     ...
;                 for (int bj = 0; bj < 2; ++bj)
; #pragma unroll
;                     for (int n = 0; n < 2; ++n) {
;                         const int col = u.pn * 256 + bj * 128 + wc * 32 + n * 16 + fq * 4;
;                         const u32x2 raw = *(const u32x2*)(src + (size_t)row * DM + col);
;                         f32x4 x = (f32x4){bflo(raw.x), bfhi(raw.x), bflo(raw.y), bfhi(raw.y)};
;                         if (ln) x = (x - mu) * rs * *(const f32x4*)(g + col) + *(const f32x4*)(b + col);
;                         const u32x2 pz = pk4(x * ALPHA + acc[ai][bj][m][n]);
;                         *(u32x2*)(dst + (size_t)row * DM + col) = pz;
;                         const float z0 = bflo(pz.x), z1 = bfhi(pz.x), z2 = bflo(pz.y), z3 = bfhi(pz.y);
;                         s1 += (z0 + z1) + (z2 + z3); s2 += (z0 * z0 + z1 * z1) + (z2 * z2 + z3 * z3);
;                     }
;                 s1 += __shfl_xor(s1, 16); s2 += __shfl_xor(s2, 16); s1 += __shfl_xor(s1, 32); s2 += __shfl_xor(s2, 32);
;                 if (fq == 0) { float* p = stm_n + (size_t)row * 32 + (u.pn * 4 + wc) * 2; p[0] = s1; p[1] = s2; }
	v_pk_fma_f32 v[24:25], v[24:25], v[42:43], v[36:37]
	s_waitcnt vmcnt(0)
	v_mov_b64_e32 v[36:37], v[240:241]
	v_pk_fma_f32 v[26:27], v[26:27], v[40:41], v[38:39]
	v_pk_fma_f32 v[8:9], v[24:25], s[72:73], v[8:9] op_sel_hi:[1,0,1]
	v_pk_fma_f32 v[10:11], v[26:27], s[72:73], v[10:11] op_sel_hi:[1,0,1]
	v_cvt_pk_bf16_f32 v8, v8, v9
	v_cvt_pk_bf16_f32 v9, v10, v11
	global_store_dwordx2 v[28:29], v[8:9], off offset:256
	v_lshlrev_b32_e32 v24, 16, v8
	v_and_b32_e32 v26, 0xffff0000, v8
	v_lshlrev_b32_e32 v8, 16, v9
	v_and_b32_e32 v10, 0xffff0000, v9
	v_mul_f32_e32 v25, v24, v24
	v_mul_f32_e32 v27, v26, v26
	v_mul_f32_e32 v9, v8, v8
	v_mul_f32_e32 v11, v10, v10
	v_pk_add_f32 v[8:9], v[8:9], v[10:11]
	s_waitcnt lgkmcnt(0)
	v_lshlrev_b32_e32 v3, 16, v36
	v_and_b32_e32 v12, 0xffff0000, v36
	v_lshlrev_b32_e32 v17, 16, v37
	v_and_b32_e32 v19, 0xffff0000, v37
	v_sub_f32_e32 v37, v12, v32
	v_sub_f32_e32 v36, v3, v32
	v_sub_f32_e32 v33, v19, v32
	v_sub_f32_e32 v32, v17, v32
	v_pk_mul_f32 v[32:33], v[34:35], v[32:33] op_sel_hi:[0,1]
	v_pk_mul_f32 v[34:35], v[34:35], v[36:37] op_sel_hi:[0,1]
	ds_read_b128 v[36:39], v244 offset:192
	ds_read_b128 v[40:43], v244 offset:448
	v_mov_b32_e32 v17, v31
	v_mov_b32_e32 v3, v13
	s_waitcnt lgkmcnt(0)
	v_pk_fma_f32 v[34:35], v[36:37], v[34:35], v[40:41]
	s_nop 0
	v_pk_fma_f32 v[4:5], v[34:35], s[72:73], v[4:5] op_sel_hi:[1,0,1]
	v_lshlrev_b32_e32 v35, 16, v30
	v_lshlrev_b32_e32 v34, 16, v22
	v_mov_b32_e32 v19, v35
	v_pk_fma_f32 v[32:33], v[38:39], v[32:33], v[42:43]
	v_pk_mul_f32 v[36:37], v[34:35], v[34:35]
	v_pk_mul_f32 v[38:39], v[18:19], v[18:19]
	v_and_b32_e32 v30, 0xffff0000, v23
	v_pk_mul_f32 v[22:23], v[16:17], v[16:17]
	v_pk_mul_f32 v[40:41], v[30:31], v[30:31]
	v_pk_mov_b32 v[42:43], v[34:35], v[36:37] op_sel:[1,0]
	v_pk_mov_b32 v[38:39], v[30:31], v[38:39] op_sel:[1,0]
	v_pk_add_f32 v[18:19], v[34:35], v[18:19]
	v_pk_add_f32 v[16:17], v[30:31], v[16:17]
	v_pk_fma_f32 v[6:7], v[32:33], s[72:73], v[6:7] op_sel_hi:[1,0,1]
	v_pk_add_f32 v[38:39], v[42:43], v[38:39]
	v_mov_b32_e32 v42, v14
	v_mov_b32_e32 v43, v22
	v_pk_mov_b32 v[14:15], v[14:15], v[40:41] op_sel:[1,0]
	v_mov_b32_e32 v19, v37
	v_mov_b32_e32 v17, v41
	v_cvt_pk_bf16_f32 v4, v4, v5
	v_cvt_pk_bf16_f32 v5, v6, v7
	v_pk_add_f32 v[14:15], v[42:43], v[14:15]
	v_pk_add_f32 v[16:17], v[18:19], v[16:17]
	global_store_dwordx2 v[28:29], v[4:5], off offset:288
	v_lshlrev_b32_e32 v28, 16, v4
	v_and_b32_e32 v32, 0xffff0000, v4
	v_lshlrev_b32_e32 v4, 16, v5
	v_and_b32_e32 v6, 0xffff0000, v5
	v_pk_add_f32 v[14:15], v[38:39], v[14:15]
	v_pk_add_f32 v[12:13], v[16:17], v[2:3]
	v_mul_f32_e32 v29, v28, v28
	v_mul_f32_e32 v33, v32, v32
	v_mul_f32_e32 v5, v4, v4
	v_mul_f32_e32 v7, v6, v6
	v_pk_add_f32 v[12:13], v[14:15], v[12:13]
	v_pk_add_f32 v[14:15], v[24:25], v[26:27]
	v_pk_add_f32 v[10:11], v[28:29], v[32:33]
	v_pk_add_f32 v[8:9], v[14:15], v[8:9]
	v_pk_add_f32 v[4:5], v[4:5], v[6:7]
	v_pk_add_f32 v[8:9], v[12:13], v[8:9]
	v_pk_add_f32 v[4:5], v[10:11], v[4:5]
	s_nop 0
	v_pk_add_f32 v[4:5], v[8:9], v[4:5]
	ds_bpermute_b32 v6, v181, v4
	ds_bpermute_b32 v7, v181, v5
	s_waitcnt lgkmcnt(0)
	v_pk_add_f32 v[4:5], v[4:5], v[6:7]
	ds_bpermute_b32 v6, v180, v4
	ds_bpermute_b32 v7, v180, v5
	s_and_saveexec_b64 s[0:1], s[40:41]
	s_cbranch_execz .LBB0_2219
	v_lshl_add_u64 v[8:9], s[50:51], 0, v[20:21]
	v_lshl_add_u64 v[8:9], s[60:61], 2, v[8:9]
	s_waitcnt lgkmcnt(0)
	v_pk_add_f32 v[4:5], v[4:5], v[6:7]
	global_store_dwordx2 v[8:9], v[4:5], off

; __device__ __forceinline__ u32x2 pk4(f32x4 v) { u32x2 r; r.x = pk2(v.x, v.y); r.y = pk2(v.z, v.w); return r; }
;     __device__ __forceinline__ void operator()(int row, int col, f32x4 v, int, float&, float&) const { *(u32x2*)(O + (size_t)row * ldc + col) = pk4(v * s); }
; __device__ __forceinline__ void stats_main(const float* stm, int row, int fq, float& mu, float& rs) {
;     const f32x4* p = (const f32x4*)(stm + (size_t)row * 32 + fq * 8);
;     const f32x4 a = p[0], b = p[1];
;     float s1 = (a.x + a.z) + (b.x + b.z), s2 = (a.y + a.w) + (b.y + b.w);
;     s1 += __shfl_xor(s1, 16); s2 += __shfl_xor(s2, 16); s1 += __shfl_xor(s1, 32); s2 += __shfl_xor(s2, 32);
;     mu = s1 * (1.f / DM); rs = __builtin_amdgcn_rsqf(fmaxf(s2 * (1.f / DM) - mu * mu, 0.f) + LN_EPS);
; }
;     __device__ __forceinline__ void operator()(const f32x4 (&acc)[2][2][4][2], const pg8::Unit& u, int wr, int wc, int fr, int fq) const {
; #pragma unroll
;         for (int ai = 0; ai < 2; ++ai)
; #pragma unroll
;             for (int m = 0; m < 4; ++m) {
;                 const int row = u.pm * 256 + ai * 128 + wr * 64 + m * 16 + fr;
;                 float mu = 0.f, rs = 1.f; if (ln) stats_main(stm_p, row, fq, mu, rs);
;                 float s1 = 0.f, s2 = 0.f;
; #pragma unroll
;                 for (int bj = 0; bj < 2; ++bj)
; #pragma unroll
;                     for (int n = 0; n < 2; ++n) {
;                         const int col = u.pn * 256 + bj * 128 + wc * 32 + n * 16 + fq * 4;
;                         const u32x2 raw = *(const u32x2*)(src + (size_t)row * DM + col);
;                         f32x4 x = (f32x4){bflo(raw.x), bfhi(raw.x), bflo(raw.y), bfhi(raw.y)};
;                         if (ln) x = (x - mu) * rs * *(const f32x4*)(g + col) + *(const f32x4*)(b + col);
;                         const u32x2 pz = pk4(x * ALPHA + acc[ai][bj][m][n]);
;                         *(u32x2*)(dst + (size_t)row * DM + col) = pz;
.LBB0_2377:
	v_readlane_b32 s70, v250, 30
	v_readlane_b32 s71, v250, 31
	v_and_b32_e32 v244, 0xfffffff0, v166
	v_lshl_add_u32 v244, s22, 8, v244
	v_and_b32_e32 v245, 31, v219
	v_add_u32_e32 v244, v244, v245
	v_lshrrev_b32_e32 v245, 5, v219
	v_lshl_add_u32 v244, v245, 7, v244
	v_lshlrev_b32_e32 v244, 2, v244
	global_load_dword v214, v244, s[46:47]
	global_load_dword v215, v244, s[48:49]
	v_lshl_add_u32 v245, s23, 8, v164
	v_lshl_add_u32 v244, s22, 8, v166
	v_lshlrev_b32_e32 v242, 11, v245
	v_lshl_add_u32 v242, v244, 1, v242
	v_lshlrev_b32_e32 v246, 7, v245
	v_mov_b32_e32 v247, 0
	v_lshlrev_b32_e32 v248, 7, v245
	v_mov_b32_e32 v249, 0
	v_add_u32_e32 v246, 0x1000, v246
	v_add_u32_e32 v248, 0x5000, v248
	v_lshl_add_u64 v[246:247], v[246:247], 0, v[134:135]
	v_lshl_add_u64 v[248:249], v[248:249], 0, v[134:135]
	global_load_dwordx4 v[190:193], v[246:247], off offset:-4080
	global_load_dwordx4 v[194:197], v[246:247], off offset:-4096
	global_load_dwordx2 v[198:199], v242, s[70:71]
	global_load_dwordx2 v[200:201], v242, s[70:71] offset:32
	global_load_dwordx2 v[202:203], v242, s[70:71] offset:256
	global_load_dwordx2 v[204:205], v242, s[70:71] offset:288
	v_lshrrev_b32_e32 v245, 6, v164
	v_lshrrev_b32_e32 v244, 5, v166
	v_lshl_add_u32 v245, v245, 2, v244
	v_lshlrev_b32_e32 v245, 9, v245
	v_and_b32_e32 v244, 12, v166
	v_lshl_add_u32 v244, v244, 2, v245
	v_add_u32_e32 v244, 0x20000, v244
	v_lshl_add_u32 v245, v219, 2, v245
	v_add_u32_e32 v245, 0x20000, v245
	s_waitcnt vmcnt(7)
	ds_write_b32 v245, v214
	s_waitcnt vmcnt(6)
	ds_write_b32 v245, v215 offset:256
	v_add_u32_e32 v243, 0x8000, v242
	global_load_dwordx4 v[206:209], v[246:247], off offset:-2032
	global_load_dwordx4 v[214:217], v[246:247], off offset:-2048
	global_load_dwordx2 v[234:235], v243, s[70:71]
	global_load_dwordx2 v[236:237], v243, s[70:71] offset:32
	global_load_dwordx2 v[238:239], v243, s[70:71] offset:256
	global_load_dwordx2 v[240:241], v243, s[70:71] offset:288
	s_waitcnt lgkmcnt(0)
	v_and_b32_e32 v140, 64, v219
	v_lshl_add_u32 v146, s23, 8, v164
	v_xor_b32_e32 v3, 16, v219
	v_add_u32_e32 v140, 64, v140
	v_cmp_lt_i32_e32 vcc, v3, v140
	v_ashrrev_i32_e32 v147, 31, v146
	v_lshlrev_b64 v[148:149], 7, v[146:147]
	v_cndmask_b32_e32 v3, v219, v3, vcc
	v_lshlrev_b32_e32 v181, 2, v3
	v_xor_b32_e32 v3, 32, v219
	v_lshl_add_u64 v[150:151], v[134:135], 0, v[148:149]
	v_cmp_lt_i32_e32 vcc, v3, v140
	s_waitcnt vmcnt(11)
	v_mov_b64_e32 v[140:141], v[190:191]
	v_mov_b64_e32 v[142:143], v[192:193]
	global_load_dwordx4 v[190:193], v[246:247], off offset:16
	s_nop 0
	s_waitcnt vmcnt(11)
	v_mov_b64_e32 v[150:151], v[194:195]
	v_mov_b64_e32 v[152:153], v[196:197]
	global_load_dwordx4 v[194:197], v[246:247], off
	v_cndmask_b32_e32 v3, v219, v3, vcc
	v_lshlrev_b32_e32 v180, 2, v3
	v_readlane_b32 s70, v250, 30
	v_lshl_add_u32 v144, s22, 8, v166
	v_readlane_b32 s71, v250, 31
	v_ashrrev_i32_e32 v145, 31, v144
	s_lshl_b32 s0, s22, 3
	v_readlane_b32 s1, v252, 30
	s_or_b32 s68, s0, s1
	s_ashr_i32 s69, s68, 31
	s_waitcnt lgkmcnt(0)
	v_pk_add_f32 v[140:141], v[140:141], v[142:143]
	v_pk_add_f32 v[150:151], v[150:151], v[152:153]
	s_nop 0
	v_pk_add_f32 v[140:141], v[150:151], v[140:141]
	ds_bpermute_b32 v142, v181, v140
	ds_bpermute_b32 v143, v181, v141
	s_waitcnt lgkmcnt(0)
	v_pk_add_f32 v[140:141], v[140:141], v[142:143]
	ds_bpermute_b32 v142, v180, v140
	ds_bpermute_b32 v143, v180, v141
	s_waitcnt lgkmcnt(0)
	v_pk_add_f32 v[140:141], v[140:141], v[142:143]
	s_nop 0
	v_pk_mul_f32 v[160:161], v[140:141], s[82:83] op_sel_hi:[1,0]
	v_lshlrev_b64 v[140:141], 11, v[146:147]
	v_lshl_add_u64 v[140:141], s[70:71], 0, v[140:141]
	v_lshl_add_u64 v[152:153], v[144:145], 1, v[140:141]
	v_add_u32_e32 v243, 0x10000, v242
	s_waitcnt vmcnt(11)
	v_mov_b64_e32 v[140:141], v[198:199]
	global_load_dwordx2 v[198:199], v243, s[70:71]
	v_fma_f32 v3, -v160, v160, v161
	v_max_f32_e32 v3, 0, v3
	v_add_f32_e32 v3, 0x3727c5ac, v3
	v_rsq_f32_e32 v162, v3
	s_waitcnt lgkmcnt(0)
	v_lshlrev_b32_e32 v142, 16, v141
	v_and_b32_e32 v143, 0xffff0000, v141
	v_lshlrev_b32_e32 v3, 16, v140
	v_and_b32_e32 v140, 0xffff0000, v140
	v_sub_f32_e32 v143, v143, v160
	v_sub_f32_e32 v142, v142, v160
	v_sub_f32_e32 v141, v140, v160
	v_sub_f32_e32 v140, v3, v160
	v_pk_mul_f32 v[150:151], v[142:143], v[162:163] op_sel_hi:[1,0]
	v_lshlrev_b64 v[142:143], 2, v[144:145]
	v_pk_mul_f32 v[158:159], v[140:141], v[162:163] op_sel_hi:[1,0]
	v_lshl_add_u64 v[140:141], s[46:47], 0, v[142:143]
	v_lshl_add_u64 v[142:143], s[48:49], 0, v[142:143]
	ds_read_b128 v[154:157], v244
	ds_read_b128 v[182:185], v244 offset:256
	s_waitcnt lgkmcnt(0)
	v_pk_fma_f32 v[154:155], v[154:155], v[158:159], v[182:183]
	s_nop 0
	v_pk_fma_f32 v[128:129], v[154:155], s[72:73], v[128:129] op_sel_hi:[1,0,1]
	s_waitcnt vmcnt(11)
	v_mov_b64_e32 v[154:155], v[200:201]
	global_load_dwordx2 v[200:201], v243, s[70:71] offset:32
	v_pk_fma_f32 v[150:151], v[156:157], v[150:151], v[184:185]
	s_waitcnt lgkmcnt(0)
	v_lshlrev_b32_e32 v3, 16, v154
	v_pk_fma_f32 v[130:131], v[150:151], s[72:73], v[130:131] op_sel_hi:[1,0,1]
	v_cvt_pk_bf16_f32 v150, v128, v129
	v_cvt_pk_bf16_f32 v151, v130, v131
	v_and_b32_e32 v129, 0xffff0000, v154
	v_lshlrev_b32_e32 v131, 16, v155
	v_and_b32_e32 v147, 0xffff0000, v155
	global_store_dwordx2 v[152:153], v[150:151], off
	v_sub_f32_e32 v155, v129, v160
	v_sub_f32_e32 v154, v3, v160
	v_sub_f32_e32 v157, v147, v160
	v_sub_f32_e32 v156, v131, v160
	v_pk_mul_f32 v[158:159], v[162:163], v[156:157] op_sel_hi:[0,1]
	v_pk_mul_f32 v[168:169], v[162:163], v[154:155] op_sel_hi:[0,1]
	ds_read_b128 v[154:157], v244 offset:64
	ds_read_b128 v[182:185], v244 offset:320
	v_and_b32_e32 v130, 0xffff0000, v150
	v_lshlrev_b32_e32 v128, 16, v151
	s_waitcnt lgkmcnt(0)
; __device__ __forceinline__ u32x2 pk4(f32x4 v) { u32x2 r; r.x = pk2(v.x, v.y); r.y = pk2(v.z, v.w); return r; }
;     __device__ __forceinline__ void operator()(const f32x4 (&acc)[2][2][4][2], const pg8::Unit& u, int wr, int wc, int fr, int fq) const {
;     ...
;                 for (int bj = 0; bj < 2; ++bj)
; #pragma unroll
;                     for (int n = 0; n < 2; ++n) {
;                         const int col = u.pn * 256 + bj * 128 + wc * 32 + n * 16 + fq * 4;
;                         const u32x2 raw = *(const u32x2*)(src + (size_t)row * DM + col);
;                         f32x4 x = (f32x4){bflo(raw.x), bfhi(raw.x), bflo(raw.y), bfhi(raw.y)};
;                         if (ln) x = (x - mu) * rs * *(const f32x4*)(g + col) + *(const f32x4*)(b + col);
;                         const u32x2 pz = pk4(x * ALPHA + acc[ai][bj][m][n]);
;                         *(u32x2*)(dst + (size_t)row * DM + col) = pz;
;                         const float z0 = bflo(pz.x), z1 = bfhi(pz.x), z2 = bflo(pz.y), z3 = bfhi(pz.y);
;                         s1 += (z0 + z1) + (z2 + z3); s2 += (z0 * z0 + z1 * z1) + (z2 * z2 + z3 * z3);
;                     }
;                 s1 += __shfl_xor(s1, 16); s2 += __shfl_xor(s2, 16); s1 += __shfl_xor(s1, 32); s2 += __shfl_xor(s2, 32);
;                 if (fq == 0) { float* p = stm_n + (size_t)row * 32 + (u.pn * 4 + wc) * 2; p[0] = s1; p[1] = s2; }
	v_pk_fma_f32 v[154:155], v[154:155], v[168:169], v[182:183]
	s_nop 0
	v_pk_fma_f32 v[124:125], v[154:155], s[72:73], v[124:125] op_sel_hi:[1,0,1]
	s_waitcnt vmcnt(11)
	v_mov_b64_e32 v[154:155], v[202:203]
	global_load_dwordx2 v[202:203], v243, s[70:71] offset:256
	v_pk_fma_f32 v[156:157], v[156:157], v[158:159], v[184:185]
	v_cvt_pk_bf16_f32 v158, v124, v125
	v_pk_fma_f32 v[126:127], v[156:157], s[72:73], v[126:127] op_sel_hi:[1,0,1]
	s_waitcnt lgkmcnt(0)
	v_lshlrev_b32_e32 v3, 16, v154
	v_cvt_pk_bf16_f32 v159, v126, v127
	v_lshlrev_b32_e32 v126, 16, v159
	v_and_b32_e32 v127, 0xffff0000, v159
	v_mul_f32_e32 v124, v126, v126
	v_pk_fma_f32 v[124:125], v[126:127], v[126:127], v[124:125] op_sel_hi:[1,1,0]
	v_lshlrev_b32_e32 v129, 16, v155
	v_and_b32_e32 v124, 0xffff0000, v154
	v_and_b32_e32 v131, 0xffff0000, v155
	global_store_dwordx2 v[152:153], v[158:159], off offset:32
	v_sub_f32_e32 v155, v124, v160
	v_sub_f32_e32 v154, v3, v160
	v_sub_f32_e32 v157, v131, v160
	v_sub_f32_e32 v156, v129, v160
	v_pk_mul_f32 v[168:169], v[162:163], v[156:157] op_sel_hi:[0,1]
	v_pk_mul_f32 v[186:187], v[162:163], v[154:155] op_sel_hi:[0,1]
	ds_read_b128 v[154:157], v244 offset:128
	ds_read_b128 v[182:185], v244 offset:384
	v_and_b32_e32 v159, 0xffff0000, v158
	s_waitcnt lgkmcnt(0)
	v_pk_fma_f32 v[154:155], v[154:155], v[186:187], v[182:183]
	v_pk_fma_f32 v[156:157], v[156:157], v[168:169], v[184:185]
	v_pk_fma_f32 v[120:121], v[154:155], s[72:73], v[120:121] op_sel_hi:[1,0,1]
	v_pk_fma_f32 v[122:123], v[156:157], s[72:73], v[122:123] op_sel_hi:[1,0,1]
	s_waitcnt vmcnt(11)
	v_mov_b64_e32 v[168:169], v[204:205]
	global_load_dwordx2 v[204:205], v243, s[70:71] offset:288
	v_cvt_pk_bf16_f32 v120, v120, v121
	v_cvt_pk_bf16_f32 v121, v122, v123
	global_store_dwordx2 v[152:153], v[120:121], off offset:256
	ds_read_b128 v[182:185], v244 offset:192
	ds_read_b128 v[186:189], v244 offset:448
	v_lshlrev_b32_e32 v154, 16, v120
	v_and_b32_e32 v156, 0xffff0000, v120
	v_lshlrev_b32_e32 v120, 16, v121
	v_and_b32_e32 v122, 0xffff0000, v121
	v_mul_f32_e32 v155, v154, v154
	v_mul_f32_e32 v157, v156, v156
	v_mul_f32_e32 v121, v120, v120
	v_mul_f32_e32 v123, v122, v122
	v_pk_add_f32 v[120:121], v[120:121], v[122:123]
	s_waitcnt lgkmcnt(0)
	v_lshlrev_b32_e32 v3, 16, v168
	v_and_b32_e32 v124, 0xffff0000, v168
	v_lshlrev_b32_e32 v129, 16, v169
	v_and_b32_e32 v131, 0xffff0000, v169
	v_sub_f32_e32 v169, v124, v160
	v_sub_f32_e32 v168, v3, v160
	v_sub_f32_e32 v161, v131, v160
	v_sub_f32_e32 v160, v129, v160
	v_pk_mul_f32 v[160:161], v[162:163], v[160:161] op_sel_hi:[0,1]
	v_pk_mul_f32 v[162:163], v[162:163], v[168:169] op_sel_hi:[0,1]
	s_waitcnt lgkmcnt(0)
	v_pk_fma_f32 v[162:163], v[182:183], v[162:163], v[186:187]
	v_mov_b32_e32 v129, v159
	v_pk_fma_f32 v[116:117], v[162:163], s[72:73], v[116:117] op_sel_hi:[1,0,1]
	v_lshlrev_b32_e32 v163, 16, v158
	v_lshlrev_b32_e32 v162, 16, v150
	v_mov_b32_e32 v131, v163
	v_pk_mul_f32 v[168:169], v[162:163], v[162:163]
	v_pk_mul_f32 v[182:183], v[130:131], v[130:131]
	v_and_b32_e32 v158, 0xffff0000, v151
	v_pk_fma_f32 v[160:161], v[184:185], v[160:161], v[188:189]
	v_pk_mul_f32 v[150:151], v[128:129], v[128:129]
	v_pk_mul_f32 v[184:185], v[158:159], v[158:159]
	v_pk_mov_b32 v[186:187], v[162:163], v[168:169] op_sel:[1,0]
	v_pk_mov_b32 v[182:183], v[158:159], v[182:183] op_sel:[1,0]
	v_pk_add_f32 v[130:131], v[162:163], v[130:131]
	v_pk_add_f32 v[128:129], v[158:159], v[128:129]
	v_pk_fma_f32 v[118:119], v[160:161], s[72:73], v[118:119] op_sel_hi:[1,0,1]
	v_pk_add_f32 v[182:183], v[186:187], v[182:183]
	v_mov_b32_e32 v186, v126
	v_mov_b32_e32 v187, v150
	v_pk_mov_b32 v[126:127], v[126:127], v[184:185] op_sel:[1,0]
	v_mov_b32_e32 v131, v169
	v_mov_b32_e32 v129, v185
	v_cvt_pk_bf16_f32 v116, v116, v117
	v_cvt_pk_bf16_f32 v117, v118, v119
	v_pk_add_f32 v[126:127], v[186:187], v[126:127]
	v_pk_add_f32 v[128:129], v[130:131], v[128:129]
	v_mov_b32_e32 v3, v125
	global_store_dwordx2 v[152:153], v[116:117], off offset:288
	v_lshlrev_b32_e32 v152, 16, v116
	v_and_b32_e32 v160, 0xffff0000, v116
	v_lshlrev_b32_e32 v116, 16, v117
	v_and_b32_e32 v118, 0xffff0000, v117
	v_pk_add_f32 v[126:127], v[182:183], v[126:127]
	v_pk_add_f32 v[124:125], v[128:129], v[2:3]
	v_mul_f32_e32 v153, v152, v152
	v_mul_f32_e32 v161, v160, v160
	v_mul_f32_e32 v117, v116, v116
	v_mul_f32_e32 v119, v118, v118
	v_pk_add_f32 v[124:125], v[126:127], v[124:125]
	v_pk_add_f32 v[126:127], v[154:155], v[156:157]
	v_pk_add_f32 v[122:123], v[152:153], v[160:161]
	v_pk_add_f32 v[120:121], v[126:127], v[120:121]
	v_pk_add_f32 v[116:117], v[116:117], v[118:119]
	v_pk_add_f32 v[120:121], v[124:125], v[120:121]
	v_pk_add_f32 v[116:117], v[122:123], v[116:117]
	s_nop 0
	v_pk_add_f32 v[116:117], v[120:121], v[116:117]
	ds_bpermute_b32 v118, v181, v116
	ds_bpermute_b32 v119, v181, v117
	s_waitcnt lgkmcnt(0)
	v_pk_add_f32 v[116:117], v[116:117], v[118:119]
	ds_bpermute_b32 v118, v180, v116
	ds_bpermute_b32 v119, v180, v117
	s_and_saveexec_b64 s[0:1], s[40:41]
	s_cbranch_execz .LBB0_2379
	v_lshl_add_u64 v[120:121], s[52:53], 0, v[148:149]
	v_lshl_add_u64 v[120:121], s[68:69], 2, v[120:121]
	s_waitcnt lgkmcnt(0)
	v_pk_add_f32 v[116:117], v[116:117], v[118:119]
	global_store_dwordx2 v[120:121], v[116:117], off
; __device__ __forceinline__ u32x2 pk4(f32x4 v) { u32x2 r; r.x = pk2(v.x, v.y); r.y = pk2(v.z, v.w); return r; }
; __device__ __forceinline__ void stats_main(const float* stm, int row, int fq, float& mu, float& rs) {
;     const f32x4* p = (const f32x4*)(stm + (size_t)row * 32 + fq * 8);
;     const f32x4 a = p[0], b = p[1];
;     float s1 = (a.x + a.z) + (b.x + b.z), s2 = (a.y + a.w) + (b.y + b.w);
;     s1 += __shfl_xor(s1, 16); s2 += __shfl_xor(s2, 16); s1 += __shfl_xor(s1, 32); s2 += __shfl_xor(s2, 32);
;     mu = s1 * (1.f / DM); rs = __builtin_amdgcn_rsqf(fmaxf(s2 * (1.f / DM) - mu * mu, 0.f) + LN_EPS);
; }
;     __device__ __forceinline__ void operator()(const f32x4 (&acc)[2][2][4][2], const pg8::Unit& u, int wr, int wc, int fr, int fq) const {
;     ...
;                 const int row = u.pm * 256 + ai * 128 + wr * 64 + m * 16 + fr;
;                 float mu = 0.f, rs = 1.f; if (ln) stats_main(stm_p, row, fq, mu, rs);
;                 float s1 = 0.f, s2 = 0.f;
; #pragma unroll
;                 for (int bj = 0; bj < 2; ++bj)
; #pragma unroll
;                     for (int n = 0; n < 2; ++n) {
;                         const int col = u.pn * 256 + bj * 128 + wc * 32 + n * 16 + fq * 4;
;                         const u32x2 raw = *(const u32x2*)(src + (size_t)row * DM + col);
;                         f32x4 x = (f32x4){bflo(raw.x), bfhi(raw.x), bflo(raw.y), bfhi(raw.y)};
;                         if (ln) x = (x - mu) * rs * *(const f32x4*)(g + col) + *(const f32x4*)(b + col);
;                         const u32x2 pz = pk4(x * ALPHA + acc[ai][bj][m][n]);
;                         *(u32x2*)(dst + (size_t)row * DM + col) = pz;
;                         const float z0 = bflo(pz.x), z1 = bfhi(pz.x), z2 = bflo(pz.y), z3 = bfhi(pz.y);
;                         s1 += (z0 + z1) + (z2 + z3); s2 += (z0 * z0 + z1 * z1) + (z2 * z2 + z3 * z3);
;                     }
;                 s1 += __shfl_xor(s1, 16); s2 += __shfl_xor(s2, 16); s1 += __shfl_xor(s1, 32); s2 += __shfl_xor(s2, 32);
;                 if (fq == 0) { float* p = stm_n + (size_t)row * 32 + (u.pn * 4 + wc) * 2; p[0] = s1; p[1] = s2; }
.LBB0_2379:
	s_or_b64 exec, exec, s[0:1]
	v_or_b32_e32 v126, 16, v146
	v_ashrrev_i32_e32 v127, 31, v126
	v_lshlrev_b64 v[116:117], 7, v[126:127]
	v_lshl_add_u64 v[122:123], v[134:135], 0, v[116:117]
	s_waitcnt lgkmcnt(0)
	s_waitcnt vmcnt(11)
	v_mov_b64_e32 v[118:119], v[206:207]
	v_mov_b64_e32 v[120:121], v[208:209]
	global_load_dwordx4 v[206:209], v[246:247], off offset:2064
	s_nop 0
	s_waitcnt vmcnt(11)
	v_mov_b64_e32 v[122:123], v[214:215]
	v_mov_b64_e32 v[124:125], v[216:217]
	global_load_dwordx4 v[214:217], v[246:247], off offset:2048
	s_waitcnt lgkmcnt(0)
	v_pk_add_f32 v[118:119], v[118:119], v[120:121]
	s_waitcnt lgkmcnt(0)
	v_pk_add_f32 v[122:123], v[122:123], v[124:125]
	s_nop 0
	v_pk_add_f32 v[118:119], v[122:123], v[118:119]
	ds_bpermute_b32 v120, v181, v118
	ds_bpermute_b32 v121, v181, v119
	s_waitcnt lgkmcnt(0)
	v_pk_add_f32 v[118:119], v[118:119], v[120:121]
	ds_bpermute_b32 v120, v180, v118
	ds_bpermute_b32 v121, v180, v119
	s_waitcnt lgkmcnt(0)
	v_pk_add_f32 v[118:119], v[118:119], v[120:121]
	s_nop 0
	v_pk_mul_f32 v[128:129], v[118:119], s[82:83] op_sel_hi:[1,0]
	v_lshlrev_b64 v[118:119], 11, v[126:127]
	v_lshl_add_u64 v[118:119], s[70:71], 0, v[118:119]
	v_lshl_add_u64 v[124:125], v[144:145], 1, v[118:119]
	v_add_u32_e32 v243, 0x18000, v242
	s_waitcnt vmcnt(11)
	v_mov_b64_e32 v[118:119], v[234:235]
	global_load_dwordx2 v[234:235], v243, s[70:71]
	v_fma_f32 v3, -v128, v128, v129
	v_max_f32_e32 v3, 0, v3
	v_add_f32_e32 v3, 0x3727c5ac, v3
	v_rsq_f32_e32 v130, v3
	s_waitcnt lgkmcnt(0)
	v_lshlrev_b32_e32 v3, 16, v118
	v_and_b32_e32 v118, 0xffff0000, v118
	v_lshlrev_b32_e32 v120, 16, v119
	v_and_b32_e32 v121, 0xffff0000, v119
	v_sub_f32_e32 v119, v118, v128
	v_sub_f32_e32 v118, v3, v128
	v_sub_f32_e32 v121, v121, v128
	v_sub_f32_e32 v120, v120, v128
	v_pk_mul_f32 v[122:123], v[120:121], v[130:131] op_sel_hi:[1,0]
	v_pk_mul_f32 v[126:127], v[118:119], v[130:131] op_sel_hi:[1,0]
	ds_read_b128 v[118:121], v244
	ds_read_b128 v[148:151], v244 offset:256
	s_waitcnt lgkmcnt(0)
	v_pk_fma_f32 v[120:121], v[120:121], v[122:123], v[150:151]
	s_nop 0
	v_pk_fma_f32 v[114:115], v[120:121], s[72:73], v[114:115] op_sel_hi:[1,0,1]
	s_waitcnt vmcnt(11)
	v_mov_b64_e32 v[120:121], v[236:237]
	global_load_dwordx2 v[236:237], v243, s[70:71] offset:32
	v_pk_fma_f32 v[118:119], v[118:119], v[126:127], v[148:149]
	s_waitcnt lgkmcnt(0)
	v_lshlrev_b32_e32 v3, 16, v120
	v_pk_fma_f32 v[112:113], v[118:119], s[72:73], v[112:113] op_sel_hi:[1,0,1]
	v_cvt_pk_bf16_f32 v119, v114, v115
	v_cvt_pk_bf16_f32 v118, v112, v113
	v_and_b32_e32 v113, 0xffff0000, v120
	v_lshlrev_b32_e32 v115, 16, v121
	v_and_b32_e32 v122, 0xffff0000, v121
	global_store_dwordx2 v[124:125], v[118:119], off
	v_sub_f32_e32 v121, v113, v128
	v_sub_f32_e32 v120, v3, v128
	v_sub_f32_e32 v123, v122, v128
	v_sub_f32_e32 v122, v115, v128
	v_pk_mul_f32 v[126:127], v[130:131], v[122:123] op_sel_hi:[0,1]
	v_pk_mul_f32 v[152:153], v[130:131], v[120:121] op_sel_hi:[0,1]
	ds_read_b128 v[120:123], v244 offset:64
	ds_read_b128 v[148:151], v244 offset:320
	v_and_b32_e32 v114, 0xffff0000, v118
	v_lshlrev_b32_e32 v112, 16, v119
	s_waitcnt lgkmcnt(0)
	v_pk_fma_f32 v[120:121], v[120:121], v[152:153], v[148:149]
	s_nop 0
	v_pk_fma_f32 v[108:109], v[120:121], s[72:73], v[108:109] op_sel_hi:[1,0,1]
	s_waitcnt vmcnt(11)
	v_mov_b64_e32 v[120:121], v[238:239]
	global_load_dwordx2 v[238:239], v243, s[70:71] offset:256
	v_pk_fma_f32 v[122:123], v[122:123], v[126:127], v[150:151]
	v_cvt_pk_bf16_f32 v126, v108, v109
	v_pk_fma_f32 v[110:111], v[122:123], s[72:73], v[110:111] op_sel_hi:[1,0,1]
	s_waitcnt lgkmcnt(0)
	v_lshlrev_b32_e32 v3, 16, v120
	v_cvt_pk_bf16_f32 v127, v110, v111
	v_lshlrev_b32_e32 v110, 16, v127
	v_and_b32_e32 v111, 0xffff0000, v127
	v_mul_f32_e32 v108, v110, v110
	v_pk_fma_f32 v[108:109], v[110:111], v[110:111], v[108:109] op_sel_hi:[1,1,0]
	v_lshlrev_b32_e32 v113, 16, v121
	v_and_b32_e32 v108, 0xffff0000, v120
	v_and_b32_e32 v115, 0xffff0000, v121
	global_store_dwordx2 v[124:125], v[126:127], off offset:32
	v_sub_f32_e32 v121, v108, v128
	v_sub_f32_e32 v120, v3, v128
	v_sub_f32_e32 v123, v115, v128
	v_sub_f32_e32 v122, v113, v128
	v_pk_mul_f32 v[152:153], v[130:131], v[122:123] op_sel_hi:[0,1]
	v_pk_mul_f32 v[154:155], v[130:131], v[120:121] op_sel_hi:[0,1]
	ds_read_b128 v[120:123], v244 offset:128
	ds_read_b128 v[148:151], v244 offset:384
	v_and_b32_e32 v127, 0xffff0000, v126
	s_waitcnt lgkmcnt(0)
	v_pk_fma_f32 v[120:121], v[120:121], v[154:155], v[148:149]
	s_waitcnt vmcnt(11)
	v_mov_b64_e32 v[148:149], v[240:241]
	global_load_dwordx2 v[240:241], v243, s[70:71] offset:288
	v_pk_fma_f32 v[122:123], v[122:123], v[152:153], v[150:151]
	v_pk_fma_f32 v[104:105], v[120:121], s[72:73], v[104:105] op_sel_hi:[1,0,1]
	v_pk_fma_f32 v[106:107], v[122:123], s[72:73], v[106:107] op_sel_hi:[1,0,1]
	v_cvt_pk_bf16_f32 v104, v104, v105
	v_cvt_pk_bf16_f32 v105, v106, v107
	global_store_dwordx2 v[124:125], v[104:105], off offset:256
	v_lshlrev_b32_e32 v120, 16, v104
	v_and_b32_e32 v122, 0xffff0000, v104
	v_lshlrev_b32_e32 v104, 16, v105
	v_and_b32_e32 v106, 0xffff0000, v105
	v_mul_f32_e32 v121, v120, v120
	v_mul_f32_e32 v123, v122, v122
	v_mul_f32_e32 v105, v104, v104
	v_mul_f32_e32 v107, v106, v106
	v_pk_add_f32 v[104:105], v[104:105], v[106:107]
	s_waitcnt lgkmcnt(0)
	v_lshlrev_b32_e32 v3, 16, v148
	v_and_b32_e32 v108, 0xffff0000, v148
	v_lshlrev_b32_e32 v113, 16, v149
	v_and_b32_e32 v115, 0xffff0000, v149
	v_sub_f32_e32 v149, v108, v128
	v_sub_f32_e32 v148, v3, v128
	v_sub_f32_e32 v129, v115, v128
	v_sub_f32_e32 v128, v113, v128
	v_pk_mul_f32 v[128:129], v[130:131], v[128:129] op_sel_hi:[0,1]
	v_pk_mul_f32 v[130:131], v[130:131], v[148:149] op_sel_hi:[0,1]
	ds_read_b128 v[148:151], v244 offset:192
	ds_read_b128 v[152:155], v244 offset:448
	v_mov_b32_e32 v113, v127
	v_mov_b32_e32 v3, v109
	s_waitcnt lgkmcnt(0)
; __device__ __forceinline__ u32x2 pk4(f32x4 v) { u32x2 r; r.x = pk2(v.x, v.y); r.y = pk2(v.z, v.w); return r; }
; __device__ __forceinline__ void stats_main(const float* stm, int row, int fq, float& mu, float& rs) {
;     const f32x4* p = (const f32x4*)(stm + (size_t)row * 32 + fq * 8);
;     const f32x4 a = p[0], b = p[1];
;     float s1 = (a.x + a.z) + (b.x + b.z), s2 = (a.y + a.w) + (b.y + b.w);
;     s1 += __shfl_xor(s1, 16); s2 += __shfl_xor(s2, 16); s1 += __shfl_xor(s1, 32); s2 += __shfl_xor(s2, 32);
;     mu = s1 * (1.f / DM); rs = __builtin_amdgcn_rsqf(fmaxf(s2 * (1.f / DM) - mu * mu, 0.f) + LN_EPS);
; }
;     __device__ __forceinline__ void operator()(const f32x4 (&acc)[2][2][4][2], const pg8::Unit& u, int wr, int wc, int fr, int fq) const {
;     ...
;                 for (int bj = 0; bj < 2; ++bj)
; #pragma unroll
;                     for (int n = 0; n < 2; ++n) {
;                         const int col = u.pn * 256 + bj * 128 + wc * 32 + n * 16 + fq * 4;
;                         const u32x2 raw = *(const u32x2*)(src + (size_t)row * DM + col);
;                         f32x4 x = (f32x4){bflo(raw.x), bfhi(raw.x), bflo(raw.y), bfhi(raw.y)};
;                         if (ln) x = (x - mu) * rs * *(const f32x4*)(g + col) + *(const f32x4*)(b + col);
;                         const u32x2 pz = pk4(x * ALPHA + acc[ai][bj][m][n]);
;                         *(u32x2*)(dst + (size_t)row * DM + col) = pz;
;                         const float z0 = bflo(pz.x), z1 = bfhi(pz.x), z2 = bflo(pz.y), z3 = bfhi(pz.y);
;                         s1 += (z0 + z1) + (z2 + z3); s2 += (z0 * z0 + z1 * z1) + (z2 * z2 + z3 * z3);
;                     }
;                 s1 += __shfl_xor(s1, 16); s2 += __shfl_xor(s2, 16); s1 += __shfl_xor(s1, 32); s2 += __shfl_xor(s2, 32);
;                 if (fq == 0) { float* p = stm_n + (size_t)row * 32 + (u.pn * 4 + wc) * 2; p[0] = s1; p[1] = s2; }
	v_pk_fma_f32 v[130:131], v[148:149], v[130:131], v[152:153]
	s_nop 0
	v_pk_fma_f32 v[100:101], v[130:131], s[72:73], v[100:101] op_sel_hi:[1,0,1]
	v_lshlrev_b32_e32 v131, 16, v126
	v_lshlrev_b32_e32 v130, 16, v118
	v_mov_b32_e32 v115, v131
	v_pk_fma_f32 v[128:129], v[150:151], v[128:129], v[154:155]
	v_pk_mul_f32 v[148:149], v[130:131], v[130:131]
	v_pk_mul_f32 v[150:151], v[114:115], v[114:115]
	v_and_b32_e32 v126, 0xffff0000, v119
	v_pk_mul_f32 v[118:119], v[112:113], v[112:113]
	v_pk_mul_f32 v[152:153], v[126:127], v[126:127]
	v_pk_mov_b32 v[154:155], v[130:131], v[148:149] op_sel:[1,0]
	v_pk_mov_b32 v[150:151], v[126:127], v[150:151] op_sel:[1,0]
	v_pk_add_f32 v[114:115], v[130:131], v[114:115]
	v_pk_add_f32 v[112:113], v[126:127], v[112:113]
	v_pk_fma_f32 v[102:103], v[128:129], s[72:73], v[102:103] op_sel_hi:[1,0,1]
	v_pk_add_f32 v[150:151], v[154:155], v[150:151]
	v_mov_b32_e32 v154, v110
	v_mov_b32_e32 v155, v118
	v_pk_mov_b32 v[110:111], v[110:111], v[152:153] op_sel:[1,0]
	v_mov_b32_e32 v115, v149
	v_mov_b32_e32 v113, v153
	v_cvt_pk_bf16_f32 v100, v100, v101
	v_cvt_pk_bf16_f32 v101, v102, v103
	v_pk_add_f32 v[110:111], v[154:155], v[110:111]
	v_pk_add_f32 v[112:113], v[114:115], v[112:113]
	global_store_dwordx2 v[124:125], v[100:101], off offset:288
	v_lshlrev_b32_e32 v124, 16, v100
	v_and_b32_e32 v128, 0xffff0000, v100
	v_lshlrev_b32_e32 v100, 16, v101
	v_and_b32_e32 v102, 0xffff0000, v101
	v_pk_add_f32 v[110:111], v[150:151], v[110:111]
	v_pk_add_f32 v[108:109], v[112:113], v[2:3]
	v_mul_f32_e32 v125, v124, v124
	v_mul_f32_e32 v129, v128, v128
	v_mul_f32_e32 v101, v100, v100
	v_mul_f32_e32 v103, v102, v102
	v_pk_add_f32 v[108:109], v[110:111], v[108:109]
	v_pk_add_f32 v[110:111], v[120:121], v[122:123]
	v_pk_add_f32 v[106:107], v[124:125], v[128:129]
	v_pk_add_f32 v[104:105], v[110:111], v[104:105]
	v_pk_add_f32 v[100:101], v[100:101], v[102:103]
	v_pk_add_f32 v[104:105], v[108:109], v[104:105]
	v_pk_add_f32 v[100:101], v[106:107], v[100:101]
	s_nop 0
	v_pk_add_f32 v[100:101], v[104:105], v[100:101]
	ds_bpermute_b32 v102, v181, v100
	ds_bpermute_b32 v103, v181, v101
	s_waitcnt lgkmcnt(0)
	v_pk_add_f32 v[100:101], v[100:101], v[102:103]
	ds_bpermute_b32 v102, v180, v100
	ds_bpermute_b32 v103, v180, v101
	s_and_saveexec_b64 s[0:1], s[40:41]
	s_cbranch_execz .LBB0_2381
	v_lshl_add_u64 v[104:105], s[52:53], 0, v[116:117]
	v_lshl_add_u64 v[104:105], s[68:69], 2, v[104:105]
	s_waitcnt lgkmcnt(0)
	v_pk_add_f32 v[100:101], v[100:101], v[102:103]
	global_store_dwordx2 v[104:105], v[100:101], off
.LBB0_2381:
	s_or_b64 exec, exec, s[0:1]
	v_or_b32_e32 v110, 32, v146
	v_ashrrev_i32_e32 v111, 31, v110
	v_lshlrev_b64 v[100:101], 7, v[110:111]
	v_lshl_add_u64 v[106:107], v[134:135], 0, v[100:101]
	s_waitcnt lgkmcnt(0)
	s_waitcnt vmcnt(11)
	v_mov_b64_e32 v[102:103], v[190:191]
	v_mov_b64_e32 v[104:105], v[192:193]
	global_load_dwordx4 v[190:193], v[248:249], off offset:-4080
	s_nop 0
	s_waitcnt vmcnt(11)
	v_mov_b64_e32 v[106:107], v[194:195]
	v_mov_b64_e32 v[108:109], v[196:197]
	global_load_dwordx4 v[194:197], v[248:249], off offset:-4096
	s_waitcnt lgkmcnt(0)
	v_pk_add_f32 v[102:103], v[102:103], v[104:105]
	s_waitcnt lgkmcnt(0)
	v_pk_add_f32 v[106:107], v[106:107], v[108:109]
	s_nop 0
	v_pk_add_f32 v[102:103], v[106:107], v[102:103]
	ds_bpermute_b32 v104, v181, v102
	ds_bpermute_b32 v105, v181, v103
	s_waitcnt lgkmcnt(0)
	v_pk_add_f32 v[102:103], v[102:103], v[104:105]
	ds_bpermute_b32 v104, v180, v102
	ds_bpermute_b32 v105, v180, v103
	s_waitcnt lgkmcnt(0)
	v_pk_add_f32 v[102:103], v[102:103], v[104:105]
	s_nop 0
	v_pk_mul_f32 v[112:113], v[102:103], s[82:83] op_sel_hi:[1,0]
	v_lshlrev_b64 v[102:103], 11, v[110:111]
	v_lshl_add_u64 v[102:103], s[70:71], 0, v[102:103]
	v_lshl_add_u64 v[108:109], v[144:145], 1, v[102:103]
	v_add_u32_e32 v243, 0x40000, v242
	s_waitcnt vmcnt(11)
	v_mov_b64_e32 v[102:103], v[198:199]
	global_load_dwordx2 v[198:199], v243, s[70:71]
	v_fma_f32 v3, -v112, v112, v113
	v_max_f32_e32 v3, 0, v3
	v_add_f32_e32 v3, 0x3727c5ac, v3
	v_rsq_f32_e32 v114, v3
	s_waitcnt lgkmcnt(0)
	v_lshlrev_b32_e32 v3, 16, v102
	v_and_b32_e32 v102, 0xffff0000, v102
	v_lshlrev_b32_e32 v104, 16, v103
	v_and_b32_e32 v105, 0xffff0000, v103
	v_sub_f32_e32 v103, v102, v112
	v_sub_f32_e32 v102, v3, v112
	v_sub_f32_e32 v105, v105, v112
	v_sub_f32_e32 v104, v104, v112
	v_pk_mul_f32 v[106:107], v[104:105], v[114:115] op_sel_hi:[1,0]
	v_pk_mul_f32 v[110:111], v[102:103], v[114:115] op_sel_hi:[1,0]
	ds_read_b128 v[102:105], v244
	ds_read_b128 v[116:119], v244 offset:256
	s_waitcnt lgkmcnt(0)
	v_pk_fma_f32 v[104:105], v[104:105], v[106:107], v[118:119]
	s_nop 0
	v_pk_fma_f32 v[98:99], v[104:105], s[72:73], v[98:99] op_sel_hi:[1,0,1]
	s_waitcnt vmcnt(11)
	v_mov_b64_e32 v[104:105], v[200:201]
	global_load_dwordx2 v[200:201], v243, s[70:71] offset:32
	v_pk_fma_f32 v[102:103], v[102:103], v[110:111], v[116:117]
	s_waitcnt lgkmcnt(0)
	v_lshlrev_b32_e32 v3, 16, v104
	v_pk_fma_f32 v[96:97], v[102:103], s[72:73], v[96:97] op_sel_hi:[1,0,1]
	v_cvt_pk_bf16_f32 v103, v98, v99
	v_cvt_pk_bf16_f32 v102, v96, v97
	v_and_b32_e32 v97, 0xffff0000, v104
	v_lshlrev_b32_e32 v99, 16, v105
	v_and_b32_e32 v106, 0xffff0000, v105
	global_store_dwordx2 v[108:109], v[102:103], off
	v_sub_f32_e32 v105, v97, v112
	v_sub_f32_e32 v104, v3, v112
	v_sub_f32_e32 v107, v106, v112
	v_sub_f32_e32 v106, v99, v112
	v_pk_mul_f32 v[110:111], v[114:115], v[106:107] op_sel_hi:[0,1]
	v_pk_mul_f32 v[120:121], v[114:115], v[104:105] op_sel_hi:[0,1]
	ds_read_b128 v[104:107], v244 offset:64
	ds_read_b128 v[116:119], v244 offset:320
	v_and_b32_e32 v98, 0xffff0000, v102
	v_lshlrev_b32_e32 v96, 16, v103
	s_waitcnt lgkmcnt(0)
; __device__ __forceinline__ u32x2 pk4(f32x4 v) { u32x2 r; r.x = pk2(v.x, v.y); r.y = pk2(v.z, v.w); return r; }
;     __device__ __forceinline__ void operator()(const f32x4 (&acc)[2][2][4][2], const pg8::Unit& u, int wr, int wc, int fr, int fq) const {
;     ...
;                 for (int bj = 0; bj < 2; ++bj)
; #pragma unroll
;                     for (int n = 0; n < 2; ++n) {
;                         const int col = u.pn * 256 + bj * 128 + wc * 32 + n * 16 + fq * 4;
;                         const u32x2 raw = *(const u32x2*)(src + (size_t)row * DM + col);
;                         f32x4 x = (f32x4){bflo(raw.x), bfhi(raw.x), bflo(raw.y), bfhi(raw.y)};
;                         if (ln) x = (x - mu) * rs * *(const f32x4*)(g + col) + *(const f32x4*)(b + col);
;                         const u32x2 pz = pk4(x * ALPHA + acc[ai][bj][m][n]);
;                         *(u32x2*)(dst + (size_t)row * DM + col) = pz;
;                         const float z0 = bflo(pz.x), z1 = bfhi(pz.x), z2 = bflo(pz.y), z3 = bfhi(pz.y);
;                         s1 += (z0 + z1) + (z2 + z3); s2 += (z0 * z0 + z1 * z1) + (z2 * z2 + z3 * z3);
;                     }
;                 s1 += __shfl_xor(s1, 16); s2 += __shfl_xor(s2, 16); s1 += __shfl_xor(s1, 32); s2 += __shfl_xor(s2, 32);
;                 if (fq == 0) { float* p = stm_n + (size_t)row * 32 + (u.pn * 4 + wc) * 2; p[0] = s1; p[1] = s2; }
	v_pk_fma_f32 v[104:105], v[104:105], v[120:121], v[116:117]
	s_nop 0
	v_pk_fma_f32 v[92:93], v[104:105], s[72:73], v[92:93] op_sel_hi:[1,0,1]
	s_waitcnt vmcnt(11)
	v_mov_b64_e32 v[104:105], v[202:203]
	global_load_dwordx2 v[202:203], v243, s[70:71] offset:256
	v_pk_fma_f32 v[106:107], v[106:107], v[110:111], v[118:119]
	v_cvt_pk_bf16_f32 v110, v92, v93
	v_pk_fma_f32 v[94:95], v[106:107], s[72:73], v[94:95] op_sel_hi:[1,0,1]
	s_waitcnt lgkmcnt(0)
	v_lshlrev_b32_e32 v3, 16, v104
	v_cvt_pk_bf16_f32 v111, v94, v95
	v_lshlrev_b32_e32 v94, 16, v111
	v_and_b32_e32 v95, 0xffff0000, v111
	v_mul_f32_e32 v92, v94, v94
	v_pk_fma_f32 v[92:93], v[94:95], v[94:95], v[92:93] op_sel_hi:[1,1,0]
	v_lshlrev_b32_e32 v97, 16, v105
	v_and_b32_e32 v92, 0xffff0000, v104
	v_and_b32_e32 v99, 0xffff0000, v105
	global_store_dwordx2 v[108:109], v[110:111], off offset:32
	v_sub_f32_e32 v105, v92, v112
	v_sub_f32_e32 v104, v3, v112
	v_sub_f32_e32 v107, v99, v112
	v_sub_f32_e32 v106, v97, v112
	v_pk_mul_f32 v[120:121], v[114:115], v[106:107] op_sel_hi:[0,1]
	v_pk_mul_f32 v[122:123], v[114:115], v[104:105] op_sel_hi:[0,1]
	ds_read_b128 v[104:107], v244 offset:128
	ds_read_b128 v[116:119], v244 offset:384
	v_and_b32_e32 v111, 0xffff0000, v110
	s_waitcnt lgkmcnt(0)
	v_pk_fma_f32 v[104:105], v[104:105], v[122:123], v[116:117]
	s_waitcnt vmcnt(11)
	v_mov_b64_e32 v[116:117], v[204:205]
	global_load_dwordx2 v[204:205], v243, s[70:71] offset:288
	v_pk_fma_f32 v[106:107], v[106:107], v[120:121], v[118:119]
	v_pk_fma_f32 v[88:89], v[104:105], s[72:73], v[88:89] op_sel_hi:[1,0,1]
	v_pk_fma_f32 v[90:91], v[106:107], s[72:73], v[90:91] op_sel_hi:[1,0,1]
	v_cvt_pk_bf16_f32 v88, v88, v89
	v_cvt_pk_bf16_f32 v89, v90, v91
	global_store_dwordx2 v[108:109], v[88:89], off offset:256
	v_lshlrev_b32_e32 v104, 16, v88
	v_and_b32_e32 v106, 0xffff0000, v88
	v_lshlrev_b32_e32 v88, 16, v89
	v_and_b32_e32 v90, 0xffff0000, v89
	v_mul_f32_e32 v105, v104, v104
	v_mul_f32_e32 v107, v106, v106
	v_mul_f32_e32 v89, v88, v88
	v_mul_f32_e32 v91, v90, v90
	v_pk_add_f32 v[88:89], v[88:89], v[90:91]
	s_waitcnt lgkmcnt(0)
	v_lshlrev_b32_e32 v3, 16, v116
	v_and_b32_e32 v92, 0xffff0000, v116
	v_lshlrev_b32_e32 v97, 16, v117
	v_and_b32_e32 v99, 0xffff0000, v117
	v_sub_f32_e32 v117, v92, v112
	v_sub_f32_e32 v116, v3, v112
	v_sub_f32_e32 v113, v99, v112
	v_sub_f32_e32 v112, v97, v112
	v_pk_mul_f32 v[112:113], v[114:115], v[112:113] op_sel_hi:[0,1]
	v_pk_mul_f32 v[114:115], v[114:115], v[116:117] op_sel_hi:[0,1]
	ds_read_b128 v[116:119], v244 offset:192
	ds_read_b128 v[120:123], v244 offset:448
	v_mov_b32_e32 v97, v111
	v_mov_b32_e32 v3, v93
	s_waitcnt lgkmcnt(0)
	v_pk_fma_f32 v[114:115], v[116:117], v[114:115], v[120:121]
	s_nop 0
	v_pk_fma_f32 v[84:85], v[114:115], s[72:73], v[84:85] op_sel_hi:[1,0,1]
	v_lshlrev_b32_e32 v115, 16, v110
	v_lshlrev_b32_e32 v114, 16, v102
	v_mov_b32_e32 v99, v115
	v_pk_fma_f32 v[112:113], v[118:119], v[112:113], v[122:123]
	v_pk_mul_f32 v[116:117], v[114:115], v[114:115]
	v_pk_mul_f32 v[118:119], v[98:99], v[98:99]
	v_and_b32_e32 v110, 0xffff0000, v103
	v_pk_mul_f32 v[102:103], v[96:97], v[96:97]
	v_pk_mul_f32 v[120:121], v[110:111], v[110:111]
	v_pk_mov_b32 v[122:123], v[114:115], v[116:117] op_sel:[1,0]
	v_pk_mov_b32 v[118:119], v[110:111], v[118:119] op_sel:[1,0]
	v_pk_add_f32 v[98:99], v[114:115], v[98:99]
	v_pk_add_f32 v[96:97], v[110:111], v[96:97]
	v_pk_fma_f32 v[86:87], v[112:113], s[72:73], v[86:87] op_sel_hi:[1,0,1]
	v_pk_add_f32 v[118:119], v[122:123], v[118:119]
	v_mov_b32_e32 v122, v94
	v_mov_b32_e32 v123, v102
	v_pk_mov_b32 v[94:95], v[94:95], v[120:121] op_sel:[1,0]
	v_mov_b32_e32 v99, v117
	v_mov_b32_e32 v97, v121
	v_cvt_pk_bf16_f32 v84, v84, v85
	v_cvt_pk_bf16_f32 v85, v86, v87
	v_pk_add_f32 v[94:95], v[122:123], v[94:95]
	v_pk_add_f32 v[96:97], v[98:99], v[96:97]
	global_store_dwordx2 v[108:109], v[84:85], off offset:288
	v_lshlrev_b32_e32 v108, 16, v84
	v_and_b32_e32 v112, 0xffff0000, v84
	v_lshlrev_b32_e32 v84, 16, v85
	v_and_b32_e32 v86, 0xffff0000, v85
	v_pk_add_f32 v[94:95], v[118:119], v[94:95]
	v_pk_add_f32 v[92:93], v[96:97], v[2:3]
	v_mul_f32_e32 v109, v108, v108
	v_mul_f32_e32 v113, v112, v112
	v_mul_f32_e32 v85, v84, v84
	v_mul_f32_e32 v87, v86, v86
	v_pk_add_f32 v[92:93], v[94:95], v[92:93]
	v_pk_add_f32 v[94:95], v[104:105], v[106:107]
	v_pk_add_f32 v[90:91], v[108:109], v[112:113]
	v_pk_add_f32 v[88:89], v[94:95], v[88:89]
	v_pk_add_f32 v[84:85], v[84:85], v[86:87]
	v_pk_add_f32 v[88:89], v[92:93], v[88:89]
	v_pk_add_f32 v[84:85], v[90:91], v[84:85]
	s_nop 0
	v_pk_add_f32 v[84:85], v[88:89], v[84:85]
	ds_bpermute_b32 v86, v181, v84
	ds_bpermute_b32 v87, v181, v85
	s_waitcnt lgkmcnt(0)
	v_pk_add_f32 v[84:85], v[84:85], v[86:87]
	ds_bpermute_b32 v86, v180, v84
	ds_bpermute_b32 v87, v180, v85
	s_and_saveexec_b64 s[0:1], s[40:41]
	s_mov_b32 s78, 0x20000
	s_mov_b32 s76, 0x30000
	s_cbranch_execz .LBB0_2383
	v_lshl_add_u64 v[88:89], s[52:53], 0, v[100:101]
	v_lshl_add_u64 v[88:89], s[68:69], 2, v[88:89]
	s_waitcnt lgkmcnt(0)
	v_pk_add_f32 v[84:85], v[84:85], v[86:87]
	global_store_dwordx2 v[88:89], v[84:85], off
; __device__ __forceinline__ u32x2 pk4(f32x4 v) { u32x2 r; r.x = pk2(v.x, v.y); r.y = pk2(v.z, v.w); return r; }
; __device__ __forceinline__ void stats_main(const float* stm, int row, int fq, float& mu, float& rs) {
;     const f32x4* p = (const f32x4*)(stm + (size_t)row * 32 + fq * 8);
;     const f32x4 a = p[0], b = p[1];
;     float s1 = (a.x + a.z) + (b.x + b.z), s2 = (a.y + a.w) + (b.y + b.w);
;     s1 += __shfl_xor(s1, 16); s2 += __shfl_xor(s2, 16); s1 += __shfl_xor(s1, 32); s2 += __shfl_xor(s2, 32);
;     mu = s1 * (1.f / DM); rs = __builtin_amdgcn_rsqf(fmaxf(s2 * (1.f / DM) - mu * mu, 0.f) + LN_EPS);
; }
;     __device__ __forceinline__ void operator()(const f32x4 (&acc)[2][2][4][2], const pg8::Unit& u, int wr, int wc, int fr, int fq) const {
;     ...
;                 const int row = u.pm * 256 + ai * 128 + wr * 64 + m * 16 + fr;
;                 float mu = 0.f, rs = 1.f; if (ln) stats_main(stm_p, row, fq, mu, rs);
;                 float s1 = 0.f, s2 = 0.f;
; #pragma unroll
;                 for (int bj = 0; bj < 2; ++bj)
; #pragma unroll
;                     for (int n = 0; n < 2; ++n) {
;                         const int col = u.pn * 256 + bj * 128 + wc * 32 + n * 16 + fq * 4;
;                         const u32x2 raw = *(const u32x2*)(src + (size_t)row * DM + col);
;                         f32x4 x = (f32x4){bflo(raw.x), bfhi(raw.x), bflo(raw.y), bfhi(raw.y)};
;                         if (ln) x = (x - mu) * rs * *(const f32x4*)(g + col) + *(const f32x4*)(b + col);
;                         const u32x2 pz = pk4(x * ALPHA + acc[ai][bj][m][n]);
;                         *(u32x2*)(dst + (size_t)row * DM + col) = pz;
;                         const float z0 = bflo(pz.x), z1 = bfhi(pz.x), z2 = bflo(pz.y), z3 = bfhi(pz.y);
;                         s1 += (z0 + z1) + (z2 + z3); s2 += (z0 * z0 + z1 * z1) + (z2 * z2 + z3 * z3);
;                     }
;                 s1 += __shfl_xor(s1, 16); s2 += __shfl_xor(s2, 16); s1 += __shfl_xor(s1, 32); s2 += __shfl_xor(s2, 32);
;                 if (fq == 0) { float* p = stm_n + (size_t)row * 32 + (u.pn * 4 + wc) * 2; p[0] = s1; p[1] = s2; }
.LBB0_2383:
	s_or_b64 exec, exec, s[0:1]
	v_or_b32_e32 v94, 48, v146
	v_ashrrev_i32_e32 v95, 31, v94
	v_lshlrev_b64 v[84:85], 7, v[94:95]
	v_lshl_add_u64 v[90:91], v[134:135], 0, v[84:85]
	s_waitcnt lgkmcnt(0)
	s_waitcnt vmcnt(11)
	v_mov_b64_e32 v[86:87], v[206:207]
	v_mov_b64_e32 v[88:89], v[208:209]
	global_load_dwordx4 v[206:209], v[248:249], off offset:-2032
	s_nop 0
	s_waitcnt vmcnt(11)
	v_mov_b64_e32 v[90:91], v[214:215]
	v_mov_b64_e32 v[92:93], v[216:217]
	global_load_dwordx4 v[214:217], v[248:249], off offset:-2048
	s_waitcnt lgkmcnt(0)
	v_pk_add_f32 v[86:87], v[86:87], v[88:89]
	s_waitcnt lgkmcnt(0)
	v_pk_add_f32 v[90:91], v[90:91], v[92:93]
	s_nop 0
	v_pk_add_f32 v[86:87], v[90:91], v[86:87]
	ds_bpermute_b32 v88, v181, v86
	ds_bpermute_b32 v89, v181, v87
	s_waitcnt lgkmcnt(0)
	v_pk_add_f32 v[86:87], v[86:87], v[88:89]
	ds_bpermute_b32 v88, v180, v86
	ds_bpermute_b32 v89, v180, v87
	s_waitcnt lgkmcnt(0)
	v_pk_add_f32 v[86:87], v[86:87], v[88:89]
	s_nop 0
	v_pk_mul_f32 v[96:97], v[86:87], s[82:83] op_sel_hi:[1,0]
	v_lshlrev_b64 v[86:87], 11, v[94:95]
	v_lshl_add_u64 v[86:87], s[70:71], 0, v[86:87]
	v_lshl_add_u64 v[92:93], v[144:145], 1, v[86:87]
	v_add_u32_e32 v243, 0x48000, v242
	s_waitcnt vmcnt(11)
	v_mov_b64_e32 v[86:87], v[234:235]
	global_load_dwordx2 v[234:235], v243, s[70:71]
	v_fma_f32 v3, -v96, v96, v97
	v_max_f32_e32 v3, 0, v3
	v_add_f32_e32 v3, 0x3727c5ac, v3
	v_rsq_f32_e32 v98, v3
	s_waitcnt lgkmcnt(0)
	v_lshlrev_b32_e32 v3, 16, v86
	v_and_b32_e32 v86, 0xffff0000, v86
	v_lshlrev_b32_e32 v88, 16, v87
	v_and_b32_e32 v89, 0xffff0000, v87
	v_sub_f32_e32 v87, v86, v96
	v_sub_f32_e32 v86, v3, v96
	v_sub_f32_e32 v89, v89, v96
	v_sub_f32_e32 v88, v88, v96
	v_pk_mul_f32 v[90:91], v[88:89], v[98:99] op_sel_hi:[1,0]
	v_pk_mul_f32 v[94:95], v[86:87], v[98:99] op_sel_hi:[1,0]
	ds_read_b128 v[86:89], v244
	ds_read_b128 v[100:103], v244 offset:256
	s_waitcnt lgkmcnt(0)
	v_pk_fma_f32 v[88:89], v[88:89], v[90:91], v[102:103]
	s_nop 0
	v_pk_fma_f32 v[82:83], v[88:89], s[72:73], v[82:83] op_sel_hi:[1,0,1]
	s_waitcnt vmcnt(11)
	v_mov_b64_e32 v[88:89], v[236:237]
	global_load_dwordx2 v[236:237], v243, s[70:71] offset:32
	v_pk_fma_f32 v[86:87], v[86:87], v[94:95], v[100:101]
	s_waitcnt lgkmcnt(0)
	v_lshlrev_b32_e32 v3, 16, v88
	v_pk_fma_f32 v[80:81], v[86:87], s[72:73], v[80:81] op_sel_hi:[1,0,1]
	v_cvt_pk_bf16_f32 v87, v82, v83
	v_cvt_pk_bf16_f32 v86, v80, v81
	v_and_b32_e32 v81, 0xffff0000, v88
	v_lshlrev_b32_e32 v83, 16, v89
	v_and_b32_e32 v90, 0xffff0000, v89
	global_store_dwordx2 v[92:93], v[86:87], off
	v_sub_f32_e32 v89, v81, v96
	v_sub_f32_e32 v88, v3, v96
	v_sub_f32_e32 v91, v90, v96
	v_sub_f32_e32 v90, v83, v96
	v_pk_mul_f32 v[94:95], v[98:99], v[90:91] op_sel_hi:[0,1]
	v_pk_mul_f32 v[104:105], v[98:99], v[88:89] op_sel_hi:[0,1]
	ds_read_b128 v[88:91], v244 offset:64
	ds_read_b128 v[100:103], v244 offset:320
	v_and_b32_e32 v82, 0xffff0000, v86
	v_lshlrev_b32_e32 v80, 16, v87
	s_waitcnt lgkmcnt(0)
	v_pk_fma_f32 v[88:89], v[88:89], v[104:105], v[100:101]
	s_nop 0
	v_pk_fma_f32 v[76:77], v[88:89], s[72:73], v[76:77] op_sel_hi:[1,0,1]
	s_waitcnt vmcnt(11)
	v_mov_b64_e32 v[88:89], v[238:239]
	global_load_dwordx2 v[238:239], v243, s[70:71] offset:256
	v_pk_fma_f32 v[90:91], v[90:91], v[94:95], v[102:103]
	v_cvt_pk_bf16_f32 v94, v76, v77
	v_pk_fma_f32 v[78:79], v[90:91], s[72:73], v[78:79] op_sel_hi:[1,0,1]
	s_waitcnt lgkmcnt(0)
	v_lshlrev_b32_e32 v3, 16, v88
	v_cvt_pk_bf16_f32 v95, v78, v79
	v_lshlrev_b32_e32 v78, 16, v95
	v_and_b32_e32 v79, 0xffff0000, v95
	v_mul_f32_e32 v76, v78, v78
	v_pk_fma_f32 v[76:77], v[78:79], v[78:79], v[76:77] op_sel_hi:[1,1,0]
	v_lshlrev_b32_e32 v81, 16, v89
	v_and_b32_e32 v76, 0xffff0000, v88
	v_and_b32_e32 v83, 0xffff0000, v89
	global_store_dwordx2 v[92:93], v[94:95], off offset:32
	v_sub_f32_e32 v89, v76, v96
	v_sub_f32_e32 v88, v3, v96
	v_sub_f32_e32 v91, v83, v96
	v_sub_f32_e32 v90, v81, v96
	v_pk_mul_f32 v[104:105], v[98:99], v[90:91] op_sel_hi:[0,1]
	v_pk_mul_f32 v[106:107], v[98:99], v[88:89] op_sel_hi:[0,1]
	ds_read_b128 v[88:91], v244 offset:128
	ds_read_b128 v[100:103], v244 offset:384
	v_and_b32_e32 v95, 0xffff0000, v94
	s_waitcnt lgkmcnt(0)
	v_pk_fma_f32 v[88:89], v[88:89], v[106:107], v[100:101]
	s_waitcnt vmcnt(11)
	v_mov_b64_e32 v[100:101], v[240:241]
	global_load_dwordx2 v[240:241], v243, s[70:71] offset:288
	v_pk_fma_f32 v[90:91], v[90:91], v[104:105], v[102:103]
	v_pk_fma_f32 v[72:73], v[88:89], s[72:73], v[72:73] op_sel_hi:[1,0,1]
	v_pk_fma_f32 v[74:75], v[90:91], s[72:73], v[74:75] op_sel_hi:[1,0,1]
	v_cvt_pk_bf16_f32 v72, v72, v73
	v_cvt_pk_bf16_f32 v73, v74, v75
	global_store_dwordx2 v[92:93], v[72:73], off offset:256
	v_lshlrev_b32_e32 v88, 16, v72
	v_and_b32_e32 v90, 0xffff0000, v72
	v_lshlrev_b32_e32 v72, 16, v73
	v_and_b32_e32 v74, 0xffff0000, v73
	v_mul_f32_e32 v89, v88, v88
	v_mul_f32_e32 v91, v90, v90
	v_mul_f32_e32 v73, v72, v72
	v_mul_f32_e32 v75, v74, v74
	v_pk_add_f32 v[72:73], v[72:73], v[74:75]
	s_waitcnt lgkmcnt(0)
	v_lshlrev_b32_e32 v3, 16, v100
	v_and_b32_e32 v76, 0xffff0000, v100
	v_lshlrev_b32_e32 v81, 16, v101
	v_and_b32_e32 v83, 0xffff0000, v101
	v_sub_f32_e32 v101, v76, v96
	v_sub_f32_e32 v100, v3, v96
	v_sub_f32_e32 v97, v83, v96
	v_sub_f32_e32 v96, v81, v96
	v_pk_mul_f32 v[96:97], v[98:99], v[96:97] op_sel_hi:[0,1]
	v_pk_mul_f32 v[98:99], v[98:99], v[100:101] op_sel_hi:[0,1]
	ds_read_b128 v[100:103], v244 offset:192
	ds_read_b128 v[104:107], v244 offset:448
	v_mov_b32_e32 v81, v95
	v_mov_b32_e32 v3, v77
	s_waitcnt lgkmcnt(0)
; __device__ __forceinline__ u32x2 pk4(f32x4 v) { u32x2 r; r.x = pk2(v.x, v.y); r.y = pk2(v.z, v.w); return r; }
; __device__ __forceinline__ void stats_main(const float* stm, int row, int fq, float& mu, float& rs) {
;     const f32x4* p = (const f32x4*)(stm + (size_t)row * 32 + fq * 8);
;     const f32x4 a = p[0], b = p[1];
;     float s1 = (a.x + a.z) + (b.x + b.z), s2 = (a.y + a.w) + (b.y + b.w);
;     s1 += __shfl_xor(s1, 16); s2 += __shfl_xor(s2, 16); s1 += __shfl_xor(s1, 32); s2 += __shfl_xor(s2, 32);
;     mu = s1 * (1.f / DM); rs = __builtin_amdgcn_rsqf(fmaxf(s2 * (1.f / DM) - mu * mu, 0.f) + LN_EPS);
; }
;     __device__ __forceinline__ void operator()(const f32x4 (&acc)[2][2][4][2], const pg8::Unit& u, int wr, int wc, int fr, int fq) const {
;     ...
;                 for (int bj = 0; bj < 2; ++bj)
; #pragma unroll
;                     for (int n = 0; n < 2; ++n) {
;                         const int col = u.pn * 256 + bj * 128 + wc * 32 + n * 16 + fq * 4;
;                         const u32x2 raw = *(const u32x2*)(src + (size_t)row * DM + col);
;                         f32x4 x = (f32x4){bflo(raw.x), bfhi(raw.x), bflo(raw.y), bfhi(raw.y)};
;                         if (ln) x = (x - mu) * rs * *(const f32x4*)(g + col) + *(const f32x4*)(b + col);
;                         const u32x2 pz = pk4(x * ALPHA + acc[ai][bj][m][n]);
;                         *(u32x2*)(dst + (size_t)row * DM + col) = pz;
;                         const float z0 = bflo(pz.x), z1 = bfhi(pz.x), z2 = bflo(pz.y), z3 = bfhi(pz.y);
;                         s1 += (z0 + z1) + (z2 + z3); s2 += (z0 * z0 + z1 * z1) + (z2 * z2 + z3 * z3);
;                     }
;                 s1 += __shfl_xor(s1, 16); s2 += __shfl_xor(s2, 16); s1 += __shfl_xor(s1, 32); s2 += __shfl_xor(s2, 32);
;                 if (fq == 0) { float* p = stm_n + (size_t)row * 32 + (u.pn * 4 + wc) * 2; p[0] = s1; p[1] = s2; }
	v_pk_fma_f32 v[98:99], v[100:101], v[98:99], v[104:105]
	s_nop 0
	v_pk_fma_f32 v[68:69], v[98:99], s[72:73], v[68:69] op_sel_hi:[1,0,1]
	v_lshlrev_b32_e32 v99, 16, v94
	v_lshlrev_b32_e32 v98, 16, v86
	v_mov_b32_e32 v83, v99
	v_pk_fma_f32 v[96:97], v[102:103], v[96:97], v[106:107]
	v_pk_mul_f32 v[100:101], v[98:99], v[98:99]
	v_pk_mul_f32 v[102:103], v[82:83], v[82:83]
	v_and_b32_e32 v94, 0xffff0000, v87
	v_pk_mul_f32 v[86:87], v[80:81], v[80:81]
	v_pk_mul_f32 v[104:105], v[94:95], v[94:95]
	v_pk_mov_b32 v[106:107], v[98:99], v[100:101] op_sel:[1,0]
	v_pk_mov_b32 v[102:103], v[94:95], v[102:103] op_sel:[1,0]
	v_pk_add_f32 v[82:83], v[98:99], v[82:83]
	v_pk_add_f32 v[80:81], v[94:95], v[80:81]
	v_pk_fma_f32 v[70:71], v[96:97], s[72:73], v[70:71] op_sel_hi:[1,0,1]
	v_pk_add_f32 v[102:103], v[106:107], v[102:103]
	v_mov_b32_e32 v106, v78
	v_mov_b32_e32 v107, v86
	v_pk_mov_b32 v[78:79], v[78:79], v[104:105] op_sel:[1,0]
	v_mov_b32_e32 v83, v101
	v_mov_b32_e32 v81, v105
	v_cvt_pk_bf16_f32 v68, v68, v69
	v_cvt_pk_bf16_f32 v69, v70, v71
	v_pk_add_f32 v[78:79], v[106:107], v[78:79]
	v_pk_add_f32 v[80:81], v[82:83], v[80:81]
	global_store_dwordx2 v[92:93], v[68:69], off offset:288
	v_lshlrev_b32_e32 v92, 16, v68
	v_and_b32_e32 v96, 0xffff0000, v68
	v_lshlrev_b32_e32 v68, 16, v69
	v_and_b32_e32 v70, 0xffff0000, v69
	v_pk_add_f32 v[78:79], v[102:103], v[78:79]
	v_pk_add_f32 v[76:77], v[80:81], v[2:3]
	v_mul_f32_e32 v93, v92, v92
	v_mul_f32_e32 v97, v96, v96
	v_mul_f32_e32 v69, v68, v68
	v_mul_f32_e32 v71, v70, v70
	v_pk_add_f32 v[76:77], v[78:79], v[76:77]
	v_pk_add_f32 v[78:79], v[88:89], v[90:91]
	v_pk_add_f32 v[74:75], v[92:93], v[96:97]
	v_pk_add_f32 v[72:73], v[78:79], v[72:73]
	v_pk_add_f32 v[68:69], v[68:69], v[70:71]
	v_pk_add_f32 v[72:73], v[76:77], v[72:73]
	v_pk_add_f32 v[68:69], v[74:75], v[68:69]
	s_nop 0
	v_pk_add_f32 v[68:69], v[72:73], v[68:69]
	ds_bpermute_b32 v70, v181, v68
	ds_bpermute_b32 v71, v181, v69
	s_waitcnt lgkmcnt(0)
	v_pk_add_f32 v[68:69], v[68:69], v[70:71]
	ds_bpermute_b32 v70, v180, v68
	ds_bpermute_b32 v71, v180, v69
	s_and_saveexec_b64 s[0:1], s[40:41]
	s_cbranch_execz .LBB0_2385
	v_lshl_add_u64 v[72:73], s[52:53], 0, v[84:85]
	v_lshl_add_u64 v[72:73], s[68:69], 2, v[72:73]
	s_waitcnt lgkmcnt(0)
	v_pk_add_f32 v[68:69], v[68:69], v[70:71]
	global_store_dwordx2 v[72:73], v[68:69], off
.LBB0_2385:
	s_or_b64 exec, exec, s[0:1]
	v_add_u32_e32 v78, 0x80, v146
	v_ashrrev_i32_e32 v79, 31, v78
	v_lshlrev_b64 v[68:69], 7, v[78:79]
	v_lshl_add_u64 v[74:75], v[134:135], 0, v[68:69]
	s_waitcnt lgkmcnt(0)
	s_waitcnt vmcnt(11)
	v_mov_b64_e32 v[70:71], v[190:191]
	v_mov_b64_e32 v[72:73], v[192:193]
	global_load_dwordx4 v[190:193], v[248:249], off offset:16
	s_nop 0
	s_waitcnt vmcnt(11)
	v_mov_b64_e32 v[74:75], v[194:195]
	v_mov_b64_e32 v[76:77], v[196:197]
	global_load_dwordx4 v[194:197], v[248:249], off
	s_waitcnt lgkmcnt(0)
	v_pk_add_f32 v[70:71], v[70:71], v[72:73]
	s_waitcnt lgkmcnt(0)
	v_pk_add_f32 v[74:75], v[74:75], v[76:77]
	s_nop 0
	v_pk_add_f32 v[70:71], v[74:75], v[70:71]
	ds_bpermute_b32 v72, v181, v70
	ds_bpermute_b32 v73, v181, v71
	s_waitcnt lgkmcnt(0)
	v_pk_add_f32 v[70:71], v[70:71], v[72:73]
	ds_bpermute_b32 v72, v180, v70
	ds_bpermute_b32 v73, v180, v71
	s_waitcnt lgkmcnt(0)
	v_pk_add_f32 v[70:71], v[70:71], v[72:73]
	s_nop 0
	v_pk_mul_f32 v[80:81], v[70:71], s[82:83] op_sel_hi:[1,0]
	v_lshlrev_b64 v[70:71], 11, v[78:79]
	v_lshl_add_u64 v[70:71], s[70:71], 0, v[70:71]
	v_lshl_add_u64 v[76:77], v[144:145], 1, v[70:71]
	v_add_u32_e32 v243, 0x50000, v242
	s_waitcnt vmcnt(11)
	v_mov_b64_e32 v[70:71], v[198:199]
	global_load_dwordx2 v[198:199], v243, s[70:71]
	v_fma_f32 v3, -v80, v80, v81
	v_max_f32_e32 v3, 0, v3
	v_add_f32_e32 v3, 0x3727c5ac, v3
	v_rsq_f32_e32 v82, v3
	s_waitcnt lgkmcnt(0)
	v_lshlrev_b32_e32 v3, 16, v70
	v_and_b32_e32 v70, 0xffff0000, v70
	v_lshlrev_b32_e32 v72, 16, v71
	v_and_b32_e32 v73, 0xffff0000, v71
	v_sub_f32_e32 v71, v70, v80
	v_sub_f32_e32 v70, v3, v80
	v_sub_f32_e32 v73, v73, v80
	v_sub_f32_e32 v72, v72, v80
	v_pk_mul_f32 v[74:75], v[72:73], v[82:83] op_sel_hi:[1,0]
	v_pk_mul_f32 v[78:79], v[70:71], v[82:83] op_sel_hi:[1,0]
	ds_read_b128 v[70:73], v244
	ds_read_b128 v[84:87], v244 offset:256
	s_waitcnt lgkmcnt(0)
	v_pk_fma_f32 v[72:73], v[72:73], v[74:75], v[86:87]
	s_nop 0
	v_pk_fma_f32 v[66:67], v[72:73], s[72:73], v[66:67] op_sel_hi:[1,0,1]
	s_waitcnt vmcnt(11)
	v_mov_b64_e32 v[72:73], v[200:201]
	global_load_dwordx2 v[200:201], v243, s[70:71] offset:32
	v_pk_fma_f32 v[70:71], v[70:71], v[78:79], v[84:85]
	s_waitcnt lgkmcnt(0)
	v_lshlrev_b32_e32 v3, 16, v72
	v_pk_fma_f32 v[64:65], v[70:71], s[72:73], v[64:65] op_sel_hi:[1,0,1]
	v_cvt_pk_bf16_f32 v71, v66, v67
	v_cvt_pk_bf16_f32 v70, v64, v65
	v_and_b32_e32 v65, 0xffff0000, v72
	v_lshlrev_b32_e32 v67, 16, v73
	v_and_b32_e32 v74, 0xffff0000, v73
	global_store_dwordx2 v[76:77], v[70:71], off
	v_sub_f32_e32 v73, v65, v80
	v_sub_f32_e32 v72, v3, v80
	v_sub_f32_e32 v75, v74, v80
	v_sub_f32_e32 v74, v67, v80
	v_pk_mul_f32 v[78:79], v[82:83], v[74:75] op_sel_hi:[0,1]
	v_pk_mul_f32 v[88:89], v[82:83], v[72:73] op_sel_hi:[0,1]
	ds_read_b128 v[72:75], v244 offset:64
	ds_read_b128 v[84:87], v244 offset:320
	v_and_b32_e32 v66, 0xffff0000, v70
	v_lshlrev_b32_e32 v64, 16, v71
	s_waitcnt lgkmcnt(0)
	v_pk_fma_f32 v[72:73], v[72:73], v[88:89], v[84:85]
	s_nop 0
	v_pk_fma_f32 v[60:61], v[72:73], s[72:73], v[60:61] op_sel_hi:[1,0,1]
	s_waitcnt vmcnt(11)
	v_mov_b64_e32 v[72:73], v[202:203]
	global_load_dwordx2 v[202:203], v243, s[70:71] offset:256
	v_pk_fma_f32 v[74:75], v[74:75], v[78:79], v[86:87]
	v_cvt_pk_bf16_f32 v78, v60, v61
	v_pk_fma_f32 v[62:63], v[74:75], s[72:73], v[62:63] op_sel_hi:[1,0,1]
	s_waitcnt lgkmcnt(0)
; __device__ __forceinline__ u32x2 pk4(f32x4 v) { u32x2 r; r.x = pk2(v.x, v.y); r.y = pk2(v.z, v.w); return r; }
;     __device__ __forceinline__ void operator()(const f32x4 (&acc)[2][2][4][2], const pg8::Unit& u, int wr, int wc, int fr, int fq) const {
;     ...
;                 for (int bj = 0; bj < 2; ++bj)
; #pragma unroll
;                     for (int n = 0; n < 2; ++n) {
;                         const int col = u.pn * 256 + bj * 128 + wc * 32 + n * 16 + fq * 4;
;                         const u32x2 raw = *(const u32x2*)(src + (size_t)row * DM + col);
;                         f32x4 x = (f32x4){bflo(raw.x), bfhi(raw.x), bflo(raw.y), bfhi(raw.y)};
;                         if (ln) x = (x - mu) * rs * *(const f32x4*)(g + col) + *(const f32x4*)(b + col);
;                         const u32x2 pz = pk4(x * ALPHA + acc[ai][bj][m][n]);
;                         *(u32x2*)(dst + (size_t)row * DM + col) = pz;
;                         const float z0 = bflo(pz.x), z1 = bfhi(pz.x), z2 = bflo(pz.y), z3 = bfhi(pz.y);
;                         s1 += (z0 + z1) + (z2 + z3); s2 += (z0 * z0 + z1 * z1) + (z2 * z2 + z3 * z3);
;                     }
;                 s1 += __shfl_xor(s1, 16); s2 += __shfl_xor(s2, 16); s1 += __shfl_xor(s1, 32); s2 += __shfl_xor(s2, 32);
;                 if (fq == 0) { float* p = stm_n + (size_t)row * 32 + (u.pn * 4 + wc) * 2; p[0] = s1; p[1] = s2; }
	v_lshlrev_b32_e32 v3, 16, v72
	v_cvt_pk_bf16_f32 v79, v62, v63
	v_lshlrev_b32_e32 v62, 16, v79
	v_and_b32_e32 v63, 0xffff0000, v79
	v_mul_f32_e32 v60, v62, v62
	v_pk_fma_f32 v[60:61], v[62:63], v[62:63], v[60:61] op_sel_hi:[1,1,0]
	v_lshlrev_b32_e32 v65, 16, v73
	v_and_b32_e32 v60, 0xffff0000, v72
	v_and_b32_e32 v67, 0xffff0000, v73
	global_store_dwordx2 v[76:77], v[78:79], off offset:32
	v_sub_f32_e32 v73, v60, v80
	v_sub_f32_e32 v72, v3, v80
	v_sub_f32_e32 v75, v67, v80
	v_sub_f32_e32 v74, v65, v80
	v_pk_mul_f32 v[88:89], v[82:83], v[74:75] op_sel_hi:[0,1]
	v_pk_mul_f32 v[90:91], v[82:83], v[72:73] op_sel_hi:[0,1]
	ds_read_b128 v[72:75], v244 offset:128
	ds_read_b128 v[84:87], v244 offset:384
	v_and_b32_e32 v79, 0xffff0000, v78
	s_waitcnt lgkmcnt(0)
	v_pk_fma_f32 v[72:73], v[72:73], v[90:91], v[84:85]
	s_waitcnt vmcnt(11)
	v_mov_b64_e32 v[84:85], v[204:205]
	global_load_dwordx2 v[204:205], v243, s[70:71] offset:288
	v_pk_fma_f32 v[74:75], v[74:75], v[88:89], v[86:87]
	v_pk_fma_f32 v[56:57], v[72:73], s[72:73], v[56:57] op_sel_hi:[1,0,1]
	v_pk_fma_f32 v[58:59], v[74:75], s[72:73], v[58:59] op_sel_hi:[1,0,1]
	v_cvt_pk_bf16_f32 v56, v56, v57
	v_cvt_pk_bf16_f32 v57, v58, v59
	global_store_dwordx2 v[76:77], v[56:57], off offset:256
	v_lshlrev_b32_e32 v72, 16, v56
	v_and_b32_e32 v74, 0xffff0000, v56
	v_lshlrev_b32_e32 v56, 16, v57
	v_and_b32_e32 v58, 0xffff0000, v57
	v_mul_f32_e32 v73, v72, v72
	v_mul_f32_e32 v75, v74, v74
	v_mul_f32_e32 v57, v56, v56
	v_mul_f32_e32 v59, v58, v58
	v_pk_add_f32 v[56:57], v[56:57], v[58:59]
	s_waitcnt lgkmcnt(0)
	v_lshlrev_b32_e32 v3, 16, v84
	v_and_b32_e32 v60, 0xffff0000, v84
	v_lshlrev_b32_e32 v65, 16, v85
	v_and_b32_e32 v67, 0xffff0000, v85
	v_sub_f32_e32 v85, v60, v80
	v_sub_f32_e32 v84, v3, v80
	v_sub_f32_e32 v81, v67, v80
	v_sub_f32_e32 v80, v65, v80
	v_pk_mul_f32 v[80:81], v[82:83], v[80:81] op_sel_hi:[0,1]
	v_pk_mul_f32 v[82:83], v[82:83], v[84:85] op_sel_hi:[0,1]
	ds_read_b128 v[84:87], v244 offset:192
	ds_read_b128 v[88:91], v244 offset:448
	v_mov_b32_e32 v65, v79
	v_mov_b32_e32 v3, v61
	s_waitcnt lgkmcnt(0)
	v_pk_fma_f32 v[82:83], v[84:85], v[82:83], v[88:89]
	s_nop 0
	v_pk_fma_f32 v[52:53], v[82:83], s[72:73], v[52:53] op_sel_hi:[1,0,1]
	v_lshlrev_b32_e32 v83, 16, v78
	v_lshlrev_b32_e32 v82, 16, v70
	v_mov_b32_e32 v67, v83
	v_pk_fma_f32 v[80:81], v[86:87], v[80:81], v[90:91]
	v_pk_mul_f32 v[84:85], v[82:83], v[82:83]
	v_pk_mul_f32 v[86:87], v[66:67], v[66:67]
	v_and_b32_e32 v78, 0xffff0000, v71
	v_pk_mul_f32 v[70:71], v[64:65], v[64:65]
	v_pk_mul_f32 v[88:89], v[78:79], v[78:79]
	v_pk_mov_b32 v[90:91], v[82:83], v[84:85] op_sel:[1,0]
	v_pk_mov_b32 v[86:87], v[78:79], v[86:87] op_sel:[1,0]
	v_pk_add_f32 v[66:67], v[82:83], v[66:67]
	v_pk_add_f32 v[64:65], v[78:79], v[64:65]
	v_pk_fma_f32 v[54:55], v[80:81], s[72:73], v[54:55] op_sel_hi:[1,0,1]
	v_pk_add_f32 v[86:87], v[90:91], v[86:87]
	v_mov_b32_e32 v90, v62
	v_mov_b32_e32 v91, v70
	v_pk_mov_b32 v[62:63], v[62:63], v[88:89] op_sel:[1,0]
	v_mov_b32_e32 v67, v85
	v_mov_b32_e32 v65, v89
	v_cvt_pk_bf16_f32 v52, v52, v53
	v_cvt_pk_bf16_f32 v53, v54, v55
	v_pk_add_f32 v[62:63], v[90:91], v[62:63]
	v_pk_add_f32 v[64:65], v[66:67], v[64:65]
	global_store_dwordx2 v[76:77], v[52:53], off offset:288
	v_lshlrev_b32_e32 v76, 16, v52
	v_and_b32_e32 v80, 0xffff0000, v52
	v_lshlrev_b32_e32 v52, 16, v53
	v_and_b32_e32 v54, 0xffff0000, v53
	v_pk_add_f32 v[62:63], v[86:87], v[62:63]
	v_pk_add_f32 v[60:61], v[64:65], v[2:3]
	v_mul_f32_e32 v77, v76, v76
	v_mul_f32_e32 v81, v80, v80
	v_mul_f32_e32 v53, v52, v52
	v_mul_f32_e32 v55, v54, v54
	v_pk_add_f32 v[60:61], v[62:63], v[60:61]
	v_pk_add_f32 v[62:63], v[72:73], v[74:75]
	v_pk_add_f32 v[58:59], v[76:77], v[80:81]
	v_pk_add_f32 v[56:57], v[62:63], v[56:57]
	v_pk_add_f32 v[52:53], v[52:53], v[54:55]
	v_pk_add_f32 v[56:57], v[60:61], v[56:57]
	v_pk_add_f32 v[52:53], v[58:59], v[52:53]
	s_nop 0
	v_pk_add_f32 v[52:53], v[56:57], v[52:53]
	ds_bpermute_b32 v54, v181, v52
	ds_bpermute_b32 v55, v181, v53
	s_waitcnt lgkmcnt(0)
	v_pk_add_f32 v[52:53], v[52:53], v[54:55]
	ds_bpermute_b32 v54, v180, v52
	ds_bpermute_b32 v55, v180, v53
	s_and_saveexec_b64 s[0:1], s[40:41]
	s_cbranch_execz .LBB0_2387
	v_lshl_add_u64 v[56:57], s[52:53], 0, v[68:69]
	v_lshl_add_u64 v[56:57], s[68:69], 2, v[56:57]
	s_waitcnt lgkmcnt(0)
	v_pk_add_f32 v[52:53], v[52:53], v[54:55]
	global_store_dwordx2 v[56:57], v[52:53], off
; __device__ __forceinline__ u32x2 pk4(f32x4 v) { u32x2 r; r.x = pk2(v.x, v.y); r.y = pk2(v.z, v.w); return r; }
; __device__ __forceinline__ void stats_main(const float* stm, int row, int fq, float& mu, float& rs) {
;     const f32x4* p = (const f32x4*)(stm + (size_t)row * 32 + fq * 8);
;     const f32x4 a = p[0], b = p[1];
;     float s1 = (a.x + a.z) + (b.x + b.z), s2 = (a.y + a.w) + (b.y + b.w);
;     s1 += __shfl_xor(s1, 16); s2 += __shfl_xor(s2, 16); s1 += __shfl_xor(s1, 32); s2 += __shfl_xor(s2, 32);
;     mu = s1 * (1.f / DM); rs = __builtin_amdgcn_rsqf(fmaxf(s2 * (1.f / DM) - mu * mu, 0.f) + LN_EPS);
; }
;     __device__ __forceinline__ void operator()(const f32x4 (&acc)[2][2][4][2], const pg8::Unit& u, int wr, int wc, int fr, int fq) const {
;     ...
;                 const int row = u.pm * 256 + ai * 128 + wr * 64 + m * 16 + fr;
;                 float mu = 0.f, rs = 1.f; if (ln) stats_main(stm_p, row, fq, mu, rs);
;                 float s1 = 0.f, s2 = 0.f;
; #pragma unroll
;                 for (int bj = 0; bj < 2; ++bj)
; #pragma unroll
;                     for (int n = 0; n < 2; ++n) {
;                         const int col = u.pn * 256 + bj * 128 + wc * 32 + n * 16 + fq * 4;
;                         const u32x2 raw = *(const u32x2*)(src + (size_t)row * DM + col);
;                         f32x4 x = (f32x4){bflo(raw.x), bfhi(raw.x), bflo(raw.y), bfhi(raw.y)};
;                         if (ln) x = (x - mu) * rs * *(const f32x4*)(g + col) + *(const f32x4*)(b + col);
;                         const u32x2 pz = pk4(x * ALPHA + acc[ai][bj][m][n]);
;                         *(u32x2*)(dst + (size_t)row * DM + col) = pz;
;                         const float z0 = bflo(pz.x), z1 = bfhi(pz.x), z2 = bflo(pz.y), z3 = bfhi(pz.y);
;                         s1 += (z0 + z1) + (z2 + z3); s2 += (z0 * z0 + z1 * z1) + (z2 * z2 + z3 * z3);
;                     }
;                 s1 += __shfl_xor(s1, 16); s2 += __shfl_xor(s2, 16); s1 += __shfl_xor(s1, 32); s2 += __shfl_xor(s2, 32);
;                 if (fq == 0) { float* p = stm_n + (size_t)row * 32 + (u.pn * 4 + wc) * 2; p[0] = s1; p[1] = s2; }
.LBB0_2387:
	s_or_b64 exec, exec, s[0:1]
	v_add_u32_e32 v62, 0x90, v146
	v_ashrrev_i32_e32 v63, 31, v62
	v_lshlrev_b64 v[52:53], 7, v[62:63]
	v_lshl_add_u64 v[58:59], v[134:135], 0, v[52:53]
	s_waitcnt lgkmcnt(0)
	s_waitcnt vmcnt(11)
	v_mov_b64_e32 v[54:55], v[206:207]
	v_mov_b64_e32 v[56:57], v[208:209]
	global_load_dwordx4 v[206:209], v[248:249], off offset:2064
	s_nop 0
	s_waitcnt vmcnt(11)
	v_mov_b64_e32 v[58:59], v[214:215]
	v_mov_b64_e32 v[60:61], v[216:217]
	global_load_dwordx4 v[214:217], v[248:249], off offset:2048
	s_waitcnt lgkmcnt(0)
	v_pk_add_f32 v[54:55], v[54:55], v[56:57]
	s_waitcnt lgkmcnt(0)
	v_pk_add_f32 v[58:59], v[58:59], v[60:61]
	s_nop 0
	v_pk_add_f32 v[54:55], v[58:59], v[54:55]
	ds_bpermute_b32 v56, v181, v54
	ds_bpermute_b32 v57, v181, v55
	s_waitcnt lgkmcnt(0)
	v_pk_add_f32 v[54:55], v[54:55], v[56:57]
	ds_bpermute_b32 v56, v180, v54
	ds_bpermute_b32 v57, v180, v55
	s_waitcnt lgkmcnt(0)
	v_pk_add_f32 v[54:55], v[54:55], v[56:57]
	s_nop 0
	v_pk_mul_f32 v[64:65], v[54:55], s[82:83] op_sel_hi:[1,0]
	v_lshlrev_b64 v[54:55], 11, v[62:63]
	v_lshl_add_u64 v[54:55], s[70:71], 0, v[54:55]
	v_lshl_add_u64 v[60:61], v[144:145], 1, v[54:55]
	v_add_u32_e32 v243, 0x58000, v242
	s_waitcnt vmcnt(11)
	v_mov_b64_e32 v[54:55], v[234:235]
	global_load_dwordx2 v[234:235], v243, s[70:71]
	v_fma_f32 v3, -v64, v64, v65
	v_max_f32_e32 v3, 0, v3
	v_add_f32_e32 v3, 0x3727c5ac, v3
	v_rsq_f32_e32 v66, v3
	s_waitcnt lgkmcnt(0)
	v_lshlrev_b32_e32 v3, 16, v54
	v_and_b32_e32 v54, 0xffff0000, v54
	v_lshlrev_b32_e32 v56, 16, v55
	v_and_b32_e32 v57, 0xffff0000, v55
	v_sub_f32_e32 v55, v54, v64
	v_sub_f32_e32 v54, v3, v64
	v_sub_f32_e32 v57, v57, v64
	v_sub_f32_e32 v56, v56, v64
	v_pk_mul_f32 v[58:59], v[56:57], v[66:67] op_sel_hi:[1,0]
	v_pk_mul_f32 v[62:63], v[54:55], v[66:67] op_sel_hi:[1,0]
	ds_read_b128 v[54:57], v244
	ds_read_b128 v[68:71], v244 offset:256
	s_waitcnt lgkmcnt(0)
	v_pk_fma_f32 v[56:57], v[56:57], v[58:59], v[70:71]
	s_nop 0
	v_pk_fma_f32 v[50:51], v[56:57], s[72:73], v[50:51] op_sel_hi:[1,0,1]
	s_waitcnt vmcnt(11)
	v_mov_b64_e32 v[56:57], v[236:237]
	global_load_dwordx2 v[236:237], v243, s[70:71] offset:32
	v_pk_fma_f32 v[54:55], v[54:55], v[62:63], v[68:69]
	s_waitcnt lgkmcnt(0)
	v_lshlrev_b32_e32 v3, 16, v56
	v_pk_fma_f32 v[48:49], v[54:55], s[72:73], v[48:49] op_sel_hi:[1,0,1]
	v_cvt_pk_bf16_f32 v55, v50, v51
	v_cvt_pk_bf16_f32 v54, v48, v49
	v_and_b32_e32 v49, 0xffff0000, v56
	v_lshlrev_b32_e32 v51, 16, v57
	v_and_b32_e32 v58, 0xffff0000, v57
	global_store_dwordx2 v[60:61], v[54:55], off
	v_sub_f32_e32 v57, v49, v64
	v_sub_f32_e32 v56, v3, v64
	v_sub_f32_e32 v59, v58, v64
	v_sub_f32_e32 v58, v51, v64
	v_pk_mul_f32 v[62:63], v[66:67], v[58:59] op_sel_hi:[0,1]
	v_pk_mul_f32 v[72:73], v[66:67], v[56:57] op_sel_hi:[0,1]
	ds_read_b128 v[56:59], v244 offset:64
	ds_read_b128 v[68:71], v244 offset:320
	v_and_b32_e32 v50, 0xffff0000, v54
	v_lshlrev_b32_e32 v48, 16, v55
	s_waitcnt lgkmcnt(0)
	v_pk_fma_f32 v[56:57], v[56:57], v[72:73], v[68:69]
	s_nop 0
	v_pk_fma_f32 v[44:45], v[56:57], s[72:73], v[44:45] op_sel_hi:[1,0,1]
	s_waitcnt vmcnt(11)
	v_mov_b64_e32 v[56:57], v[238:239]
	global_load_dwordx2 v[238:239], v243, s[70:71] offset:256
	v_pk_fma_f32 v[58:59], v[58:59], v[62:63], v[70:71]
	v_cvt_pk_bf16_f32 v62, v44, v45
	v_pk_fma_f32 v[46:47], v[58:59], s[72:73], v[46:47] op_sel_hi:[1,0,1]
	s_waitcnt lgkmcnt(0)
	v_lshlrev_b32_e32 v3, 16, v56
	v_cvt_pk_bf16_f32 v63, v46, v47
	v_lshlrev_b32_e32 v46, 16, v63
	v_and_b32_e32 v47, 0xffff0000, v63
	v_mul_f32_e32 v44, v46, v46
	v_pk_fma_f32 v[44:45], v[46:47], v[46:47], v[44:45] op_sel_hi:[1,1,0]
	v_lshlrev_b32_e32 v49, 16, v57
	v_and_b32_e32 v44, 0xffff0000, v56
	v_and_b32_e32 v51, 0xffff0000, v57
	global_store_dwordx2 v[60:61], v[62:63], off offset:32
	v_sub_f32_e32 v57, v44, v64
	v_sub_f32_e32 v56, v3, v64
	v_sub_f32_e32 v59, v51, v64
	v_sub_f32_e32 v58, v49, v64
	v_pk_mul_f32 v[72:73], v[66:67], v[58:59] op_sel_hi:[0,1]
	v_pk_mul_f32 v[74:75], v[66:67], v[56:57] op_sel_hi:[0,1]
	ds_read_b128 v[56:59], v244 offset:128
	ds_read_b128 v[68:71], v244 offset:384
	v_and_b32_e32 v63, 0xffff0000, v62
	s_waitcnt lgkmcnt(0)
	v_pk_fma_f32 v[56:57], v[56:57], v[74:75], v[68:69]
	s_waitcnt vmcnt(11)
	v_mov_b64_e32 v[68:69], v[240:241]
	global_load_dwordx2 v[240:241], v243, s[70:71] offset:288
	v_pk_fma_f32 v[58:59], v[58:59], v[72:73], v[70:71]
	v_pk_fma_f32 v[40:41], v[56:57], s[72:73], v[40:41] op_sel_hi:[1,0,1]
	v_pk_fma_f32 v[42:43], v[58:59], s[72:73], v[42:43] op_sel_hi:[1,0,1]
	v_cvt_pk_bf16_f32 v40, v40, v41
	v_cvt_pk_bf16_f32 v41, v42, v43
	global_store_dwordx2 v[60:61], v[40:41], off offset:256
	v_lshlrev_b32_e32 v56, 16, v40
	v_and_b32_e32 v58, 0xffff0000, v40
	v_lshlrev_b32_e32 v40, 16, v41
	v_and_b32_e32 v42, 0xffff0000, v41
	v_mul_f32_e32 v57, v56, v56
	v_mul_f32_e32 v59, v58, v58
	v_mul_f32_e32 v41, v40, v40
	v_mul_f32_e32 v43, v42, v42
	v_pk_add_f32 v[40:41], v[40:41], v[42:43]
	s_waitcnt lgkmcnt(0)
	v_lshlrev_b32_e32 v3, 16, v68
	v_and_b32_e32 v44, 0xffff0000, v68
	v_lshlrev_b32_e32 v49, 16, v69
	v_and_b32_e32 v51, 0xffff0000, v69
	v_sub_f32_e32 v69, v44, v64
	v_sub_f32_e32 v68, v3, v64
	v_sub_f32_e32 v65, v51, v64
	v_sub_f32_e32 v64, v49, v64
	v_pk_mul_f32 v[64:65], v[66:67], v[64:65] op_sel_hi:[0,1]
	v_pk_mul_f32 v[66:67], v[66:67], v[68:69] op_sel_hi:[0,1]
	ds_read_b128 v[68:71], v244 offset:192
	ds_read_b128 v[72:75], v244 offset:448
	v_mov_b32_e32 v49, v63
	v_mov_b32_e32 v3, v45
	s_waitcnt lgkmcnt(0)
; __device__ __forceinline__ u32x2 pk4(f32x4 v) { u32x2 r; r.x = pk2(v.x, v.y); r.y = pk2(v.z, v.w); return r; }
; __device__ __forceinline__ void stats_main(const float* stm, int row, int fq, float& mu, float& rs) {
;     const f32x4* p = (const f32x4*)(stm + (size_t)row * 32 + fq * 8);
;     const f32x4 a = p[0], b = p[1];
;     float s1 = (a.x + a.z) + (b.x + b.z), s2 = (a.y + a.w) + (b.y + b.w);
;     s1 += __shfl_xor(s1, 16); s2 += __shfl_xor(s2, 16); s1 += __shfl_xor(s1, 32); s2 += __shfl_xor(s2, 32);
;     mu = s1 * (1.f / DM); rs = __builtin_amdgcn_rsqf(fmaxf(s2 * (1.f / DM) - mu * mu, 0.f) + LN_EPS);
; }
;     __device__ __forceinline__ void operator()(const f32x4 (&acc)[2][2][4][2], const pg8::Unit& u, int wr, int wc, int fr, int fq) const {
;     ...
;                 for (int bj = 0; bj < 2; ++bj)
; #pragma unroll
;                     for (int n = 0; n < 2; ++n) {
;                         const int col = u.pn * 256 + bj * 128 + wc * 32 + n * 16 + fq * 4;
;                         const u32x2 raw = *(const u32x2*)(src + (size_t)row * DM + col);
;                         f32x4 x = (f32x4){bflo(raw.x), bfhi(raw.x), bflo(raw.y), bfhi(raw.y)};
;                         if (ln) x = (x - mu) * rs * *(const f32x4*)(g + col) + *(const f32x4*)(b + col);
;                         const u32x2 pz = pk4(x * ALPHA + acc[ai][bj][m][n]);
;                         *(u32x2*)(dst + (size_t)row * DM + col) = pz;
;                         const float z0 = bflo(pz.x), z1 = bfhi(pz.x), z2 = bflo(pz.y), z3 = bfhi(pz.y);
;                         s1 += (z0 + z1) + (z2 + z3); s2 += (z0 * z0 + z1 * z1) + (z2 * z2 + z3 * z3);
;                     }
;                 s1 += __shfl_xor(s1, 16); s2 += __shfl_xor(s2, 16); s1 += __shfl_xor(s1, 32); s2 += __shfl_xor(s2, 32);
;                 if (fq == 0) { float* p = stm_n + (size_t)row * 32 + (u.pn * 4 + wc) * 2; p[0] = s1; p[1] = s2; }
	v_pk_fma_f32 v[66:67], v[68:69], v[66:67], v[72:73]
	s_nop 0
	v_pk_fma_f32 v[36:37], v[66:67], s[72:73], v[36:37] op_sel_hi:[1,0,1]
	v_lshlrev_b32_e32 v67, 16, v62
	v_lshlrev_b32_e32 v66, 16, v54
	v_mov_b32_e32 v51, v67
	v_pk_fma_f32 v[64:65], v[70:71], v[64:65], v[74:75]
	v_pk_mul_f32 v[68:69], v[66:67], v[66:67]
	v_pk_mul_f32 v[70:71], v[50:51], v[50:51]
	v_and_b32_e32 v62, 0xffff0000, v55
	v_pk_mul_f32 v[54:55], v[48:49], v[48:49]
	v_pk_mul_f32 v[72:73], v[62:63], v[62:63]
	v_pk_mov_b32 v[74:75], v[66:67], v[68:69] op_sel:[1,0]
	v_pk_mov_b32 v[70:71], v[62:63], v[70:71] op_sel:[1,0]
	v_pk_add_f32 v[50:51], v[66:67], v[50:51]
	v_pk_add_f32 v[48:49], v[62:63], v[48:49]
	v_pk_fma_f32 v[38:39], v[64:65], s[72:73], v[38:39] op_sel_hi:[1,0,1]
	v_pk_add_f32 v[70:71], v[74:75], v[70:71]
	v_mov_b32_e32 v74, v46
	v_mov_b32_e32 v75, v54
	v_pk_mov_b32 v[46:47], v[46:47], v[72:73] op_sel:[1,0]
	v_mov_b32_e32 v51, v69
	v_mov_b32_e32 v49, v73
	v_cvt_pk_bf16_f32 v36, v36, v37
	v_cvt_pk_bf16_f32 v37, v38, v39
	v_pk_add_f32 v[46:47], v[74:75], v[46:47]
	v_pk_add_f32 v[48:49], v[50:51], v[48:49]
	global_store_dwordx2 v[60:61], v[36:37], off offset:288
	v_lshlrev_b32_e32 v60, 16, v36
	v_and_b32_e32 v64, 0xffff0000, v36
	v_lshlrev_b32_e32 v36, 16, v37
	v_and_b32_e32 v38, 0xffff0000, v37
	v_pk_add_f32 v[46:47], v[70:71], v[46:47]
	v_pk_add_f32 v[44:45], v[48:49], v[2:3]
	v_mul_f32_e32 v61, v60, v60
	v_mul_f32_e32 v65, v64, v64
	v_mul_f32_e32 v37, v36, v36
	v_mul_f32_e32 v39, v38, v38
	v_pk_add_f32 v[44:45], v[46:47], v[44:45]
	v_pk_add_f32 v[46:47], v[56:57], v[58:59]
	v_pk_add_f32 v[42:43], v[60:61], v[64:65]
	v_pk_add_f32 v[40:41], v[46:47], v[40:41]
	v_pk_add_f32 v[36:37], v[36:37], v[38:39]
	v_pk_add_f32 v[40:41], v[44:45], v[40:41]
	v_pk_add_f32 v[36:37], v[42:43], v[36:37]
	s_nop 0
	v_pk_add_f32 v[36:37], v[40:41], v[36:37]
	ds_bpermute_b32 v38, v181, v36
	ds_bpermute_b32 v39, v181, v37
	s_waitcnt lgkmcnt(0)
	v_pk_add_f32 v[36:37], v[36:37], v[38:39]
	ds_bpermute_b32 v38, v180, v36
	ds_bpermute_b32 v39, v180, v37
	s_and_saveexec_b64 s[0:1], s[40:41]
	s_cbranch_execz .LBB0_2389
	v_lshl_add_u64 v[40:41], s[52:53], 0, v[52:53]
	v_lshl_add_u64 v[40:41], s[68:69], 2, v[40:41]
	s_waitcnt lgkmcnt(0)
	v_pk_add_f32 v[36:37], v[36:37], v[38:39]
	global_store_dwordx2 v[40:41], v[36:37], off
.LBB0_2389:
	s_or_b64 exec, exec, s[0:1]
	v_add_u32_e32 v46, 0xa0, v146
	v_ashrrev_i32_e32 v47, 31, v46
	v_lshlrev_b64 v[36:37], 7, v[46:47]
	v_lshl_add_u64 v[42:43], v[134:135], 0, v[36:37]
	s_waitcnt lgkmcnt(0)
	s_waitcnt vmcnt(11)
	v_mov_b64_e32 v[38:39], v[190:191]
	v_mov_b64_e32 v[40:41], v[192:193]
	s_nop 0
	s_waitcnt vmcnt(10)
	v_mov_b64_e32 v[42:43], v[194:195]
	v_mov_b64_e32 v[44:45], v[196:197]
	s_waitcnt lgkmcnt(0)
	v_pk_add_f32 v[38:39], v[38:39], v[40:41]
	s_waitcnt lgkmcnt(0)
	v_pk_add_f32 v[42:43], v[42:43], v[44:45]
	s_nop 0
	v_pk_add_f32 v[38:39], v[42:43], v[38:39]
	ds_bpermute_b32 v40, v181, v38
	ds_bpermute_b32 v41, v181, v39
	s_waitcnt lgkmcnt(0)
	v_pk_add_f32 v[38:39], v[38:39], v[40:41]
	ds_bpermute_b32 v40, v180, v38
	ds_bpermute_b32 v41, v180, v39
	s_waitcnt lgkmcnt(0)
	v_pk_add_f32 v[38:39], v[38:39], v[40:41]
	s_nop 0
	v_pk_mul_f32 v[48:49], v[38:39], s[82:83] op_sel_hi:[1,0]
	v_lshlrev_b64 v[38:39], 11, v[46:47]
	v_lshl_add_u64 v[38:39], s[70:71], 0, v[38:39]
	v_lshl_add_u64 v[44:45], v[144:145], 1, v[38:39]
	s_waitcnt vmcnt(9)
	v_mov_b64_e32 v[38:39], v[198:199]
	v_fma_f32 v3, -v48, v48, v49
	v_max_f32_e32 v3, 0, v3
	v_add_f32_e32 v3, 0x3727c5ac, v3
	v_rsq_f32_e32 v50, v3
	s_waitcnt lgkmcnt(0)
	v_lshlrev_b32_e32 v3, 16, v38
	v_and_b32_e32 v38, 0xffff0000, v38
	v_lshlrev_b32_e32 v40, 16, v39
	v_and_b32_e32 v41, 0xffff0000, v39
	v_sub_f32_e32 v39, v38, v48
	v_sub_f32_e32 v38, v3, v48
	v_sub_f32_e32 v41, v41, v48
	v_sub_f32_e32 v40, v40, v48
	v_pk_mul_f32 v[42:43], v[40:41], v[50:51] op_sel_hi:[1,0]
	v_pk_mul_f32 v[46:47], v[38:39], v[50:51] op_sel_hi:[1,0]
	ds_read_b128 v[38:41], v244
	ds_read_b128 v[52:55], v244 offset:256
	s_waitcnt lgkmcnt(0)
	v_pk_fma_f32 v[40:41], v[40:41], v[42:43], v[54:55]
	s_nop 0
	v_pk_fma_f32 v[34:35], v[40:41], s[72:73], v[34:35] op_sel_hi:[1,0,1]
	s_waitcnt vmcnt(8)
	v_mov_b64_e32 v[40:41], v[200:201]
	v_pk_fma_f32 v[38:39], v[38:39], v[46:47], v[52:53]
	s_waitcnt lgkmcnt(0)
	v_lshlrev_b32_e32 v3, 16, v40
	v_pk_fma_f32 v[32:33], v[38:39], s[72:73], v[32:33] op_sel_hi:[1,0,1]
	v_cvt_pk_bf16_f32 v39, v34, v35
	v_cvt_pk_bf16_f32 v38, v32, v33
	v_and_b32_e32 v33, 0xffff0000, v40
	v_lshlrev_b32_e32 v35, 16, v41
	v_and_b32_e32 v42, 0xffff0000, v41
	global_store_dwordx2 v[44:45], v[38:39], off
	v_sub_f32_e32 v41, v33, v48
	v_sub_f32_e32 v40, v3, v48
	v_sub_f32_e32 v43, v42, v48
	v_sub_f32_e32 v42, v35, v48
	v_pk_mul_f32 v[46:47], v[50:51], v[42:43] op_sel_hi:[0,1]
	v_pk_mul_f32 v[56:57], v[50:51], v[40:41] op_sel_hi:[0,1]
	ds_read_b128 v[40:43], v244 offset:64
	ds_read_b128 v[52:55], v244 offset:320
	v_and_b32_e32 v34, 0xffff0000, v38
	v_lshlrev_b32_e32 v32, 16, v39
	s_waitcnt lgkmcnt(0)
	v_pk_fma_f32 v[40:41], v[40:41], v[56:57], v[52:53]
	s_nop 0
	v_pk_fma_f32 v[28:29], v[40:41], s[72:73], v[28:29] op_sel_hi:[1,0,1]
	s_waitcnt vmcnt(7)
	v_mov_b64_e32 v[40:41], v[202:203]
	v_pk_fma_f32 v[42:43], v[42:43], v[46:47], v[54:55]
	v_cvt_pk_bf16_f32 v46, v28, v29
	v_pk_fma_f32 v[30:31], v[42:43], s[72:73], v[30:31] op_sel_hi:[1,0,1]
	s_waitcnt lgkmcnt(0)
; __device__ __forceinline__ u32x2 pk4(f32x4 v) { u32x2 r; r.x = pk2(v.x, v.y); r.y = pk2(v.z, v.w); return r; }
;     __device__ __forceinline__ void operator()(const f32x4 (&acc)[2][2][4][2], const pg8::Unit& u, int wr, int wc, int fr, int fq) const {
;     ...
;                 for (int bj = 0; bj < 2; ++bj)
; #pragma unroll
;                     for (int n = 0; n < 2; ++n) {
;                         const int col = u.pn * 256 + bj * 128 + wc * 32 + n * 16 + fq * 4;
;                         const u32x2 raw = *(const u32x2*)(src + (size_t)row * DM + col);
;                         f32x4 x = (f32x4){bflo(raw.x), bfhi(raw.x), bflo(raw.y), bfhi(raw.y)};
;                         if (ln) x = (x - mu) * rs * *(const f32x4*)(g + col) + *(const f32x4*)(b + col);
;                         const u32x2 pz = pk4(x * ALPHA + acc[ai][bj][m][n]);
;                         *(u32x2*)(dst + (size_t)row * DM + col) = pz;
;                         const float z0 = bflo(pz.x), z1 = bfhi(pz.x), z2 = bflo(pz.y), z3 = bfhi(pz.y);
;                         s1 += (z0 + z1) + (z2 + z3); s2 += (z0 * z0 + z1 * z1) + (z2 * z2 + z3 * z3);
;                     }
;                 s1 += __shfl_xor(s1, 16); s2 += __shfl_xor(s2, 16); s1 += __shfl_xor(s1, 32); s2 += __shfl_xor(s2, 32);
;                 if (fq == 0) { float* p = stm_n + (size_t)row * 32 + (u.pn * 4 + wc) * 2; p[0] = s1; p[1] = s2; }
	v_lshlrev_b32_e32 v3, 16, v40
	v_cvt_pk_bf16_f32 v47, v30, v31
	v_lshlrev_b32_e32 v30, 16, v47
	v_and_b32_e32 v31, 0xffff0000, v47
	v_mul_f32_e32 v28, v30, v30
	v_pk_fma_f32 v[28:29], v[30:31], v[30:31], v[28:29] op_sel_hi:[1,1,0]
	v_lshlrev_b32_e32 v33, 16, v41
	v_and_b32_e32 v28, 0xffff0000, v40
	v_and_b32_e32 v35, 0xffff0000, v41
	global_store_dwordx2 v[44:45], v[46:47], off offset:32
	v_sub_f32_e32 v41, v28, v48
	v_sub_f32_e32 v40, v3, v48
	v_sub_f32_e32 v43, v35, v48
	v_sub_f32_e32 v42, v33, v48
	v_pk_mul_f32 v[56:57], v[50:51], v[42:43] op_sel_hi:[0,1]
	v_pk_mul_f32 v[58:59], v[50:51], v[40:41] op_sel_hi:[0,1]
	ds_read_b128 v[40:43], v244 offset:128
	ds_read_b128 v[52:55], v244 offset:384
	v_and_b32_e32 v47, 0xffff0000, v46
	s_waitcnt lgkmcnt(0)
	v_pk_fma_f32 v[40:41], v[40:41], v[58:59], v[52:53]
	s_waitcnt vmcnt(6)
	v_mov_b64_e32 v[52:53], v[204:205]
	v_pk_fma_f32 v[42:43], v[42:43], v[56:57], v[54:55]
	v_pk_fma_f32 v[24:25], v[40:41], s[72:73], v[24:25] op_sel_hi:[1,0,1]
	v_pk_fma_f32 v[26:27], v[42:43], s[72:73], v[26:27] op_sel_hi:[1,0,1]
	v_cvt_pk_bf16_f32 v24, v24, v25
	v_cvt_pk_bf16_f32 v25, v26, v27
	global_store_dwordx2 v[44:45], v[24:25], off offset:256
	v_lshlrev_b32_e32 v40, 16, v24
	v_and_b32_e32 v42, 0xffff0000, v24
	v_lshlrev_b32_e32 v24, 16, v25
	v_and_b32_e32 v26, 0xffff0000, v25
	v_mul_f32_e32 v41, v40, v40
	v_mul_f32_e32 v43, v42, v42
	v_mul_f32_e32 v25, v24, v24
	v_mul_f32_e32 v27, v26, v26
	v_pk_add_f32 v[24:25], v[24:25], v[26:27]
	s_waitcnt lgkmcnt(0)
	v_lshlrev_b32_e32 v3, 16, v52
	v_and_b32_e32 v28, 0xffff0000, v52
	v_lshlrev_b32_e32 v33, 16, v53
	v_and_b32_e32 v35, 0xffff0000, v53
	v_sub_f32_e32 v53, v28, v48
	v_sub_f32_e32 v52, v3, v48
	v_sub_f32_e32 v49, v35, v48
	v_sub_f32_e32 v48, v33, v48
	v_pk_mul_f32 v[48:49], v[50:51], v[48:49] op_sel_hi:[0,1]
	v_pk_mul_f32 v[50:51], v[50:51], v[52:53] op_sel_hi:[0,1]
	ds_read_b128 v[52:55], v244 offset:192
	ds_read_b128 v[56:59], v244 offset:448
	v_mov_b32_e32 v33, v47
	v_mov_b32_e32 v3, v29
	s_waitcnt lgkmcnt(0)
	v_pk_fma_f32 v[50:51], v[52:53], v[50:51], v[56:57]
	s_nop 0
	v_pk_fma_f32 v[20:21], v[50:51], s[72:73], v[20:21] op_sel_hi:[1,0,1]
	v_lshlrev_b32_e32 v51, 16, v46
	v_lshlrev_b32_e32 v50, 16, v38
	v_mov_b32_e32 v35, v51
	v_pk_fma_f32 v[48:49], v[54:55], v[48:49], v[58:59]
	v_pk_mul_f32 v[52:53], v[50:51], v[50:51]
	v_pk_mul_f32 v[54:55], v[34:35], v[34:35]
	v_and_b32_e32 v46, 0xffff0000, v39
	v_pk_mul_f32 v[38:39], v[32:33], v[32:33]
	v_pk_mul_f32 v[56:57], v[46:47], v[46:47]
	v_pk_mov_b32 v[58:59], v[50:51], v[52:53] op_sel:[1,0]
	v_pk_mov_b32 v[54:55], v[46:47], v[54:55] op_sel:[1,0]
	v_pk_add_f32 v[34:35], v[50:51], v[34:35]
	v_pk_add_f32 v[32:33], v[46:47], v[32:33]
	v_pk_fma_f32 v[22:23], v[48:49], s[72:73], v[22:23] op_sel_hi:[1,0,1]
	v_pk_add_f32 v[54:55], v[58:59], v[54:55]
	v_mov_b32_e32 v58, v30
	v_mov_b32_e32 v59, v38
	v_pk_mov_b32 v[30:31], v[30:31], v[56:57] op_sel:[1,0]
	v_mov_b32_e32 v35, v53
	v_mov_b32_e32 v33, v57
	v_cvt_pk_bf16_f32 v20, v20, v21
	v_cvt_pk_bf16_f32 v21, v22, v23
	v_pk_add_f32 v[30:31], v[58:59], v[30:31]
	v_pk_add_f32 v[32:33], v[34:35], v[32:33]
	global_store_dwordx2 v[44:45], v[20:21], off offset:288
	v_lshlrev_b32_e32 v44, 16, v20
	v_and_b32_e32 v48, 0xffff0000, v20
	v_lshlrev_b32_e32 v20, 16, v21
	v_and_b32_e32 v22, 0xffff0000, v21
	v_pk_add_f32 v[30:31], v[54:55], v[30:31]
	v_pk_add_f32 v[28:29], v[32:33], v[2:3]
	v_mul_f32_e32 v45, v44, v44
	v_mul_f32_e32 v49, v48, v48
	v_mul_f32_e32 v21, v20, v20
	v_mul_f32_e32 v23, v22, v22
	v_pk_add_f32 v[28:29], v[30:31], v[28:29]
	v_pk_add_f32 v[30:31], v[40:41], v[42:43]
	v_pk_add_f32 v[26:27], v[44:45], v[48:49]
	v_pk_add_f32 v[24:25], v[30:31], v[24:25]
	v_pk_add_f32 v[20:21], v[20:21], v[22:23]
	v_pk_add_f32 v[24:25], v[28:29], v[24:25]
	v_pk_add_f32 v[20:21], v[26:27], v[20:21]
	s_nop 0
	v_pk_add_f32 v[20:21], v[24:25], v[20:21]
	ds_bpermute_b32 v22, v181, v20
	ds_bpermute_b32 v23, v181, v21
	s_waitcnt lgkmcnt(0)
	v_pk_add_f32 v[20:21], v[20:21], v[22:23]
	ds_bpermute_b32 v22, v180, v20
	ds_bpermute_b32 v23, v180, v21
	s_and_saveexec_b64 s[0:1], s[40:41]
	s_cbranch_execz .LBB0_2391
	v_lshl_add_u64 v[24:25], s[52:53], 0, v[36:37]
	v_lshl_add_u64 v[24:25], s[68:69], 2, v[24:25]
	s_waitcnt lgkmcnt(0)
	v_pk_add_f32 v[20:21], v[20:21], v[22:23]
	global_store_dwordx2 v[24:25], v[20:21], off
; __device__ __forceinline__ u32x2 pk4(f32x4 v) { u32x2 r; r.x = pk2(v.x, v.y); r.y = pk2(v.z, v.w); return r; }
; __device__ __forceinline__ void stats_main(const float* stm, int row, int fq, float& mu, float& rs) {
;     const f32x4* p = (const f32x4*)(stm + (size_t)row * 32 + fq * 8);
;     const f32x4 a = p[0], b = p[1];
;     float s1 = (a.x + a.z) + (b.x + b.z), s2 = (a.y + a.w) + (b.y + b.w);
;     s1 += __shfl_xor(s1, 16); s2 += __shfl_xor(s2, 16); s1 += __shfl_xor(s1, 32); s2 += __shfl_xor(s2, 32);
;     mu = s1 * (1.f / DM); rs = __builtin_amdgcn_rsqf(fmaxf(s2 * (1.f / DM) - mu * mu, 0.f) + LN_EPS);
; }
;     __device__ __forceinline__ void operator()(const f32x4 (&acc)[2][2][4][2], const pg8::Unit& u, int wr, int wc, int fr, int fq) const {
;     ...
;                 const int row = u.pm * 256 + ai * 128 + wr * 64 + m * 16 + fr;
;                 float mu = 0.f, rs = 1.f; if (ln) stats_main(stm_p, row, fq, mu, rs);
;                 float s1 = 0.f, s2 = 0.f;
; #pragma unroll
;                 for (int bj = 0; bj < 2; ++bj)
; #pragma unroll
;                     for (int n = 0; n < 2; ++n) {
;                         const int col = u.pn * 256 + bj * 128 + wc * 32 + n * 16 + fq * 4;
;                         const u32x2 raw = *(const u32x2*)(src + (size_t)row * DM + col);
;                         f32x4 x = (f32x4){bflo(raw.x), bfhi(raw.x), bflo(raw.y), bfhi(raw.y)};
;                         if (ln) x = (x - mu) * rs * *(const f32x4*)(g + col) + *(const f32x4*)(b + col);
;                         const u32x2 pz = pk4(x * ALPHA + acc[ai][bj][m][n]);
;                         *(u32x2*)(dst + (size_t)row * DM + col) = pz;
.LBB0_2391:
	s_or_b64 exec, exec, s[0:1]
	v_add_u32_e32 v30, 0xb0, v146
	v_ashrrev_i32_e32 v31, 31, v30
	v_lshlrev_b64 v[20:21], 7, v[30:31]
	v_lshl_add_u64 v[26:27], v[134:135], 0, v[20:21]
	s_waitcnt lgkmcnt(0)
	s_waitcnt vmcnt(5)
	v_mov_b64_e32 v[22:23], v[206:207]
	v_mov_b64_e32 v[24:25], v[208:209]
	s_nop 0
	s_waitcnt vmcnt(4)
	v_mov_b64_e32 v[26:27], v[214:215]
	v_mov_b64_e32 v[28:29], v[216:217]
	s_waitcnt lgkmcnt(0)
	v_pk_add_f32 v[22:23], v[22:23], v[24:25]
	s_waitcnt lgkmcnt(0)
	v_pk_add_f32 v[26:27], v[26:27], v[28:29]
	s_nop 0
	v_pk_add_f32 v[22:23], v[26:27], v[22:23]
	ds_bpermute_b32 v24, v181, v22
	ds_bpermute_b32 v25, v181, v23
	s_waitcnt lgkmcnt(0)
	v_pk_add_f32 v[22:23], v[22:23], v[24:25]
	ds_bpermute_b32 v24, v180, v22
	ds_bpermute_b32 v25, v180, v23
	s_waitcnt lgkmcnt(0)
	v_pk_add_f32 v[22:23], v[22:23], v[24:25]
	s_nop 0
	v_pk_mul_f32 v[32:33], v[22:23], s[82:83] op_sel_hi:[1,0]
	v_lshlrev_b64 v[22:23], 11, v[30:31]
	v_lshl_add_u64 v[22:23], s[70:71], 0, v[22:23]
	v_lshl_add_u64 v[28:29], v[144:145], 1, v[22:23]
	s_waitcnt vmcnt(3)
	v_mov_b64_e32 v[22:23], v[234:235]
	v_fma_f32 v3, -v32, v32, v33
	v_max_f32_e32 v3, 0, v3
	v_add_f32_e32 v3, 0x3727c5ac, v3
	v_rsq_f32_e32 v34, v3
	s_waitcnt lgkmcnt(0)
	v_lshlrev_b32_e32 v3, 16, v22
	v_and_b32_e32 v22, 0xffff0000, v22
	v_lshlrev_b32_e32 v24, 16, v23
	v_and_b32_e32 v25, 0xffff0000, v23
	v_sub_f32_e32 v23, v22, v32
	v_sub_f32_e32 v22, v3, v32
	v_sub_f32_e32 v25, v25, v32
	v_sub_f32_e32 v24, v24, v32
	v_pk_mul_f32 v[26:27], v[24:25], v[34:35] op_sel_hi:[1,0]
	v_pk_mul_f32 v[30:31], v[22:23], v[34:35] op_sel_hi:[1,0]
	ds_read_b128 v[22:25], v244
	ds_read_b128 v[36:39], v244 offset:256
	s_waitcnt lgkmcnt(0)
	v_pk_fma_f32 v[24:25], v[24:25], v[26:27], v[38:39]
	s_nop 0
	v_pk_fma_f32 v[18:19], v[24:25], s[72:73], v[18:19] op_sel_hi:[1,0,1]
	s_waitcnt vmcnt(2)
	v_mov_b64_e32 v[24:25], v[236:237]
	v_pk_fma_f32 v[22:23], v[22:23], v[30:31], v[36:37]
	s_waitcnt lgkmcnt(0)
	v_lshlrev_b32_e32 v3, 16, v24
	v_pk_fma_f32 v[16:17], v[22:23], s[72:73], v[16:17] op_sel_hi:[1,0,1]
	v_cvt_pk_bf16_f32 v23, v18, v19
	v_cvt_pk_bf16_f32 v22, v16, v17
	v_and_b32_e32 v17, 0xffff0000, v24
	v_lshlrev_b32_e32 v19, 16, v25
	v_and_b32_e32 v26, 0xffff0000, v25
	global_store_dwordx2 v[28:29], v[22:23], off
	v_sub_f32_e32 v25, v17, v32
	v_sub_f32_e32 v24, v3, v32
	v_sub_f32_e32 v27, v26, v32
	v_sub_f32_e32 v26, v19, v32
	v_pk_mul_f32 v[30:31], v[34:35], v[26:27] op_sel_hi:[0,1]
	v_pk_mul_f32 v[40:41], v[34:35], v[24:25] op_sel_hi:[0,1]
	ds_read_b128 v[24:27], v244 offset:64
	ds_read_b128 v[36:39], v244 offset:320
	v_and_b32_e32 v18, 0xffff0000, v22
	v_lshlrev_b32_e32 v16, 16, v23
	s_waitcnt lgkmcnt(0)
	v_pk_fma_f32 v[24:25], v[24:25], v[40:41], v[36:37]
	s_nop 0
	v_pk_fma_f32 v[12:13], v[24:25], s[72:73], v[12:13] op_sel_hi:[1,0,1]
	s_waitcnt vmcnt(1)
	v_mov_b64_e32 v[24:25], v[238:239]
	v_pk_fma_f32 v[26:27], v[26:27], v[30:31], v[38:39]
	v_cvt_pk_bf16_f32 v30, v12, v13
	v_pk_fma_f32 v[14:15], v[26:27], s[72:73], v[14:15] op_sel_hi:[1,0,1]
	s_waitcnt lgkmcnt(0)
	v_lshlrev_b32_e32 v3, 16, v24
	v_cvt_pk_bf16_f32 v31, v14, v15
	v_lshlrev_b32_e32 v14, 16, v31
	v_and_b32_e32 v15, 0xffff0000, v31
	v_mul_f32_e32 v12, v14, v14
	v_pk_fma_f32 v[12:13], v[14:15], v[14:15], v[12:13] op_sel_hi:[1,1,0]
	v_lshlrev_b32_e32 v17, 16, v25
	v_and_b32_e32 v12, 0xffff0000, v24
	v_and_b32_e32 v19, 0xffff0000, v25
	global_store_dwordx2 v[28:29], v[30:31], off offset:32
	v_sub_f32_e32 v25, v12, v32
	v_sub_f32_e32 v24, v3, v32
	v_sub_f32_e32 v27, v19, v32
	v_sub_f32_e32 v26, v17, v32
	v_pk_mul_f32 v[40:41], v[34:35], v[26:27] op_sel_hi:[0,1]
	v_pk_mul_f32 v[42:43], v[34:35], v[24:25] op_sel_hi:[0,1]
	ds_read_b128 v[24:27], v244 offset:128
	ds_read_b128 v[36:39], v244 offset:384
	v_and_b32_e32 v31, 0xffff0000, v30
	s_waitcnt lgkmcnt(0)
; __device__ __forceinline__ u32x2 pk4(f32x4 v) { u32x2 r; r.x = pk2(v.x, v.y); r.y = pk2(v.z, v.w); return r; }
;     __device__ __forceinline__ void operator()(const f32x4 (&acc)[2][2][4][2], const pg8::Unit& u, int wr, int wc, int fr, int fq) const {
;     ...
;                 for (int bj = 0; bj < 2; ++bj)
; #pragma unroll
;                     for (int n = 0; n < 2; ++n) {
;                         const int col = u.pn * 256 + bj * 128 + wc * 32 + n * 16 + fq * 4;
;                         const u32x2 raw = *(const u32x2*)(src + (size_t)row * DM + col);
;                         f32x4 x = (f32x4){bflo(raw.x), bfhi(raw.x), bflo(raw.y), bfhi(raw.y)};
;                         if (ln) x = (x - mu) * rs * *(const f32x4*)(g + col) + *(const f32x4*)(b + col);
;                         const u32x2 pz = pk4(x * ALPHA + acc[ai][bj][m][n]);
;                         *(u32x2*)(dst + (size_t)row * DM + col) = pz;
;                         const float z0 = bflo(pz.x), z1 = bfhi(pz.x), z2 = bflo(pz.y), z3 = bfhi(pz.y);
;                         s1 += (z0 + z1) + (z2 + z3); s2 += (z0 * z0 + z1 * z1) + (z2 * z2 + z3 * z3);
;                     }
;                 s1 += __shfl_xor(s1, 16); s2 += __shfl_xor(s2, 16); s1 += __shfl_xor(s1, 32); s2 += __shfl_xor(s2, 32);
;                 if (fq == 0) { float* p = stm_n + (size_t)row * 32 + (u.pn * 4 + wc) * 2; p[0] = s1; p[1] = s2; }
	v_pk_fma_f32 v[24:25], v[24:25], v[42:43], v[36:37]
	s_waitcnt vmcnt(0)
	v_mov_b64_e32 v[36:37], v[240:241]
	v_pk_fma_f32 v[26:27], v[26:27], v[40:41], v[38:39]
	v_pk_fma_f32 v[8:9], v[24:25], s[72:73], v[8:9] op_sel_hi:[1,0,1]
	v_pk_fma_f32 v[10:11], v[26:27], s[72:73], v[10:11] op_sel_hi:[1,0,1]
	v_cvt_pk_bf16_f32 v8, v8, v9
	v_cvt_pk_bf16_f32 v9, v10, v11
	global_store_dwordx2 v[28:29], v[8:9], off offset:256
	v_lshlrev_b32_e32 v24, 16, v8
	v_and_b32_e32 v26, 0xffff0000, v8
	v_lshlrev_b32_e32 v8, 16, v9
	v_and_b32_e32 v10, 0xffff0000, v9
	v_mul_f32_e32 v25, v24, v24
	v_mul_f32_e32 v27, v26, v26
	v_mul_f32_e32 v9, v8, v8
	v_mul_f32_e32 v11, v10, v10
	v_pk_add_f32 v[8:9], v[8:9], v[10:11]
	s_waitcnt lgkmcnt(0)
	v_lshlrev_b32_e32 v3, 16, v36
	v_and_b32_e32 v12, 0xffff0000, v36
	v_lshlrev_b32_e32 v17, 16, v37
	v_and_b32_e32 v19, 0xffff0000, v37
	v_sub_f32_e32 v37, v12, v32
	v_sub_f32_e32 v36, v3, v32
	v_sub_f32_e32 v33, v19, v32
	v_sub_f32_e32 v32, v17, v32
	v_pk_mul_f32 v[32:33], v[34:35], v[32:33] op_sel_hi:[0,1]
	v_pk_mul_f32 v[34:35], v[34:35], v[36:37] op_sel_hi:[0,1]
	ds_read_b128 v[36:39], v244 offset:192
	ds_read_b128 v[40:43], v244 offset:448
	v_mov_b32_e32 v17, v31
	v_mov_b32_e32 v3, v13
	s_waitcnt lgkmcnt(0)
	v_pk_fma_f32 v[34:35], v[36:37], v[34:35], v[40:41]
	s_nop 0
	v_pk_fma_f32 v[4:5], v[34:35], s[72:73], v[4:5] op_sel_hi:[1,0,1]
	v_lshlrev_b32_e32 v35, 16, v30
	v_lshlrev_b32_e32 v34, 16, v22
	v_mov_b32_e32 v19, v35
	v_pk_fma_f32 v[32:33], v[38:39], v[32:33], v[42:43]
	v_pk_mul_f32 v[36:37], v[34:35], v[34:35]
	v_pk_mul_f32 v[38:39], v[18:19], v[18:19]
	v_and_b32_e32 v30, 0xffff0000, v23
	v_pk_mul_f32 v[22:23], v[16:17], v[16:17]
	v_pk_mul_f32 v[40:41], v[30:31], v[30:31]
	v_pk_mov_b32 v[42:43], v[34:35], v[36:37] op_sel:[1,0]
	v_pk_mov_b32 v[38:39], v[30:31], v[38:39] op_sel:[1,0]
	v_pk_add_f32 v[18:19], v[34:35], v[18:19]
	v_pk_add_f32 v[16:17], v[30:31], v[16:17]
	v_pk_fma_f32 v[6:7], v[32:33], s[72:73], v[6:7] op_sel_hi:[1,0,1]
	v_pk_add_f32 v[38:39], v[42:43], v[38:39]
	v_mov_b32_e32 v42, v14
	v_mov_b32_e32 v43, v22
	v_pk_mov_b32 v[14:15], v[14:15], v[40:41] op_sel:[1,0]
	v_mov_b32_e32 v19, v37
	v_mov_b32_e32 v17, v41
	v_cvt_pk_bf16_f32 v4, v4, v5
	v_cvt_pk_bf16_f32 v5, v6, v7
	v_pk_add_f32 v[14:15], v[42:43], v[14:15]
	v_pk_add_f32 v[16:17], v[18:19], v[16:17]
	global_store_dwordx2 v[28:29], v[4:5], off offset:288
	v_lshlrev_b32_e32 v28, 16, v4
	v_and_b32_e32 v32, 0xffff0000, v4
	v_lshlrev_b32_e32 v4, 16, v5
	v_and_b32_e32 v6, 0xffff0000, v5
	v_pk_add_f32 v[14:15], v[38:39], v[14:15]
	v_pk_add_f32 v[12:13], v[16:17], v[2:3]
	v_mul_f32_e32 v29, v28, v28
	v_mul_f32_e32 v33, v32, v32
	v_mul_f32_e32 v5, v4, v4
	v_mul_f32_e32 v7, v6, v6
	v_pk_add_f32 v[12:13], v[14:15], v[12:13]
	v_pk_add_f32 v[14:15], v[24:25], v[26:27]
	v_pk_add_f32 v[10:11], v[28:29], v[32:33]
	v_pk_add_f32 v[8:9], v[14:15], v[8:9]
	v_pk_add_f32 v[4:5], v[4:5], v[6:7]
	v_pk_add_f32 v[8:9], v[12:13], v[8:9]
	v_pk_add_f32 v[4:5], v[10:11], v[4:5]
	s_nop 0
	v_pk_add_f32 v[4:5], v[8:9], v[4:5]
	ds_bpermute_b32 v6, v181, v4
	ds_bpermute_b32 v7, v181, v5
	s_waitcnt lgkmcnt(0)
	v_pk_add_f32 v[4:5], v[4:5], v[6:7]
	ds_bpermute_b32 v6, v180, v4
	ds_bpermute_b32 v7, v180, v5
	s_and_saveexec_b64 s[0:1], s[40:41]
	s_cbranch_execz .LBB0_2393
	v_lshl_add_u64 v[8:9], s[52:53], 0, v[20:21]
	v_lshl_add_u64 v[8:9], s[68:69], 2, v[8:9]
	s_waitcnt lgkmcnt(0)
	v_pk_add_f32 v[4:5], v[4:5], v[6:7]
	global_store_dwordx2 v[8:9], v[4:5], off

; __device__ __forceinline__ void final_ln(const bf16_t* ZB, const float* gam, const float* bet, float* yout, int gw, int NGW, int lane) {
;     f32x4 gv[4], bv[4];
; #pragma unroll
;     for (int j = 0; j < 4; ++j) { gv[j] = *(const f32x4*)(gam + 4 * lane + 256 * j); bv[j] = *(const f32x4*)(bet + 4 * lane + 256 * j); }
;     for (int row = gw; row < MR; row += NGW) {
;         const u32x2* zr = (const u32x2*)(ZB + (size_t)row * DM) + lane;
;         f32x4 v[4]; float s = 0.f;
; #pragma unroll
;         for (int j = 0; j < 4; ++j) { const u32x2 raw = zr[64 * j]; v[j] = (f32x4){bflo(raw.x), bfhi(raw.x), bflo(raw.y), bfhi(raw.y)}; s += (v[j].x + v[j].y) + (v[j].z + v[j].w); }
.LBB0_2455:
	s_cmp_lt_i32 s24, 18
	s_cselect_b64 s[0:1], -1, 0
	s_cmp_gt_i32 s25, 17
	s_cselect_b64 s[2:3], -1, 0
	s_and_b64 s[2:3], s[0:1], s[2:3]
	v_readlane_b32 s18, v251, 63
	v_readlane_b32 s20, v253, 20
	s_andn2_b64 vcc, exec, s[2:3]
	v_readlane_b32 s19, v252, 0
	v_readlane_b32 s6, v250, 18
	v_readlane_b32 s21, v253, 21
	s_cbranch_vccnz .LBB0_2459
	v_readlane_b32 s2, v251, 38
	v_mbcnt_lo_u32_b32 v34, -1, 0
	v_mbcnt_hi_u32_b32 v34, -1, v34
	s_cmpk_lt_i32 s2, 0x4080
	v_readlane_b32 s3, v251, 39
	s_cbranch_scc0 .LBB0_2459
	v_lshlrev_b32_e32 v0, 2, v34
	v_readlane_b32 s36, v251, 22
	v_ashrrev_i32_e32 v1, 31, v0
	v_readlane_b32 s48, v251, 34
	v_readlane_b32 s49, v251, 35
	v_lshlrev_b64 v[0:1], 2, v[0:1]
	v_readlane_b32 s50, v251, 36
	v_readlane_b32 s51, v251, 37
	s_mov_b64 s[12:13], s[48:49]
	s_mov_b64 s[14:15], s[50:51]
	v_lshl_add_u64 v[2:3], s[12:13], 0, v[0:1]
	v_lshl_add_u64 v[4:5], s[14:15], 0, v[0:1]
	v_add_co_u32_e32 v0, vcc, 0x1000, v2
	s_mov_b32 s8, s2
	s_mov_b64 s[2:3], 0x1000
	v_addc_co_u32_e32 v1, vcc, 0, v3, vcc
	v_lshl_add_u64 v[28:29], v[4:5], 0, s[2:3]
	v_add_co_u32_e32 v4, vcc, 0x1000, v4
	v_lshl_add_u64 v[24:25], v[2:3], 0, s[2:3]
	s_nop 0
	v_addc_co_u32_e32 v5, vcc, 0, v5, vcc
	global_load_dwordx4 v[0:3], v[0:1], off
	s_waitcnt lgkmcnt(0)
	global_load_dwordx4 v[4:7], v[4:5], off
	s_nop 0
	global_load_dwordx4 v[8:11], v[24:25], off offset:1024
	global_load_dwordx4 v[12:15], v[24:25], off offset:2048
	global_load_dwordx4 v[16:19], v[28:29], off offset:1024
	global_load_dwordx4 v[20:23], v[28:29], off offset:2048
	s_nop 0
	global_load_dwordx4 v[24:27], v[24:25], off offset:3072
	s_nop 0
	global_load_dwordx4 v[28:31], v[28:29], off offset:3072
	v_and_b32_e32 v32, 64, v219
	v_add_u32_e32 v32, 64, v32
	v_xor_b32_e32 v33, 1, v219
	v_cmp_lt_i32_e32 vcc, v33, v32
	s_ashr_i32 s9, s8, 31
	v_readlane_b32 s12, v250, 10
	v_cndmask_b32_e32 v33, v219, v33, vcc
	v_lshlrev_b32_e32 v36, 2, v33
	v_xor_b32_e32 v33, 2, v219
	v_cmp_lt_i32_e32 vcc, v33, v32
	s_lshl_b64 s[2:3], s[8:9], 11
	v_readlane_b32 s14, v250, 12
	v_cndmask_b32_e32 v33, v219, v33, vcc
	v_lshlrev_b32_e32 v37, 2, v33
	v_xor_b32_e32 v33, 4, v219
	v_cmp_lt_i32_e32 vcc, v33, v32
	v_readlane_b32 s15, v250, 13
	s_add_u32 s2, s14, s2
	v_cndmask_b32_e32 v33, v219, v33, vcc
	v_lshlrev_b32_e32 v38, 2, v33
	v_xor_b32_e32 v33, 8, v219
	v_cmp_lt_i32_e32 vcc, v33, v32
	v_ashrrev_i32_e32 v35, 31, v34
	s_addc_u32 s3, s15, s3
	v_cndmask_b32_e32 v33, v219, v33, vcc
	v_lshlrev_b32_e32 v39, 2, v33
	v_xor_b32_e32 v33, 16, v219
	v_cmp_lt_i32_e32 vcc, v33, v32
	v_readlane_b32 s10, v250, 2
	v_readlane_b32 s11, v250, 3
	v_cndmask_b32_e32 v33, v219, v33, vcc
	v_lshlrev_b32_e32 v40, 2, v33
	v_xor_b32_e32 v33, 32, v219
	v_cmp_lt_i32_e32 vcc, v33, v32
	s_lshl_b64 s[4:5], s[8:9], 12
	v_readlane_b32 s13, v250, 11
	v_cndmask_b32_e32 v32, v219, v33, vcc
	v_lshlrev_b32_e32 v41, 2, v32
	v_lshl_add_u64 v[32:33], v[34:35], 3, s[2:3]
	s_mov_b64 s[2:3], 0x5b34100
	v_lshl_add_u64 v[32:33], v[32:33], 0, s[2:3]
	s_lshl_b64 s[2:3], s[10:11], 11
	s_add_u32 s4, s12, s4
	s_addc_u32 s5, s13, s5
	v_lshl_add_u64 v[34:35], v[34:35], 4, s[4:5]
	s_mov_b64 s[4:5], 0xc00
	v_lshl_add_u64 v[34:35], v[34:35], 0, s[4:5]
	v_readlane_b32 s4, v250, 4
	v_mov_b32_e32 v42, 0x3727c5ac
	v_readlane_b32 s5, v250, 5
	v_readlane_b32 s37, v251, 23
	v_readlane_b32 s38, v251, 24
	v_readlane_b32 s39, v251, 25
	v_readlane_b32 s40, v251, 26
	v_readlane_b32 s41, v251, 27
	v_readlane_b32 s42, v251, 28
	v_readlane_b32 s43, v251, 29
	v_readlane_b32 s44, v251, 30
	v_readlane_b32 s45, v251, 31
	v_readlane_b32 s46, v251, 32
	v_readlane_b32 s47, v251, 33
	global_load_dwordx2 v[44:45], v[32:33], off
	global_load_dwordx2 v[46:47], v[32:33], off offset:512
	global_load_dwordx2 v[48:49], v[32:33], off offset:1024
	global_load_dwordx2 v[50:51], v[32:33], off offset:1536
	v_lshl_add_u64 v[32:33], v[32:33], 0, s[2:3]
	s_waitcnt vmcnt(0)
; __device__ __forceinline__ void final_ln(const bf16_t* ZB, const float* gam, const float* bet, float* yout, int gw, int NGW, int lane) {
;     ...
;     for (int row = gw; row < MR; row += NGW) {
;         const u32x2* zr = (const u32x2*)(ZB + (size_t)row * DM) + lane;
;         f32x4 v[4]; float s = 0.f;
; #pragma unroll
;         for (int j = 0; j < 4; ++j) { const u32x2 raw = zr[64 * j]; v[j] = (f32x4){bflo(raw.x), bfhi(raw.x), bflo(raw.y), bfhi(raw.y)}; s += (v[j].x + v[j].y) + (v[j].z + v[j].w); }
;         const float mean = wave_sum(s) * (1.f / DM); float s2 = 0.f;
; #pragma unroll
;         for (int j = 0; j < 4; ++j) { v[j] = v[j] - mean; s2 += (v[j].x * v[j].x + v[j].y * v[j].y) + (v[j].z * v[j].z + v[j].w * v[j].w); }
;         const float rstd = __builtin_amdgcn_rsqf(wave_sum(s2) * (1.f / DM) + LN_EPS);
;         f32x4* o = (f32x4*)(yout + (size_t)row * DM) + lane;
; #pragma unroll
;         for (int j = 0; j < 4; ++j) o[64 * j] = v[j] * rstd * gv[j] + bv[j];
;     }
.LBB0_2458:
	global_load_dwordx2 v[80:81], v[32:33], off
	global_load_dwordx2 v[82:83], v[32:33], off offset:512
	global_load_dwordx2 v[84:85], v[32:33], off offset:1024
	global_load_dwordx2 v[86:87], v[32:33], off offset:1536
	s_add_i32 s8, s8, s10
	v_lshl_add_u64 v[32:33], v[32:33], 0, s[2:3]
	s_cmpk_lt_i32 s8, 0x4080
	v_lshlrev_b32_e32 v53, 16, v45
	v_lshlrev_b32_e32 v52, 16, v44
	v_and_b32_e32 v45, 0xffff0000, v45
	v_and_b32_e32 v44, 0xffff0000, v44
	v_lshlrev_b32_e32 v55, 16, v47
	v_lshlrev_b32_e32 v54, 16, v46
	v_and_b32_e32 v47, 0xffff0000, v47
	v_and_b32_e32 v46, 0xffff0000, v46
	v_pk_add_f32 v[64:65], v[52:53], v[44:45]
	v_pk_add_f32 v[66:67], v[54:55], v[46:47]
	v_lshlrev_b32_e32 v56, 16, v48
	v_and_b32_e32 v57, 0xffff0000, v48
	v_lshlrev_b32_e32 v48, 16, v49
	v_and_b32_e32 v49, 0xffff0000, v49
	v_and_b32_e32 v61, 0xffff0000, v50
	v_add_f32_e32 v43, v64, v65
	v_pk_add_f32 v[64:65], v[66:67], v[66:67] op_sel:[0,1] op_sel_hi:[1,0]
	v_lshlrev_b32_e32 v59, 16, v50
	v_lshlrev_b32_e32 v63, 16, v51
	v_and_b32_e32 v51, 0xffff0000, v51
	v_add_f32_e32 v62, v56, v57
	v_add_f32_e32 v50, v48, v49
	v_add_f32_e32 v58, 0, v43
	v_mov_b32_e32 v65, v61
	v_pk_add_f32 v[66:67], v[62:63], v[50:51]
	v_pk_add_f32 v[64:65], v[58:59], v[64:65]
	s_nop 0
	v_pk_add_f32 v[64:65], v[64:65], v[66:67]
	s_nop 0
	v_add_f32_e32 v43, v64, v65
	ds_bpermute_b32 v50, v36, v43
	s_waitcnt lgkmcnt(0)
	v_add_f32_e32 v43, v43, v50
	ds_bpermute_b32 v50, v37, v43
	s_waitcnt lgkmcnt(0)
	v_add_f32_e32 v43, v43, v50
	ds_bpermute_b32 v50, v38, v43
	s_waitcnt lgkmcnt(0)
	v_add_f32_e32 v43, v43, v50
	ds_bpermute_b32 v50, v39, v43
	s_waitcnt lgkmcnt(0)
	v_add_f32_e32 v43, v43, v50
	ds_bpermute_b32 v50, v40, v43
	s_waitcnt lgkmcnt(0)
	v_add_f32_e32 v43, v43, v50
	ds_bpermute_b32 v50, v41, v43
	s_waitcnt lgkmcnt(0)
	v_add_f32_e32 v43, v43, v50
	v_fmac_f32_e32 v44, 0xba800000, v43
	v_fmac_f32_e32 v45, 0xba800000, v43
	v_fmac_f32_e32 v53, 0xba800000, v43
	v_fmac_f32_e32 v46, 0xba800000, v43
	v_fmac_f32_e32 v47, 0xba800000, v43
	v_fmac_f32_e32 v55, 0xba800000, v43
	v_fmac_f32_e32 v52, 0xba800000, v43
	v_fmac_f32_e32 v54, 0xba800000, v43
	v_fmac_f32_e32 v56, 0xba800000, v43
	v_mov_b32_e32 v64, v53
	v_mov_b32_e32 v65, v45
	v_mov_b32_e32 v53, v44
	v_mov_b32_e32 v44, v55
	v_mov_b32_e32 v45, v47
	v_mov_b32_e32 v55, v46
	v_fmac_f32_e32 v57, 0xba800000, v43
	v_fmac_f32_e32 v48, 0xba800000, v43
	v_mul_f32_e32 v46, v56, v56
	v_pk_mul_f32 v[66:67], v[64:65], v[64:65]
	v_pk_mul_f32 v[68:69], v[52:53], v[52:53]
	v_pk_mul_f32 v[70:71], v[44:45], v[44:45]
	v_pk_mul_f32 v[72:73], v[54:55], v[54:55]
	v_fmac_f32_e32 v49, 0xba800000, v43
	v_fmac_f32_e32 v59, 0xba800000, v43
	v_mul_f32_e32 v58, v48, v48
	v_pk_fma_f32 v[46:47], v[56:57], v[56:57], v[46:47] op_sel_hi:[1,1,0]
	v_pk_mov_b32 v[76:77], v[68:69], v[66:67] op_sel:[1,0]
	v_mov_b32_e32 v69, v67
	v_pk_mov_b32 v[66:67], v[72:73], v[70:71] op_sel:[1,0]
	v_mov_b32_e32 v73, v71
	v_mov_b32_e32 v60, v59
	v_pk_fma_f32 v[74:75], v[48:49], v[48:49], v[58:59] op_sel_hi:[1,1,0]
	v_mul_f32_e32 v46, v59, v59
	v_pk_add_f32 v[58:59], v[76:77], v[68:69]
	v_pk_add_f32 v[66:67], v[66:67], v[72:73]
	v_fmac_f32_e32 v51, 0xba800000, v43
	v_fmac_f32_e32 v63, 0xba800000, v43
	v_fmac_f32_e32 v61, 0xba800000, v43
	v_pk_add_f32 v[58:59], v[58:59], v[58:59] op_sel_hi:[0,1]
	v_pk_add_f32 v[66:67], v[66:67], v[66:67] op_sel_hi:[0,1]
	v_mul_f32_e32 v74, v61, v61
	v_mul_f32_e32 v58, v63, v63
	v_mul_f32_e32 v66, v51, v51
	v_pk_add_f32 v[46:47], v[46:47], v[74:75]
	v_pk_add_f32 v[58:59], v[58:59], v[66:67]
	v_mov_b32_e32 v50, v63
	v_pk_add_f32 v[46:47], v[46:47], v[58:59]
	s_nop 0
	v_add_f32_e32 v43, v46, v47
	ds_bpermute_b32 v46, v36, v43
	s_waitcnt lgkmcnt(0)
	v_add_f32_e32 v43, v43, v46
	ds_bpermute_b32 v46, v37, v43
	s_waitcnt lgkmcnt(0)
	v_add_f32_e32 v43, v43, v46
	ds_bpermute_b32 v46, v38, v43
	s_waitcnt lgkmcnt(0)
	v_add_f32_e32 v43, v43, v46
	ds_bpermute_b32 v46, v39, v43
	s_waitcnt lgkmcnt(0)
	v_add_f32_e32 v43, v43, v46
	ds_bpermute_b32 v46, v40, v43
	s_waitcnt lgkmcnt(0)
	v_add_f32_e32 v43, v43, v46
	ds_bpermute_b32 v46, v41, v43
	s_waitcnt lgkmcnt(0)
	v_add_f32_e32 v43, v43, v46
	v_fmamk_f32 v43, v43, 0x3a800000, v42
	v_rsq_f32_e32 v46, v43
	s_nop 0
	v_pk_mul_f32 v[52:53], v[52:53], v[46:47] op_sel_hi:[1,0]
	v_pk_mul_f32 v[58:59], v[64:65], v[46:47] op_sel_hi:[1,0]
	v_pk_mul_f32 v[54:55], v[54:55], v[46:47] op_sel_hi:[1,0]
	v_pk_mul_f32 v[62:63], v[44:45], v[46:47] op_sel_hi:[1,0]
	v_pk_mul_f32 v[56:57], v[56:57], v[46:47] op_sel_hi:[1,0]
	v_pk_mul_f32 v[64:65], v[48:49], v[46:47] op_sel_hi:[1,0]
	v_pk_mul_f32 v[60:61], v[60:61], v[46:47] op_sel_hi:[1,0]
	v_pk_mul_f32 v[66:67], v[50:51], v[46:47] op_sel_hi:[1,0]
	v_pk_fma_f32 v[46:47], v[2:3], v[58:59], v[6:7]
	v_pk_fma_f32 v[44:45], v[0:1], v[52:53], v[4:5]
	v_pk_fma_f32 v[50:51], v[10:11], v[62:63], v[18:19]
	v_pk_fma_f32 v[48:49], v[8:9], v[54:55], v[16:17]
	v_pk_fma_f32 v[54:55], v[14:15], v[64:65], v[22:23]
	v_pk_fma_f32 v[52:53], v[12:13], v[56:57], v[20:21]
	v_pk_fma_f32 v[58:59], v[26:27], v[66:67], v[30:31]
	v_pk_fma_f32 v[56:57], v[24:25], v[60:61], v[28:29]
	s_waitcnt vmcnt(0)
	global_store_dwordx4 v[34:35], v[44:47], off offset:-3072
	global_store_dwordx4 v[34:35], v[48:51], off offset:-2048
	global_store_dwordx4 v[34:35], v[52:55], off offset:-1024
	global_store_dwordx4 v[34:35], v[56:59], off
	v_lshl_add_u64 v[34:35], v[34:35], 0, s[4:5]
	s_nop 1
	v_mov_b64_e32 v[44:45], v[80:81]
	v_mov_b64_e32 v[46:47], v[82:83]
	v_mov_b64_e32 v[48:49], v[84:85]
	v_mov_b64_e32 v[50:51], v[86:87]
	s_cbranch_scc1 .LBB0_2458
